# K-loops: s_setprio 1 raised before the segment barrier, hipcc duplicate lgkmcnt(0) after the barrier and the mid-block prio 0/1 flip removed
# speedup vs baseline: 1.0139x; 1.0019x over previous
; #define PG8_STAGE(bufoff, gbase, voff) do { _Pragma("unroll") for (int _i = 0; _i < 2; ++_i) \
;         __builtin_amdgcn_global_load_lds((const unsigned*)((const char*)(gbase) + (voff)[_i]), (PG8_LAS unsigned*)(lds + (bufoff) + ldsw + _i * 8192), 16, 0, 0); } while (0)
; #define PG8_LDA(dst, b, h) do { _Pragma("unroll") for (int m = 0; m < 4; ++m) _Pragma("unroll") for (int k = 0; k < 2; ++k) dst[m][k] = *(const PG8_LAS bf16x8*)(lds + PG8_SA(b, h) + aoff + m * 2048 + k * 1024); } while (0)
; #define PG8_LDB(dst, b, h) do { _Pragma("unroll") for (int n = 0; n < 2; ++n) _Pragma("unroll") for (int k = 0; k < 2; ++k) dst[n][k] = *(const PG8_LAS bf16x8*)(lds + PG8_SB(b, h) + boff + n * 2048 + k * 1024); } while (0)
; #define PG8_MMA(ai, bj, At, Bt) do { __builtin_amdgcn_s_setprio(1); _Pragma("unroll") for (int m = 0; m < 4; ++m) _Pragma("unroll") for (int n = 0; n < 2; ++n) _Pragma("unroll") for (int k = 0; k < 2; ++k) \
;         acc[ai][bj][m][n] = __builtin_amdgcn_mfma_f32_16x16x32_bf16(Bt[n][k], At[m][k], acc[ai][bj][m][n], 0, 0, 0); __builtin_amdgcn_s_setprio(0); } while (0)
; #define PG8_WAIT_V(n) asm volatile("s_waitcnt vmcnt(" #n ")" ::: "memory")
; #define PG8_WAIT_L(n) asm volatile("s_waitcnt lgkmcnt(" #n ")" ::: "memory")
; #define PG8_BAR __builtin_amdgcn_s_barrier()
; #define PG8_SCHED __builtin_amdgcn_sched_barrier(0)
; template <class Epi, class Sched, bool ALIGN_EPI = false, bool SP2 = false>
; __device__ __forceinline__ void gemm_phase(PG8_LAS unsigned char* lds, const Gemm g, const Sched& S, const Epi& E) {
;     ...
;             PG8_LDB(B0, 0, 0); PG8_LDB(B1, 0, 1); PG8_SCHED; PG8_LDA(At, 0, 0); PG8_STAGE(PG8_SA(1, 1), a1 + hstep, voffA);
;             PG8_WAIT_V(8); PG8_WAIT_L(0); PG8_BAR; PG8_MMA(0, 0, At, B0); PG8_MMA(0, 1, At, B1); PG8_BAR; PG8_SCHED;
;             PG8_LDA(At, 0, 1); PG8_STAGE(PG8_SB(0, 0), b2, voffB); PG8_STAGE(PG8_SB(0, 1), b2 + hstep, voffB); PG8_STAGE(PG8_SA(0, 0), a2, voffA);
;             PG8_WAIT_V(8); PG8_WAIT_L(0); PG8_BAR; PG8_MMA(1, 0, At, B0); PG8_MMA(1, 1, At, B1); PG8_BAR; PG8_SCHED;
.LBB0_309:
	s_add_u32 s40, s54, 0xfff80080
	s_addc_u32 s41, s55, -1
	s_add_i32 s36, 0, 0x10000
	s_cmp_eq_u32 s7, 28
	s_cselect_b32 s97, s9, s41
	s_cselect_b32 s96, s35, s40
	v_add_u32_e32 v156, s36, v164
	s_cselect_b32 s85, s87, vcc_hi
	s_cselect_b32 s84, s91, vcc_lo
	s_add_i32 s37, 0, 0x14000
	ds_read_b128 v[130:133], v156
	ds_read_b128 v[168:171], v156 offset:1024
	ds_read_b128 v[172:175], v156 offset:2048
	ds_read_b128 v[176:179], v156 offset:3072
	v_add_u32_e32 v156, s37, v164
	ds_read_b128 v[180:183], v156
	ds_read_b128 v[188:191], v156 offset:1024
	ds_read_b128 v[192:195], v156 offset:2048
	ds_read_b128 v[196:199], v156 offset:3072
	v_lshl_add_u64 v[156:157], s[54:55], 0, v[146:147]
	s_add_i32 m0, s82, 0xc000
	ds_read_b128 v[200:203], v166
	ds_read_b128 v[204:207], v166 offset:1024
	ds_read_b128 v[208:211], v166 offset:2048
	ds_read_b128 v[212:215], v166 offset:3072
	ds_read_b128 v[216:219], v166 offset:4096
	ds_read_b128 v[220:223], v166 offset:5120
	ds_read_b128 v[224:227], v166 offset:6144
	ds_read_b128 v[228:231], v166 offset:7168
	s_add_u32 s98, s54, 0xfff80000
	s_addc_u32 s99, s55, -1
	s_mov_b32 m0, s60
	s_nop 0
	global_load_lds_dwordx4 v146, s[98:99]
	s_mov_b32 m0, s61
	s_nop 0
	global_load_lds_dwordx4 v148, s[98:99]
	s_add_i32 m0, s82, 0xc000
	s_nop 0
	global_load_lds_dwordx4 v[156:157], off
	v_lshl_add_u64 v[156:157], s[54:55], 0, v[148:149]
	s_add_i32 m0, s82, 0xe000
	s_nop 0
	global_load_lds_dwordx4 v[156:157], off
	s_waitcnt vmcnt(8)
	s_waitcnt lgkmcnt(0)
	s_setprio 1
	s_barrier
	v_mfma_f32_16x16x32_bf16 v[126:129], v[130:133], v[200:203], v[126:129]
	v_mfma_f32_16x16x32_bf16 v[122:125], v[172:175], v[200:203], v[122:125]
	v_mfma_f32_16x16x32_bf16 v[110:113], v[130:133], v[208:211], v[110:113]
	v_mfma_f32_16x16x32_bf16 v[106:109], v[172:175], v[208:211], v[106:109]
	v_mfma_f32_16x16x32_bf16 v[94:97], v[130:133], v[216:219], v[94:97]
	v_mfma_f32_16x16x32_bf16 v[90:93], v[172:175], v[216:219], v[90:93]
	v_mfma_f32_16x16x32_bf16 v[78:81], v[130:133], v[224:227], v[78:81]
	v_mfma_f32_16x16x32_bf16 v[74:77], v[172:175], v[224:227], v[74:77]
	v_mfma_f32_16x16x32_bf16 v[126:129], v[168:171], v[204:207], v[126:129]
	v_mfma_f32_16x16x32_bf16 v[122:125], v[176:179], v[204:207], v[122:125]
	v_mfma_f32_16x16x32_bf16 v[110:113], v[168:171], v[212:215], v[110:113]
	v_mfma_f32_16x16x32_bf16 v[106:109], v[176:179], v[212:215], v[106:109]
	v_mfma_f32_16x16x32_bf16 v[94:97], v[168:171], v[220:223], v[94:97]
	v_mfma_f32_16x16x32_bf16 v[90:93], v[176:179], v[220:223], v[90:93]
	v_mfma_f32_16x16x32_bf16 v[78:81], v[168:171], v[228:231], v[78:81]
	v_mfma_f32_16x16x32_bf16 v[74:77], v[176:179], v[228:231], v[74:77]
	v_mfma_f32_16x16x32_bf16 v[118:121], v[180:183], v[200:203], v[118:121]
	v_mfma_f32_16x16x32_bf16 v[114:117], v[192:195], v[200:203], v[114:117]
	v_mfma_f32_16x16x32_bf16 v[102:105], v[180:183], v[208:211], v[102:105]
	v_mfma_f32_16x16x32_bf16 v[98:101], v[192:195], v[208:211], v[98:101]
	v_mfma_f32_16x16x32_bf16 v[86:89], v[180:183], v[216:219], v[86:89]
	v_mfma_f32_16x16x32_bf16 v[82:85], v[192:195], v[216:219], v[82:85]
	v_mfma_f32_16x16x32_bf16 v[70:73], v[180:183], v[224:227], v[70:73]
	v_mfma_f32_16x16x32_bf16 v[66:69], v[192:195], v[224:227], v[66:69]
	v_mfma_f32_16x16x32_bf16 v[118:121], v[188:191], v[204:207], v[118:121]
	v_mfma_f32_16x16x32_bf16 v[114:117], v[196:199], v[204:207], v[114:117]
	v_mfma_f32_16x16x32_bf16 v[102:105], v[188:191], v[212:215], v[102:105]
	v_mfma_f32_16x16x32_bf16 v[98:101], v[196:199], v[212:215], v[98:101]
	v_mfma_f32_16x16x32_bf16 v[86:89], v[188:191], v[220:223], v[86:89]
	v_mfma_f32_16x16x32_bf16 v[82:85], v[196:199], v[220:223], v[82:85]
	v_mfma_f32_16x16x32_bf16 v[70:73], v[188:191], v[228:231], v[70:73]
	v_mfma_f32_16x16x32_bf16 v[66:69], v[196:199], v[228:231], v[66:69]
	s_setprio 0
	s_barrier
	s_add_i32 s36, s36, s20
	v_lshl_add_u64 v[156:157], s[84:85], 0, v[138:139]
	s_mov_b32 m0, s36
	ds_read_b128 v[200:203], v166 offset:16384
	ds_read_b128 v[204:207], v166 offset:17408
	ds_read_b128 v[208:211], v166 offset:18432
	ds_read_b128 v[212:215], v166 offset:19456
	ds_read_b128 v[216:219], v166 offset:20480
	ds_read_b128 v[220:223], v166 offset:21504
	ds_read_b128 v[224:227], v166 offset:22528
	ds_read_b128 v[228:231], v166 offset:23552
	global_load_lds_dwordx4 v[156:157], off
	s_add_i32 m0, s36, 0x2000
	s_add_u32 s40, s84, 0x80000
	v_lshl_add_u64 v[184:185], s[84:85], 0, v[142:143]
	s_addc_u32 s41, s85, 0
	s_add_i32 s36, s37, s20
	global_load_lds_dwordx4 v[184:185], off
	v_lshl_add_u64 v[232:233], s[40:41], 0, v[138:139]
	s_mov_b32 m0, s36
	v_lshl_add_u64 v[234:235], s[96:97], 0, v[140:141]
	global_load_lds_dwordx4 v[232:233], off
	v_lshl_add_u64 v[232:233], s[40:41], 0, v[142:143]
	s_add_i32 m0, s36, 0x2000
	s_nop 0
	global_load_lds_dwordx4 v[232:233], off
	v_lshl_add_u64 v[232:233], s[96:97], 0, v[136:137]
	s_mov_b32 m0, s82
	s_nop 0
	s_mov_b32 m0, s83
	s_nop 0
	s_waitcnt vmcnt(6)
	s_waitcnt lgkmcnt(0)
	s_setprio 1
	s_barrier
; #define PG8_STAGE(bufoff, gbase, voff) do { _Pragma("unroll") for (int _i = 0; _i < 2; ++_i) \
;         __builtin_amdgcn_global_load_lds((const unsigned*)((const char*)(gbase) + (voff)[_i]), (PG8_LAS unsigned*)(lds + (bufoff) + ldsw + _i * 8192), 16, 0, 0); } while (0)
; #define PG8_LDA(dst, b, h) do { _Pragma("unroll") for (int m = 0; m < 4; ++m) _Pragma("unroll") for (int k = 0; k < 2; ++k) dst[m][k] = *(const PG8_LAS bf16x8*)(lds + PG8_SA(b, h) + aoff + m * 2048 + k * 1024); } while (0)
; #define PG8_LDB(dst, b, h) do { _Pragma("unroll") for (int n = 0; n < 2; ++n) _Pragma("unroll") for (int k = 0; k < 2; ++k) dst[n][k] = *(const PG8_LAS bf16x8*)(lds + PG8_SB(b, h) + boff + n * 2048 + k * 1024); } while (0)
; #define PG8_MMA(ai, bj, At, Bt) do { __builtin_amdgcn_s_setprio(1); _Pragma("unroll") for (int m = 0; m < 4; ++m) _Pragma("unroll") for (int n = 0; n < 2; ++n) _Pragma("unroll") for (int k = 0; k < 2; ++k) \
;         acc[ai][bj][m][n] = __builtin_amdgcn_mfma_f32_16x16x32_bf16(Bt[n][k], At[m][k], acc[ai][bj][m][n], 0, 0, 0); __builtin_amdgcn_s_setprio(0); } while (0)
; #define PG8_WAIT_V(n) asm volatile("s_waitcnt vmcnt(" #n ")" ::: "memory")
; #define PG8_WAIT_L(n) asm volatile("s_waitcnt lgkmcnt(" #n ")" ::: "memory")
; #define PG8_BAR __builtin_amdgcn_s_barrier()
; #define PG8_SCHED __builtin_amdgcn_sched_barrier(0)
; template <class Epi, class Sched, bool ALIGN_EPI = false, bool SP2 = false>
; __device__ __forceinline__ void gemm_phase(PG8_LAS unsigned char* lds, const Gemm g, const Sched& S, const Epi& E) {
;     ...
;             PG8_WAIT_V(8); PG8_WAIT_L(0); PG8_BAR; PG8_MMA(1, 0, At, B0); PG8_MMA(1, 1, At, B1); PG8_BAR; PG8_SCHED;
;             PG8_LDB(B0, 1, 0); PG8_LDB(B1, 1, 1); PG8_SCHED; PG8_LDA(At, 1, 0); PG8_STAGE(PG8_SA(0, 1), a2 + hstep, voffA);
;             PG8_WAIT_V(8); PG8_WAIT_L(0); PG8_BAR; PG8_MMA(0, 0, At, B0); PG8_MMA(0, 1, At, B1); PG8_BAR; PG8_SCHED;
	v_mfma_f32_16x16x32_bf16 v[62:65], v[130:133], v[200:203], v[62:65]
	v_mfma_f32_16x16x32_bf16 v[58:61], v[172:175], v[200:203], v[58:61]
	v_mfma_f32_16x16x32_bf16 v[46:49], v[130:133], v[208:211], v[46:49]
	v_mfma_f32_16x16x32_bf16 v[42:45], v[172:175], v[208:211], v[42:45]
	v_mfma_f32_16x16x32_bf16 v[30:33], v[130:133], v[216:219], v[30:33]
	v_mfma_f32_16x16x32_bf16 v[26:29], v[172:175], v[216:219], v[26:29]
	v_mfma_f32_16x16x32_bf16 v[14:17], v[130:133], v[224:227], v[14:17]
	v_mfma_f32_16x16x32_bf16 v[10:13], v[172:175], v[224:227], v[10:13]
	v_mfma_f32_16x16x32_bf16 v[62:65], v[168:171], v[204:207], v[62:65]
	v_mfma_f32_16x16x32_bf16 v[58:61], v[176:179], v[204:207], v[58:61]
	v_mfma_f32_16x16x32_bf16 v[46:49], v[168:171], v[212:215], v[46:49]
	v_mfma_f32_16x16x32_bf16 v[42:45], v[176:179], v[212:215], v[42:45]
	v_mfma_f32_16x16x32_bf16 v[30:33], v[168:171], v[220:223], v[30:33]
	v_mfma_f32_16x16x32_bf16 v[26:29], v[176:179], v[220:223], v[26:29]
	v_mfma_f32_16x16x32_bf16 v[14:17], v[168:171], v[228:231], v[14:17]
	v_mfma_f32_16x16x32_bf16 v[10:13], v[176:179], v[228:231], v[10:13]
	v_mfma_f32_16x16x32_bf16 v[54:57], v[180:183], v[200:203], v[54:57]
	v_mfma_f32_16x16x32_bf16 v[50:53], v[192:195], v[200:203], v[50:53]
	v_mfma_f32_16x16x32_bf16 v[38:41], v[180:183], v[208:211], v[38:41]
	v_mfma_f32_16x16x32_bf16 v[34:37], v[192:195], v[208:211], v[34:37]
	v_mfma_f32_16x16x32_bf16 v[22:25], v[180:183], v[216:219], v[22:25]
	v_mfma_f32_16x16x32_bf16 v[18:21], v[192:195], v[216:219], v[18:21]
	v_mfma_f32_16x16x32_bf16 v[6:9], v[180:183], v[224:227], v[6:9]
	v_mfma_f32_16x16x32_bf16 v[2:5], v[192:195], v[224:227], v[2:5]
	v_mfma_f32_16x16x32_bf16 v[54:57], v[188:191], v[204:207], v[54:57]
	v_mfma_f32_16x16x32_bf16 v[50:53], v[196:199], v[204:207], v[50:53]
	v_mfma_f32_16x16x32_bf16 v[38:41], v[188:191], v[212:215], v[38:41]
	v_mfma_f32_16x16x32_bf16 v[34:37], v[196:199], v[212:215], v[34:37]
	v_mfma_f32_16x16x32_bf16 v[22:25], v[188:191], v[220:223], v[22:25]
	v_mfma_f32_16x16x32_bf16 v[18:21], v[196:199], v[220:223], v[18:21]
	v_mfma_f32_16x16x32_bf16 v[6:9], v[188:191], v[228:231], v[6:9]
	v_mfma_f32_16x16x32_bf16 v[2:5], v[196:199], v[228:231], v[2:5]
	s_setprio 0
	s_barrier
	s_add_i32 s36, 0, 0x18000
	v_add_u32_e32 v167, s36, v164
	s_add_i32 s37, 0, 0x1c000
	ds_read_b128 v[130:133], v167
	ds_read_b128 v[168:171], v167 offset:1024
	ds_read_b128 v[172:175], v167 offset:2048
	ds_read_b128 v[176:179], v167 offset:3072
	v_add_u32_e32 v167, s37, v164
	ds_read_b128 v[180:183], v167
	ds_read_b128 v[188:191], v167 offset:1024
	ds_read_b128 v[192:195], v167 offset:2048
	ds_read_b128 v[196:199], v167 offset:3072
	s_add_u32 s40, s96, 0x80000
	s_addc_u32 s41, s97, 0
	s_mov_b32 m0, s3
	v_lshl_add_u64 v[236:237], s[40:41], 0, v[136:137]
	ds_read_b128 v[200:203], v166 offset:32768
	ds_read_b128 v[204:207], v166 offset:33792
	ds_read_b128 v[208:211], v166 offset:34816
	ds_read_b128 v[212:215], v166 offset:35840
	ds_read_b128 v[216:219], v166 offset:36864
	ds_read_b128 v[220:223], v166 offset:37888
	ds_read_b128 v[224:227], v166 offset:38912
	ds_read_b128 v[228:231], v166 offset:39936
	s_add_u32 s98, s40, 0xfff80000
	s_addc_u32 s99, s41, -1
	s_mov_b32 m0, s82
	s_nop 0
	global_load_lds_dwordx4 v136, s[98:99]
	s_mov_b32 m0, s83
	s_nop 0
	global_load_lds_dwordx4 v140, s[98:99]
	s_mov_b32 m0, s3
	s_nop 0
	global_load_lds_dwordx4 v[236:237], off
	v_lshl_add_u64 v[236:237], s[40:41], 0, v[140:141]
	s_mov_b32 m0, s74
	s_nop 0
	global_load_lds_dwordx4 v[236:237], off
	s_waitcnt vmcnt(8)
	s_waitcnt lgkmcnt(0)
	s_setprio 1
	s_barrier
	v_mfma_f32_16x16x32_bf16 v[126:129], v[130:133], v[200:203], v[126:129]
	v_mfma_f32_16x16x32_bf16 v[122:125], v[172:175], v[200:203], v[122:125]
	v_mfma_f32_16x16x32_bf16 v[110:113], v[130:133], v[208:211], v[110:113]
	v_mfma_f32_16x16x32_bf16 v[106:109], v[172:175], v[208:211], v[106:109]
	v_mfma_f32_16x16x32_bf16 v[94:97], v[130:133], v[216:219], v[94:97]
	v_mfma_f32_16x16x32_bf16 v[90:93], v[172:175], v[216:219], v[90:93]
	v_mfma_f32_16x16x32_bf16 v[78:81], v[130:133], v[224:227], v[78:81]
	v_mfma_f32_16x16x32_bf16 v[74:77], v[172:175], v[224:227], v[74:77]
	v_mfma_f32_16x16x32_bf16 v[126:129], v[168:171], v[204:207], v[126:129]
	v_mfma_f32_16x16x32_bf16 v[122:125], v[176:179], v[204:207], v[122:125]
	v_mfma_f32_16x16x32_bf16 v[110:113], v[168:171], v[212:215], v[110:113]
	v_mfma_f32_16x16x32_bf16 v[106:109], v[176:179], v[212:215], v[106:109]
	v_mfma_f32_16x16x32_bf16 v[94:97], v[168:171], v[220:223], v[94:97]
	v_mfma_f32_16x16x32_bf16 v[90:93], v[176:179], v[220:223], v[90:93]
	v_mfma_f32_16x16x32_bf16 v[78:81], v[168:171], v[228:231], v[78:81]
	v_mfma_f32_16x16x32_bf16 v[74:77], v[176:179], v[228:231], v[74:77]
	v_mfma_f32_16x16x32_bf16 v[118:121], v[180:183], v[200:203], v[118:121]
	v_mfma_f32_16x16x32_bf16 v[114:117], v[192:195], v[200:203], v[114:117]
	v_mfma_f32_16x16x32_bf16 v[102:105], v[180:183], v[208:211], v[102:105]
	v_mfma_f32_16x16x32_bf16 v[98:101], v[192:195], v[208:211], v[98:101]
	v_mfma_f32_16x16x32_bf16 v[86:89], v[180:183], v[216:219], v[86:89]
	v_mfma_f32_16x16x32_bf16 v[82:85], v[192:195], v[216:219], v[82:85]
	v_mfma_f32_16x16x32_bf16 v[70:73], v[180:183], v[224:227], v[70:73]
	v_mfma_f32_16x16x32_bf16 v[66:69], v[192:195], v[224:227], v[66:69]
	v_mfma_f32_16x16x32_bf16 v[118:121], v[188:191], v[204:207], v[118:121]
	v_mfma_f32_16x16x32_bf16 v[114:117], v[196:199], v[204:207], v[114:117]
	v_mfma_f32_16x16x32_bf16 v[102:105], v[188:191], v[212:215], v[102:105]
	v_mfma_f32_16x16x32_bf16 v[98:101], v[196:199], v[212:215], v[98:101]
	v_mfma_f32_16x16x32_bf16 v[86:89], v[188:191], v[220:223], v[86:89]
	v_mfma_f32_16x16x32_bf16 v[82:85], v[196:199], v[220:223], v[82:85]
	v_mfma_f32_16x16x32_bf16 v[70:73], v[188:191], v[228:231], v[70:73]
	v_mfma_f32_16x16x32_bf16 v[66:69], v[196:199], v[228:231], v[66:69]
	s_setprio 0
	s_barrier
; #define PG8_STAGE(bufoff, gbase, voff) do { _Pragma("unroll") for (int _i = 0; _i < 2; ++_i) \
;         __builtin_amdgcn_global_load_lds((const unsigned*)((const char*)(gbase) + (voff)[_i]), (PG8_LAS unsigned*)(lds + (bufoff) + ldsw + _i * 8192), 16, 0, 0); } while (0)
; #define PG8_LDA(dst, b, h) do { _Pragma("unroll") for (int m = 0; m < 4; ++m) _Pragma("unroll") for (int k = 0; k < 2; ++k) dst[m][k] = *(const PG8_LAS bf16x8*)(lds + PG8_SA(b, h) + aoff + m * 2048 + k * 1024); } while (0)
; #define PG8_MMA(ai, bj, At, Bt) do { __builtin_amdgcn_s_setprio(1); _Pragma("unroll") for (int m = 0; m < 4; ++m) _Pragma("unroll") for (int n = 0; n < 2; ++n) _Pragma("unroll") for (int k = 0; k < 2; ++k) \
;         acc[ai][bj][m][n] = __builtin_amdgcn_mfma_f32_16x16x32_bf16(Bt[n][k], At[m][k], acc[ai][bj][m][n], 0, 0, 0); __builtin_amdgcn_s_setprio(0); } while (0)
; #define PG8_WAIT_V(n) asm volatile("s_waitcnt vmcnt(" #n ")" ::: "memory")
; #define PG8_WAIT_L(n) asm volatile("s_waitcnt lgkmcnt(" #n ")" ::: "memory")
; #define PG8_BAR __builtin_amdgcn_s_barrier()
; #define PG8_SCHED __builtin_amdgcn_sched_barrier(0)
; template <class Epi, class Sched, bool ALIGN_EPI = false, bool SP2 = false>
; __device__ __forceinline__ void gemm_phase(PG8_LAS unsigned char* lds, const Gemm g, const Sched& S, const Epi& E) {
;     ...
;             PG8_LDA(At, 1, 1); PG8_STAGE(PG8_SB(1, 0), b3, voffB); PG8_STAGE(PG8_SB(1, 1), b3 + hstep, voffB); PG8_STAGE(PG8_SA(1, 0), a3, voffA);
;             PG8_WAIT_V(8); PG8_WAIT_L(0); PG8_BAR; PG8_MMA(1, 0, At, B0); PG8_MMA(1, 1, At, B1); PG8_BAR; PG8_SCHED;
	s_add_i32 s36, s36, s20
	v_lshl_add_u64 v[156:157], v[156:157], 0, s[42:43]
	s_mov_b32 m0, s36
	ds_read_b128 v[200:203], v166 offset:49152
	ds_read_b128 v[204:207], v166 offset:50176
	ds_read_b128 v[208:211], v166 offset:51200
	ds_read_b128 v[212:215], v166 offset:52224
	ds_read_b128 v[216:219], v166 offset:53248
	ds_read_b128 v[220:223], v166 offset:54272
	ds_read_b128 v[224:227], v166 offset:55296
	ds_read_b128 v[228:231], v166 offset:56320
	global_load_lds_dwordx4 v[156:157], off
	s_add_i32 m0, s36, 0x2000
	s_add_u32 s40, s84, 0x80080
	v_lshl_add_u64 v[156:157], v[184:185], 0, s[42:43]
	s_addc_u32 s41, s85, 0
	s_add_i32 s36, s37, s20
	global_load_lds_dwordx4 v[156:157], off
	v_lshl_add_u64 v[156:157], s[40:41], 0, v[138:139]
	s_mov_b32 m0, s36
	s_nop 0
	global_load_lds_dwordx4 v[156:157], off
	v_lshl_add_u64 v[156:157], s[40:41], 0, v[142:143]
	s_add_i32 m0, s36, 0x2000
	s_nop 0
	global_load_lds_dwordx4 v[156:157], off
	v_lshl_add_u64 v[156:157], v[232:233], 0, s[42:43]
	s_mov_b32 m0, s60
	s_nop 0
	v_lshl_add_u64 v[156:157], v[234:235], 0, s[42:43]
	s_mov_b32 m0, s61
	s_nop 0
	s_waitcnt vmcnt(6)
	s_waitcnt lgkmcnt(0)
	s_setprio 1
	s_barrier
	v_mfma_f32_16x16x32_bf16 v[62:65], v[130:133], v[200:203], v[62:65]
	v_mfma_f32_16x16x32_bf16 v[58:61], v[172:175], v[200:203], v[58:61]
	v_mfma_f32_16x16x32_bf16 v[46:49], v[130:133], v[208:211], v[46:49]
	v_mfma_f32_16x16x32_bf16 v[42:45], v[172:175], v[208:211], v[42:45]
	v_mfma_f32_16x16x32_bf16 v[30:33], v[130:133], v[216:219], v[30:33]
	v_mfma_f32_16x16x32_bf16 v[26:29], v[172:175], v[216:219], v[26:29]
	v_mfma_f32_16x16x32_bf16 v[14:17], v[130:133], v[224:227], v[14:17]
	v_mfma_f32_16x16x32_bf16 v[10:13], v[172:175], v[224:227], v[10:13]
	v_mfma_f32_16x16x32_bf16 v[62:65], v[168:171], v[204:207], v[62:65]
	v_mfma_f32_16x16x32_bf16 v[58:61], v[176:179], v[204:207], v[58:61]
	v_mfma_f32_16x16x32_bf16 v[46:49], v[168:171], v[212:215], v[46:49]
	v_mfma_f32_16x16x32_bf16 v[42:45], v[176:179], v[212:215], v[42:45]
	v_mfma_f32_16x16x32_bf16 v[30:33], v[168:171], v[220:223], v[30:33]
	v_mfma_f32_16x16x32_bf16 v[26:29], v[176:179], v[220:223], v[26:29]
	v_mfma_f32_16x16x32_bf16 v[14:17], v[168:171], v[228:231], v[14:17]
	v_mfma_f32_16x16x32_bf16 v[10:13], v[176:179], v[228:231], v[10:13]
	v_mfma_f32_16x16x32_bf16 v[54:57], v[180:183], v[200:203], v[54:57]
	v_mfma_f32_16x16x32_bf16 v[50:53], v[192:195], v[200:203], v[50:53]
	v_mfma_f32_16x16x32_bf16 v[38:41], v[180:183], v[208:211], v[38:41]
	v_mfma_f32_16x16x32_bf16 v[34:37], v[192:195], v[208:211], v[34:37]
	v_mfma_f32_16x16x32_bf16 v[22:25], v[180:183], v[216:219], v[22:25]
	v_mfma_f32_16x16x32_bf16 v[18:21], v[192:195], v[216:219], v[18:21]
	v_mfma_f32_16x16x32_bf16 v[6:9], v[180:183], v[224:227], v[6:9]
	v_mfma_f32_16x16x32_bf16 v[2:5], v[192:195], v[224:227], v[2:5]
	v_mfma_f32_16x16x32_bf16 v[54:57], v[188:191], v[204:207], v[54:57]
	v_mfma_f32_16x16x32_bf16 v[50:53], v[196:199], v[204:207], v[50:53]
	v_mfma_f32_16x16x32_bf16 v[38:41], v[188:191], v[212:215], v[38:41]
	v_mfma_f32_16x16x32_bf16 v[34:37], v[196:199], v[212:215], v[34:37]
	v_mfma_f32_16x16x32_bf16 v[22:25], v[188:191], v[220:223], v[22:25]
	v_mfma_f32_16x16x32_bf16 v[18:21], v[196:199], v[220:223], v[18:21]
	v_mfma_f32_16x16x32_bf16 v[6:9], v[188:191], v[228:231], v[6:9]
	v_mfma_f32_16x16x32_bf16 v[2:5], v[196:199], v[228:231], v[2:5]
	s_setprio 0
	s_barrier
	s_add_i32 s7, s7, 2
	s_add_u32 s54, s54, 0x100
	s_addc_u32 s55, s55, 0
	s_add_u32 vcc_lo, vcc_lo, 0x100
	s_addc_u32 vcc_hi, vcc_hi, 0
	s_cmp_gt_u32 s7, 29
	s_cbranch_scc0 .LBB0_309
	s_and_b64 vcc, exec, s[72:73]
	s_cbranch_vccz .LBB0_312
	s_barrier

; #define PG8_STAGE(bufoff, gbase, voff) do { _Pragma("unroll") for (int _i = 0; _i < 2; ++_i) \
;         __builtin_amdgcn_global_load_lds((const unsigned*)((const char*)(gbase) + (voff)[_i]), (PG8_LAS unsigned*)(lds + (bufoff) + ldsw + _i * 8192), 16, 0, 0); } while (0)
; #define PG8_LDA(dst, b, h) do { _Pragma("unroll") for (int m = 0; m < 4; ++m) _Pragma("unroll") for (int k = 0; k < 2; ++k) dst[m][k] = *(const PG8_LAS bf16x8*)(lds + PG8_SA(b, h) + aoff + m * 2048 + k * 1024); } while (0)
; #define PG8_LDB(dst, b, h) do { _Pragma("unroll") for (int n = 0; n < 2; ++n) _Pragma("unroll") for (int k = 0; k < 2; ++k) dst[n][k] = *(const PG8_LAS bf16x8*)(lds + PG8_SB(b, h) + boff + n * 2048 + k * 1024); } while (0)
; #define PG8_MMA(ai, bj, At, Bt) do { __builtin_amdgcn_s_setprio(1); _Pragma("unroll") for (int m = 0; m < 4; ++m) _Pragma("unroll") for (int n = 0; n < 2; ++n) _Pragma("unroll") for (int k = 0; k < 2; ++k) \
;         acc[ai][bj][m][n] = __builtin_amdgcn_mfma_f32_16x16x32_bf16(Bt[n][k], At[m][k], acc[ai][bj][m][n], 0, 0, 0); __builtin_amdgcn_s_setprio(0); } while (0)
; #define PG8_WAIT_V(n) asm volatile("s_waitcnt vmcnt(" #n ")" ::: "memory")
; #define PG8_WAIT_L(n) asm volatile("s_waitcnt lgkmcnt(" #n ")" ::: "memory")
; #define PG8_BAR __builtin_amdgcn_s_barrier()
; #define PG8_SCHED __builtin_amdgcn_sched_barrier(0)
; template <class Epi, class Sched, bool ALIGN_EPI = false, bool SP2 = false>
; __device__ __forceinline__ void gemm_phase(PG8_LAS unsigned char* lds, const Gemm g, const Sched& S, const Epi& E) {
;     ...
;             PG8_LDB(B0, 0, 0); PG8_LDB(B1, 0, 1); PG8_SCHED; PG8_LDA(At, 0, 0); PG8_STAGE(PG8_SA(1, 1), a1 + hstep, voffA);
;             PG8_WAIT_V(8); PG8_WAIT_L(0); PG8_BAR; PG8_MMA(0, 0, At, B0); PG8_MMA(0, 1, At, B1); PG8_BAR; PG8_SCHED;
;             PG8_LDA(At, 0, 1); PG8_STAGE(PG8_SB(0, 0), b2, voffB); PG8_STAGE(PG8_SB(0, 1), b2 + hstep, voffB); PG8_STAGE(PG8_SA(0, 0), a2, voffA);
;             PG8_WAIT_V(8); PG8_WAIT_L(0); PG8_BAR; PG8_MMA(1, 0, At, B0); PG8_MMA(1, 1, At, B1); PG8_BAR; PG8_SCHED;
.LBB0_592:
	ds_read_b128 v[156:159], v152
	ds_read_b128 v[160:163], v152 offset:1024
	ds_read_b128 v[164:167], v152 offset:2048
	ds_read_b128 v[168:171], v152 offset:3072
	ds_read_b128 v[172:175], v153
	ds_read_b128 v[176:179], v153 offset:1024
	ds_read_b128 v[180:183], v153 offset:2048
	ds_read_b128 v[188:191], v153 offset:3072
	s_add_u32 s46, s44, 0xfff80080
	s_addc_u32 s47, s45, -1
	s_cmp_eq_u32 s55, 28
	s_cselect_b32 s49, s35, s47
	s_cselect_b32 s48, s51, s46
	s_cselect_b32 s47, s37, s54
	s_cselect_b32 s46, s52, s53
	v_lshl_add_u64 v[148:149], s[44:45], 0, v[140:141]
	s_add_i32 m0, s17, 0xc000
	ds_read_b128 v[192:195], v154
	ds_read_b128 v[196:199], v154 offset:1024
	ds_read_b128 v[200:203], v154 offset:2048
	ds_read_b128 v[204:207], v154 offset:3072
	ds_read_b128 v[208:211], v154 offset:4096
	ds_read_b128 v[212:215], v154 offset:5120
	ds_read_b128 v[216:219], v154 offset:6144
	ds_read_b128 v[220:223], v154 offset:7168
	s_add_u32 s98, s44, 0xfff80000
	s_addc_u32 s99, s45, -1
	s_mov_b32 m0, s21
	s_nop 0
	global_load_lds_dwordx4 v140, s[98:99]
	s_mov_b32 m0, s33
	s_nop 0
	global_load_lds_dwordx4 v142, s[98:99]
	s_add_i32 m0, s17, 0xc000
	s_nop 0
	global_load_lds_dwordx4 v[148:149], off
	v_lshl_add_u64 v[148:149], s[44:45], 0, v[142:143]
	s_add_i32 m0, s17, 0xe000
	s_nop 0
	global_load_lds_dwordx4 v[148:149], off
	s_waitcnt vmcnt(8)
	s_waitcnt lgkmcnt(0)
	s_setprio 1
	s_barrier
	v_mfma_f32_16x16x32_bf16 v[126:129], v[156:159], v[192:195], v[126:129]
	v_mfma_f32_16x16x32_bf16 v[122:125], v[164:167], v[192:195], v[122:125]
	v_mfma_f32_16x16x32_bf16 v[118:121], v[156:159], v[200:203], v[118:121]
	v_mfma_f32_16x16x32_bf16 v[110:113], v[164:167], v[200:203], v[110:113]
	v_mfma_f32_16x16x32_bf16 v[102:105], v[156:159], v[208:211], v[102:105]
	v_mfma_f32_16x16x32_bf16 v[94:97], v[164:167], v[208:211], v[94:97]
	v_mfma_f32_16x16x32_bf16 v[86:89], v[156:159], v[216:219], v[86:89]
	v_mfma_f32_16x16x32_bf16 v[78:81], v[164:167], v[216:219], v[78:81]
	v_mfma_f32_16x16x32_bf16 v[126:129], v[160:163], v[196:199], v[126:129]
	v_mfma_f32_16x16x32_bf16 v[122:125], v[168:171], v[196:199], v[122:125]
	v_mfma_f32_16x16x32_bf16 v[118:121], v[160:163], v[204:207], v[118:121]
	v_mfma_f32_16x16x32_bf16 v[110:113], v[168:171], v[204:207], v[110:113]
	v_mfma_f32_16x16x32_bf16 v[102:105], v[160:163], v[212:215], v[102:105]
	v_mfma_f32_16x16x32_bf16 v[94:97], v[168:171], v[212:215], v[94:97]
	v_mfma_f32_16x16x32_bf16 v[86:89], v[160:163], v[220:223], v[86:89]
	v_mfma_f32_16x16x32_bf16 v[78:81], v[168:171], v[220:223], v[78:81]
	v_mfma_f32_16x16x32_bf16 v[114:117], v[172:175], v[192:195], v[114:117]
	v_mfma_f32_16x16x32_bf16 v[106:109], v[180:183], v[192:195], v[106:109]
	v_mfma_f32_16x16x32_bf16 v[98:101], v[172:175], v[200:203], v[98:101]
	v_mfma_f32_16x16x32_bf16 v[90:93], v[180:183], v[200:203], v[90:93]
	v_mfma_f32_16x16x32_bf16 v[82:85], v[172:175], v[208:211], v[82:85]
	v_mfma_f32_16x16x32_bf16 v[74:77], v[180:183], v[208:211], v[74:77]
	v_mfma_f32_16x16x32_bf16 v[70:73], v[172:175], v[216:219], v[70:73]
	v_mfma_f32_16x16x32_bf16 v[66:69], v[180:183], v[216:219], v[66:69]
	v_mfma_f32_16x16x32_bf16 v[114:117], v[176:179], v[196:199], v[114:117]
	v_mfma_f32_16x16x32_bf16 v[106:109], v[188:191], v[196:199], v[106:109]
	v_mfma_f32_16x16x32_bf16 v[98:101], v[176:179], v[204:207], v[98:101]
	v_mfma_f32_16x16x32_bf16 v[90:93], v[188:191], v[204:207], v[90:93]
	v_mfma_f32_16x16x32_bf16 v[82:85], v[176:179], v[212:215], v[82:85]
	v_mfma_f32_16x16x32_bf16 v[74:77], v[188:191], v[212:215], v[74:77]
	v_mfma_f32_16x16x32_bf16 v[70:73], v[176:179], v[220:223], v[70:73]
	v_mfma_f32_16x16x32_bf16 v[66:69], v[188:191], v[220:223], v[66:69]
	s_setprio 0
	s_barrier
	s_add_i32 s56, s43, s16
	v_lshl_add_u64 v[148:149], s[46:47], 0, v[132:133]
	s_mov_b32 m0, s56
	ds_read_b128 v[192:195], v154 offset:16384
	ds_read_b128 v[196:199], v154 offset:17408
	ds_read_b128 v[200:203], v154 offset:18432
	ds_read_b128 v[204:207], v154 offset:19456
	ds_read_b128 v[208:211], v154 offset:20480
	ds_read_b128 v[212:215], v154 offset:21504
	ds_read_b128 v[216:219], v154 offset:22528
	ds_read_b128 v[220:223], v154 offset:23552
	global_load_lds_dwordx4 v[148:149], off
	s_add_i32 m0, s56, 0x2000
	s_add_u32 s56, s46, 0x80000
	v_lshl_add_u64 v[184:185], s[46:47], 0, v[136:137]
	s_addc_u32 s57, s47, 0
	s_add_i32 s58, s50, s16
	global_load_lds_dwordx4 v[184:185], off
	v_lshl_add_u64 v[224:225], s[56:57], 0, v[132:133]
	s_mov_b32 m0, s58
	v_lshl_add_u64 v[226:227], s[48:49], 0, v[134:135]
	global_load_lds_dwordx4 v[224:225], off
	v_lshl_add_u64 v[224:225], s[56:57], 0, v[136:137]
	s_add_i32 m0, s58, 0x2000
	s_nop 0
	global_load_lds_dwordx4 v[224:225], off
	v_lshl_add_u64 v[224:225], s[48:49], 0, v[130:131]
	s_mov_b32 m0, s17
	s_nop 0
	s_mov_b32 m0, s18
	s_nop 0
	s_waitcnt vmcnt(6)
	s_waitcnt lgkmcnt(0)
	s_setprio 1
	s_barrier
; #define PG8_STAGE(bufoff, gbase, voff) do { _Pragma("unroll") for (int _i = 0; _i < 2; ++_i) \
;         __builtin_amdgcn_global_load_lds((const unsigned*)((const char*)(gbase) + (voff)[_i]), (PG8_LAS unsigned*)(lds + (bufoff) + ldsw + _i * 8192), 16, 0, 0); } while (0)
; #define PG8_LDA(dst, b, h) do { _Pragma("unroll") for (int m = 0; m < 4; ++m) _Pragma("unroll") for (int k = 0; k < 2; ++k) dst[m][k] = *(const PG8_LAS bf16x8*)(lds + PG8_SA(b, h) + aoff + m * 2048 + k * 1024); } while (0)
; #define PG8_LDB(dst, b, h) do { _Pragma("unroll") for (int n = 0; n < 2; ++n) _Pragma("unroll") for (int k = 0; k < 2; ++k) dst[n][k] = *(const PG8_LAS bf16x8*)(lds + PG8_SB(b, h) + boff + n * 2048 + k * 1024); } while (0)
; #define PG8_MMA(ai, bj, At, Bt) do { __builtin_amdgcn_s_setprio(1); _Pragma("unroll") for (int m = 0; m < 4; ++m) _Pragma("unroll") for (int n = 0; n < 2; ++n) _Pragma("unroll") for (int k = 0; k < 2; ++k) \
;         acc[ai][bj][m][n] = __builtin_amdgcn_mfma_f32_16x16x32_bf16(Bt[n][k], At[m][k], acc[ai][bj][m][n], 0, 0, 0); __builtin_amdgcn_s_setprio(0); } while (0)
; #define PG8_WAIT_V(n) asm volatile("s_waitcnt vmcnt(" #n ")" ::: "memory")
; #define PG8_WAIT_L(n) asm volatile("s_waitcnt lgkmcnt(" #n ")" ::: "memory")
; #define PG8_BAR __builtin_amdgcn_s_barrier()
; #define PG8_SCHED __builtin_amdgcn_sched_barrier(0)
; template <class Epi, class Sched, bool ALIGN_EPI = false, bool SP2 = false>
; __device__ __forceinline__ void gemm_phase(PG8_LAS unsigned char* lds, const Gemm g, const Sched& S, const Epi& E) {
;     ...
;             PG8_WAIT_V(8); PG8_WAIT_L(0); PG8_BAR; PG8_MMA(1, 0, At, B0); PG8_MMA(1, 1, At, B1); PG8_BAR; PG8_SCHED;
;             PG8_LDB(B0, 1, 0); PG8_LDB(B1, 1, 1); PG8_SCHED; PG8_LDA(At, 1, 0); PG8_STAGE(PG8_SA(0, 1), a2 + hstep, voffA);
;             PG8_WAIT_V(8); PG8_WAIT_L(0); PG8_BAR; PG8_MMA(0, 0, At, B0); PG8_MMA(0, 1, At, B1); PG8_BAR; PG8_SCHED;
	v_mfma_f32_16x16x32_bf16 v[62:65], v[156:159], v[192:195], v[62:65]
	v_mfma_f32_16x16x32_bf16 v[58:61], v[164:167], v[192:195], v[58:61]
	v_mfma_f32_16x16x32_bf16 v[54:57], v[156:159], v[200:203], v[54:57]
	v_mfma_f32_16x16x32_bf16 v[46:49], v[164:167], v[200:203], v[46:49]
	v_mfma_f32_16x16x32_bf16 v[38:41], v[156:159], v[208:211], v[38:41]
	v_mfma_f32_16x16x32_bf16 v[30:33], v[164:167], v[208:211], v[30:33]
	v_mfma_f32_16x16x32_bf16 v[22:25], v[156:159], v[216:219], v[22:25]
	v_mfma_f32_16x16x32_bf16 v[14:17], v[164:167], v[216:219], v[14:17]
	v_mfma_f32_16x16x32_bf16 v[62:65], v[160:163], v[196:199], v[62:65]
	v_mfma_f32_16x16x32_bf16 v[58:61], v[168:171], v[196:199], v[58:61]
	v_mfma_f32_16x16x32_bf16 v[54:57], v[160:163], v[204:207], v[54:57]
	v_mfma_f32_16x16x32_bf16 v[46:49], v[168:171], v[204:207], v[46:49]
	v_mfma_f32_16x16x32_bf16 v[38:41], v[160:163], v[212:215], v[38:41]
	v_mfma_f32_16x16x32_bf16 v[30:33], v[168:171], v[212:215], v[30:33]
	v_mfma_f32_16x16x32_bf16 v[22:25], v[160:163], v[220:223], v[22:25]
	v_mfma_f32_16x16x32_bf16 v[14:17], v[168:171], v[220:223], v[14:17]
	v_mfma_f32_16x16x32_bf16 v[50:53], v[172:175], v[192:195], v[50:53]
	v_mfma_f32_16x16x32_bf16 v[42:45], v[180:183], v[192:195], v[42:45]
	v_mfma_f32_16x16x32_bf16 v[34:37], v[172:175], v[200:203], v[34:37]
	v_mfma_f32_16x16x32_bf16 v[26:29], v[180:183], v[200:203], v[26:29]
	v_mfma_f32_16x16x32_bf16 v[18:21], v[172:175], v[208:211], v[18:21]
	v_mfma_f32_16x16x32_bf16 v[10:13], v[180:183], v[208:211], v[10:13]
	v_mfma_f32_16x16x32_bf16 v[6:9], v[172:175], v[216:219], v[6:9]
	v_mfma_f32_16x16x32_bf16 v[2:5], v[180:183], v[216:219], v[2:5]
	v_mfma_f32_16x16x32_bf16 v[50:53], v[176:179], v[196:199], v[50:53]
	v_mfma_f32_16x16x32_bf16 v[42:45], v[188:191], v[196:199], v[42:45]
	v_mfma_f32_16x16x32_bf16 v[34:37], v[176:179], v[204:207], v[34:37]
	v_mfma_f32_16x16x32_bf16 v[26:29], v[188:191], v[204:207], v[26:29]
	v_mfma_f32_16x16x32_bf16 v[18:21], v[176:179], v[212:215], v[18:21]
	v_mfma_f32_16x16x32_bf16 v[10:13], v[188:191], v[212:215], v[10:13]
	v_mfma_f32_16x16x32_bf16 v[6:9], v[176:179], v[220:223], v[6:9]
	v_mfma_f32_16x16x32_bf16 v[2:5], v[188:191], v[220:223], v[2:5]
	s_setprio 0
	s_barrier
	s_add_i32 s56, 0, 0x18000
	v_add_u32_e32 v155, s56, v151
	s_add_i32 s57, 0, 0x1c000
	ds_read_b128 v[156:159], v155
	ds_read_b128 v[160:163], v155 offset:1024
	ds_read_b128 v[164:167], v155 offset:2048
	ds_read_b128 v[168:171], v155 offset:3072
	v_add_u32_e32 v155, s57, v151
	ds_read_b128 v[172:175], v155
	ds_read_b128 v[176:179], v155 offset:1024
	ds_read_b128 v[180:183], v155 offset:2048
	ds_read_b128 v[188:191], v155 offset:3072
	s_add_u32 s48, s48, 0x80000
	s_addc_u32 s49, s49, 0
	s_mov_b32 m0, s19
	v_lshl_add_u64 v[228:229], s[48:49], 0, v[130:131]
	ds_read_b128 v[192:195], v154 offset:32768
	ds_read_b128 v[196:199], v154 offset:33792
	ds_read_b128 v[200:203], v154 offset:34816
	ds_read_b128 v[204:207], v154 offset:35840
	ds_read_b128 v[208:211], v154 offset:36864
	ds_read_b128 v[212:215], v154 offset:37888
	ds_read_b128 v[216:219], v154 offset:38912
	ds_read_b128 v[220:223], v154 offset:39936
	s_add_u32 s98, s48, 0xfff80000
	s_addc_u32 s99, s49, -1
	s_mov_b32 m0, s17
	s_nop 0
	global_load_lds_dwordx4 v130, s[98:99]
	s_mov_b32 m0, s18
	s_nop 0
	global_load_lds_dwordx4 v134, s[98:99]
	s_mov_b32 m0, s19
	s_nop 0
	global_load_lds_dwordx4 v[228:229], off
	v_lshl_add_u64 v[228:229], s[48:49], 0, v[134:135]
	s_mov_b32 m0, s20
	s_nop 0
	global_load_lds_dwordx4 v[228:229], off
	s_waitcnt vmcnt(8)
	s_waitcnt lgkmcnt(0)
	s_setprio 1
	s_barrier
	v_mfma_f32_16x16x32_bf16 v[126:129], v[156:159], v[192:195], v[126:129]
	v_mfma_f32_16x16x32_bf16 v[122:125], v[164:167], v[192:195], v[122:125]
	v_mfma_f32_16x16x32_bf16 v[118:121], v[156:159], v[200:203], v[118:121]
	v_mfma_f32_16x16x32_bf16 v[110:113], v[164:167], v[200:203], v[110:113]
	v_mfma_f32_16x16x32_bf16 v[102:105], v[156:159], v[208:211], v[102:105]
	v_mfma_f32_16x16x32_bf16 v[94:97], v[164:167], v[208:211], v[94:97]
	v_mfma_f32_16x16x32_bf16 v[86:89], v[156:159], v[216:219], v[86:89]
	v_mfma_f32_16x16x32_bf16 v[78:81], v[164:167], v[216:219], v[78:81]
	v_mfma_f32_16x16x32_bf16 v[126:129], v[160:163], v[196:199], v[126:129]
	v_mfma_f32_16x16x32_bf16 v[122:125], v[168:171], v[196:199], v[122:125]
	v_mfma_f32_16x16x32_bf16 v[118:121], v[160:163], v[204:207], v[118:121]
	v_mfma_f32_16x16x32_bf16 v[110:113], v[168:171], v[204:207], v[110:113]
	v_mfma_f32_16x16x32_bf16 v[102:105], v[160:163], v[212:215], v[102:105]
	v_mfma_f32_16x16x32_bf16 v[94:97], v[168:171], v[212:215], v[94:97]
	v_mfma_f32_16x16x32_bf16 v[86:89], v[160:163], v[220:223], v[86:89]
	v_mfma_f32_16x16x32_bf16 v[78:81], v[168:171], v[220:223], v[78:81]
	v_mfma_f32_16x16x32_bf16 v[114:117], v[172:175], v[192:195], v[114:117]
	v_mfma_f32_16x16x32_bf16 v[106:109], v[180:183], v[192:195], v[106:109]
	v_mfma_f32_16x16x32_bf16 v[98:101], v[172:175], v[200:203], v[98:101]
	v_mfma_f32_16x16x32_bf16 v[90:93], v[180:183], v[200:203], v[90:93]
	v_mfma_f32_16x16x32_bf16 v[82:85], v[172:175], v[208:211], v[82:85]
	v_mfma_f32_16x16x32_bf16 v[74:77], v[180:183], v[208:211], v[74:77]
	v_mfma_f32_16x16x32_bf16 v[70:73], v[172:175], v[216:219], v[70:73]
	v_mfma_f32_16x16x32_bf16 v[66:69], v[180:183], v[216:219], v[66:69]
	v_mfma_f32_16x16x32_bf16 v[114:117], v[176:179], v[196:199], v[114:117]
	v_mfma_f32_16x16x32_bf16 v[106:109], v[188:191], v[196:199], v[106:109]
	v_mfma_f32_16x16x32_bf16 v[98:101], v[176:179], v[204:207], v[98:101]
	v_mfma_f32_16x16x32_bf16 v[90:93], v[188:191], v[204:207], v[90:93]
	v_mfma_f32_16x16x32_bf16 v[82:85], v[176:179], v[212:215], v[82:85]
	v_mfma_f32_16x16x32_bf16 v[74:77], v[188:191], v[212:215], v[74:77]
	v_mfma_f32_16x16x32_bf16 v[70:73], v[176:179], v[220:223], v[70:73]
	v_mfma_f32_16x16x32_bf16 v[66:69], v[188:191], v[220:223], v[66:69]
	s_setprio 0
	s_barrier
; #define PG8_STAGE(bufoff, gbase, voff) do { _Pragma("unroll") for (int _i = 0; _i < 2; ++_i) \
;         __builtin_amdgcn_global_load_lds((const unsigned*)((const char*)(gbase) + (voff)[_i]), (PG8_LAS unsigned*)(lds + (bufoff) + ldsw + _i * 8192), 16, 0, 0); } while (0)
; #define PG8_LDA(dst, b, h) do { _Pragma("unroll") for (int m = 0; m < 4; ++m) _Pragma("unroll") for (int k = 0; k < 2; ++k) dst[m][k] = *(const PG8_LAS bf16x8*)(lds + PG8_SA(b, h) + aoff + m * 2048 + k * 1024); } while (0)
; #define PG8_MMA(ai, bj, At, Bt) do { __builtin_amdgcn_s_setprio(1); _Pragma("unroll") for (int m = 0; m < 4; ++m) _Pragma("unroll") for (int n = 0; n < 2; ++n) _Pragma("unroll") for (int k = 0; k < 2; ++k) \
;         acc[ai][bj][m][n] = __builtin_amdgcn_mfma_f32_16x16x32_bf16(Bt[n][k], At[m][k], acc[ai][bj][m][n], 0, 0, 0); __builtin_amdgcn_s_setprio(0); } while (0)
; #define PG8_WAIT_V(n) asm volatile("s_waitcnt vmcnt(" #n ")" ::: "memory")
; #define PG8_WAIT_L(n) asm volatile("s_waitcnt lgkmcnt(" #n ")" ::: "memory")
; #define PG8_BAR __builtin_amdgcn_s_barrier()
; #define PG8_SCHED __builtin_amdgcn_sched_barrier(0)
; template <class Epi, class Sched, bool ALIGN_EPI = false, bool SP2 = false>
; __device__ __forceinline__ void gemm_phase(PG8_LAS unsigned char* lds, const Gemm g, const Sched& S, const Epi& E) {
;     ...
;             PG8_LDA(At, 1, 1); PG8_STAGE(PG8_SB(1, 0), b3, voffB); PG8_STAGE(PG8_SB(1, 1), b3 + hstep, voffB); PG8_STAGE(PG8_SA(1, 0), a3, voffA);
;             PG8_WAIT_V(8); PG8_WAIT_L(0); PG8_BAR; PG8_MMA(1, 0, At, B0); PG8_MMA(1, 1, At, B1); PG8_BAR; PG8_SCHED;
	s_add_i32 s48, s56, s16
	v_lshl_add_u64 v[148:149], v[148:149], 0, s[26:27]
	s_mov_b32 m0, s48
	ds_read_b128 v[192:195], v154 offset:49152
	ds_read_b128 v[196:199], v154 offset:50176
	ds_read_b128 v[200:203], v154 offset:51200
	ds_read_b128 v[204:207], v154 offset:52224
	ds_read_b128 v[208:211], v154 offset:53248
	ds_read_b128 v[212:215], v154 offset:54272
	ds_read_b128 v[216:219], v154 offset:55296
	ds_read_b128 v[220:223], v154 offset:56320
	global_load_lds_dwordx4 v[148:149], off
	s_add_i32 m0, s48, 0x2000
	s_add_u32 s46, s46, 0x80080
	v_lshl_add_u64 v[148:149], v[184:185], 0, s[26:27]
	s_addc_u32 s47, s47, 0
	s_add_i32 s48, s57, s16
	global_load_lds_dwordx4 v[148:149], off
	v_lshl_add_u64 v[148:149], s[46:47], 0, v[132:133]
	s_mov_b32 m0, s48
	s_nop 0
	global_load_lds_dwordx4 v[148:149], off
	v_lshl_add_u64 v[148:149], s[46:47], 0, v[136:137]
	s_add_i32 m0, s48, 0x2000
	s_nop 0
	global_load_lds_dwordx4 v[148:149], off
	v_lshl_add_u64 v[148:149], v[224:225], 0, s[26:27]
	s_mov_b32 m0, s21
	s_nop 0
	v_lshl_add_u64 v[148:149], v[226:227], 0, s[26:27]
	s_mov_b32 m0, s33
	s_nop 0
	s_waitcnt vmcnt(6)
	s_waitcnt lgkmcnt(0)
	s_setprio 1
	s_barrier
	v_mfma_f32_16x16x32_bf16 v[62:65], v[156:159], v[192:195], v[62:65]
	v_mfma_f32_16x16x32_bf16 v[58:61], v[164:167], v[192:195], v[58:61]
	v_mfma_f32_16x16x32_bf16 v[54:57], v[156:159], v[200:203], v[54:57]
	v_mfma_f32_16x16x32_bf16 v[46:49], v[164:167], v[200:203], v[46:49]
	v_mfma_f32_16x16x32_bf16 v[38:41], v[156:159], v[208:211], v[38:41]
	v_mfma_f32_16x16x32_bf16 v[30:33], v[164:167], v[208:211], v[30:33]
	v_mfma_f32_16x16x32_bf16 v[22:25], v[156:159], v[216:219], v[22:25]
	v_mfma_f32_16x16x32_bf16 v[14:17], v[164:167], v[216:219], v[14:17]
	v_mfma_f32_16x16x32_bf16 v[62:65], v[160:163], v[196:199], v[62:65]
	v_mfma_f32_16x16x32_bf16 v[58:61], v[168:171], v[196:199], v[58:61]
	v_mfma_f32_16x16x32_bf16 v[54:57], v[160:163], v[204:207], v[54:57]
	v_mfma_f32_16x16x32_bf16 v[46:49], v[168:171], v[204:207], v[46:49]
	v_mfma_f32_16x16x32_bf16 v[38:41], v[160:163], v[212:215], v[38:41]
	v_mfma_f32_16x16x32_bf16 v[30:33], v[168:171], v[212:215], v[30:33]
	v_mfma_f32_16x16x32_bf16 v[22:25], v[160:163], v[220:223], v[22:25]
	v_mfma_f32_16x16x32_bf16 v[14:17], v[168:171], v[220:223], v[14:17]
	v_mfma_f32_16x16x32_bf16 v[50:53], v[172:175], v[192:195], v[50:53]
	v_mfma_f32_16x16x32_bf16 v[42:45], v[180:183], v[192:195], v[42:45]
	v_mfma_f32_16x16x32_bf16 v[34:37], v[172:175], v[200:203], v[34:37]
	v_mfma_f32_16x16x32_bf16 v[26:29], v[180:183], v[200:203], v[26:29]
	v_mfma_f32_16x16x32_bf16 v[18:21], v[172:175], v[208:211], v[18:21]
	v_mfma_f32_16x16x32_bf16 v[10:13], v[180:183], v[208:211], v[10:13]
	v_mfma_f32_16x16x32_bf16 v[6:9], v[172:175], v[216:219], v[6:9]
	v_mfma_f32_16x16x32_bf16 v[2:5], v[180:183], v[216:219], v[2:5]
	v_mfma_f32_16x16x32_bf16 v[50:53], v[176:179], v[196:199], v[50:53]
	v_mfma_f32_16x16x32_bf16 v[42:45], v[188:191], v[196:199], v[42:45]
	v_mfma_f32_16x16x32_bf16 v[34:37], v[176:179], v[204:207], v[34:37]
	v_mfma_f32_16x16x32_bf16 v[26:29], v[188:191], v[204:207], v[26:29]
	v_mfma_f32_16x16x32_bf16 v[18:21], v[176:179], v[212:215], v[18:21]
	v_mfma_f32_16x16x32_bf16 v[10:13], v[188:191], v[212:215], v[10:13]
	v_mfma_f32_16x16x32_bf16 v[6:9], v[176:179], v[220:223], v[6:9]
	v_mfma_f32_16x16x32_bf16 v[2:5], v[188:191], v[220:223], v[2:5]
	s_setprio 0
	s_barrier
	s_add_i32 s55, s55, 2
	s_add_u32 s44, s44, 0x100
	s_addc_u32 s45, s45, 0
	s_add_u32 s53, s53, 0x100
	s_addc_u32 s54, s54, 0
	s_cmp_gt_u32 s55, 29
	s_cbranch_scc0 .LBB0_592
	s_and_b64 vcc, exec, s[28:29]
	s_cbranch_vccz .LBB0_595
	s_barrier

; #define PG8_STAGE(bufoff, gbase, voff) do { _Pragma("unroll") for (int _i = 0; _i < 2; ++_i) \
;         __builtin_amdgcn_global_load_lds((const unsigned*)((const char*)(gbase) + (voff)[_i]), (PG8_LAS unsigned*)(lds + (bufoff) + ldsw + _i * 8192), 16, 0, 0); } while (0)
; #define PG8_LDA(dst, b, h) do { _Pragma("unroll") for (int m = 0; m < 4; ++m) _Pragma("unroll") for (int k = 0; k < 2; ++k) dst[m][k] = *(const PG8_LAS bf16x8*)(lds + PG8_SA(b, h) + aoff + m * 2048 + k * 1024); } while (0)
; #define PG8_LDB(dst, b, h) do { _Pragma("unroll") for (int n = 0; n < 2; ++n) _Pragma("unroll") for (int k = 0; k < 2; ++k) dst[n][k] = *(const PG8_LAS bf16x8*)(lds + PG8_SB(b, h) + boff + n * 2048 + k * 1024); } while (0)
; #define PG8_MMA(ai, bj, At, Bt) do { __builtin_amdgcn_s_setprio(1); _Pragma("unroll") for (int m = 0; m < 4; ++m) _Pragma("unroll") for (int n = 0; n < 2; ++n) _Pragma("unroll") for (int k = 0; k < 2; ++k) \
;         acc[ai][bj][m][n] = __builtin_amdgcn_mfma_f32_16x16x32_bf16(Bt[n][k], At[m][k], acc[ai][bj][m][n], 0, 0, 0); __builtin_amdgcn_s_setprio(0); } while (0)
; #define PG8_WAIT_V(n) asm volatile("s_waitcnt vmcnt(" #n ")" ::: "memory")
; #define PG8_WAIT_L(n) asm volatile("s_waitcnt lgkmcnt(" #n ")" ::: "memory")
; #define PG8_BAR __builtin_amdgcn_s_barrier()
; #define PG8_SCHED __builtin_amdgcn_sched_barrier(0)
; template <class Epi, class Sched, bool ALIGN_EPI = false, bool SP2 = false>
; __device__ __forceinline__ void gemm_phase(PG8_LAS unsigned char* lds, const Gemm g, const Sched& S, const Epi& E) {
;     ...
;             PG8_LDB(B0, 0, 0); PG8_LDB(B1, 0, 1); PG8_SCHED; PG8_LDA(At, 0, 0); PG8_STAGE(PG8_SA(1, 1), a1 + hstep, voffA);
;             PG8_WAIT_V(8); PG8_WAIT_L(0); PG8_BAR; PG8_MMA(0, 0, At, B0); PG8_MMA(0, 1, At, B1); PG8_BAR; PG8_SCHED;
;             PG8_LDA(At, 0, 1); PG8_STAGE(PG8_SB(0, 0), b2, voffB); PG8_STAGE(PG8_SB(0, 1), b2 + hstep, voffB); PG8_STAGE(PG8_SA(0, 0), a2, voffA);
;             PG8_WAIT_V(8); PG8_WAIT_L(0); PG8_BAR; PG8_MMA(1, 0, At, B0); PG8_MMA(1, 1, At, B1); PG8_BAR; PG8_SCHED;
.LBB0_650:
	ds_read_b128 v[154:157], v150
	ds_read_b128 v[158:161], v150 offset:1024
	ds_read_b128 v[162:165], v150 offset:2048
	ds_read_b128 v[166:169], v150 offset:3072
	ds_read_b128 v[170:173], v151
	ds_read_b128 v[174:177], v151 offset:1024
	ds_read_b128 v[178:181], v151 offset:2048
	ds_read_b128 v[182:185], v151 offset:3072
	s_add_u32 s44, s42, 0xfff80080
	s_addc_u32 s45, s43, -1
	s_cmp_eq_u32 s59, 28
	s_cselect_b32 s47, s35, s45
	s_cselect_b32 s46, s55, s44
	s_cselect_b32 s45, s31, s58
	s_cselect_b32 s44, s56, s57
	v_lshl_add_u64 v[146:147], s[42:43], 0, v[140:141]
	s_add_i32 m0, s17, 0xc000
	ds_read_b128 v[188:191], v152
	ds_read_b128 v[192:195], v152 offset:1024
	ds_read_b128 v[196:199], v152 offset:2048
	ds_read_b128 v[200:203], v152 offset:3072
	ds_read_b128 v[204:207], v152 offset:4096
	ds_read_b128 v[208:211], v152 offset:5120
	ds_read_b128 v[212:215], v152 offset:6144
	ds_read_b128 v[216:219], v152 offset:7168
	s_add_u32 s98, s42, 0xfff80000
	s_addc_u32 s99, s43, -1
	s_mov_b32 m0, s21
	s_nop 0
	global_load_lds_dwordx4 v140, s[98:99]
	s_mov_b32 m0, s33
	s_nop 0
	global_load_lds_dwordx4 v142, s[98:99]
	s_add_i32 m0, s17, 0xc000
	s_nop 0
	global_load_lds_dwordx4 v[146:147], off
	v_lshl_add_u64 v[146:147], s[42:43], 0, v[142:143]
	s_add_i32 m0, s17, 0xe000
	s_nop 0
	global_load_lds_dwordx4 v[146:147], off
	s_waitcnt vmcnt(8)
	s_waitcnt lgkmcnt(0)
	s_setprio 1
	s_barrier
	v_mfma_f32_16x16x32_bf16 v[126:129], v[154:157], v[188:191], v[126:129]
	v_mfma_f32_16x16x32_bf16 v[122:125], v[162:165], v[188:191], v[122:125]
	v_mfma_f32_16x16x32_bf16 v[118:121], v[154:157], v[196:199], v[118:121]
	v_mfma_f32_16x16x32_bf16 v[110:113], v[162:165], v[196:199], v[110:113]
	v_mfma_f32_16x16x32_bf16 v[102:105], v[154:157], v[204:207], v[102:105]
	v_mfma_f32_16x16x32_bf16 v[94:97], v[162:165], v[204:207], v[94:97]
	v_mfma_f32_16x16x32_bf16 v[86:89], v[154:157], v[212:215], v[86:89]
	v_mfma_f32_16x16x32_bf16 v[78:81], v[162:165], v[212:215], v[78:81]
	v_mfma_f32_16x16x32_bf16 v[126:129], v[158:161], v[192:195], v[126:129]
	v_mfma_f32_16x16x32_bf16 v[122:125], v[166:169], v[192:195], v[122:125]
	v_mfma_f32_16x16x32_bf16 v[118:121], v[158:161], v[200:203], v[118:121]
	v_mfma_f32_16x16x32_bf16 v[110:113], v[166:169], v[200:203], v[110:113]
	v_mfma_f32_16x16x32_bf16 v[102:105], v[158:161], v[208:211], v[102:105]
	v_mfma_f32_16x16x32_bf16 v[94:97], v[166:169], v[208:211], v[94:97]
	v_mfma_f32_16x16x32_bf16 v[86:89], v[158:161], v[216:219], v[86:89]
	v_mfma_f32_16x16x32_bf16 v[78:81], v[166:169], v[216:219], v[78:81]
	v_mfma_f32_16x16x32_bf16 v[114:117], v[170:173], v[188:191], v[114:117]
	v_mfma_f32_16x16x32_bf16 v[106:109], v[178:181], v[188:191], v[106:109]
	v_mfma_f32_16x16x32_bf16 v[98:101], v[170:173], v[196:199], v[98:101]
	v_mfma_f32_16x16x32_bf16 v[90:93], v[178:181], v[196:199], v[90:93]
	v_mfma_f32_16x16x32_bf16 v[82:85], v[170:173], v[204:207], v[82:85]
	v_mfma_f32_16x16x32_bf16 v[74:77], v[178:181], v[204:207], v[74:77]
	v_mfma_f32_16x16x32_bf16 v[70:73], v[170:173], v[212:215], v[70:73]
	v_mfma_f32_16x16x32_bf16 v[66:69], v[178:181], v[212:215], v[66:69]
	v_mfma_f32_16x16x32_bf16 v[114:117], v[174:177], v[192:195], v[114:117]
	v_mfma_f32_16x16x32_bf16 v[106:109], v[182:185], v[192:195], v[106:109]
	v_mfma_f32_16x16x32_bf16 v[98:101], v[174:177], v[200:203], v[98:101]
	v_mfma_f32_16x16x32_bf16 v[90:93], v[182:185], v[200:203], v[90:93]
	v_mfma_f32_16x16x32_bf16 v[82:85], v[174:177], v[208:211], v[82:85]
	v_mfma_f32_16x16x32_bf16 v[74:77], v[182:185], v[208:211], v[74:77]
	v_mfma_f32_16x16x32_bf16 v[70:73], v[174:177], v[216:219], v[70:73]
	v_mfma_f32_16x16x32_bf16 v[66:69], v[182:185], v[216:219], v[66:69]
	s_setprio 0
	s_barrier
	s_add_i32 s60, s48, s16
	v_lshl_add_u64 v[146:147], s[44:45], 0, v[132:133]
	s_mov_b32 m0, s60
	ds_read_b128 v[188:191], v152 offset:16384
	ds_read_b128 v[192:195], v152 offset:17408
	ds_read_b128 v[196:199], v152 offset:18432
	ds_read_b128 v[200:203], v152 offset:19456
	ds_read_b128 v[204:207], v152 offset:20480
	ds_read_b128 v[208:211], v152 offset:21504
	ds_read_b128 v[212:215], v152 offset:22528
	ds_read_b128 v[216:219], v152 offset:23552
	global_load_lds_dwordx4 v[146:147], off
	s_add_i32 m0, s60, 0x2000
	s_add_u32 s60, s44, 0x80000
	v_lshl_add_u64 v[220:221], s[44:45], 0, v[136:137]
	s_addc_u32 s61, s45, 0
	s_add_i32 s62, s49, s16
	global_load_lds_dwordx4 v[220:221], off
	v_lshl_add_u64 v[222:223], s[60:61], 0, v[132:133]
	s_mov_b32 m0, s62
	v_lshl_add_u64 v[224:225], s[46:47], 0, v[134:135]
	global_load_lds_dwordx4 v[222:223], off
	v_lshl_add_u64 v[222:223], s[60:61], 0, v[136:137]
	s_add_i32 m0, s62, 0x2000
	s_nop 0
	global_load_lds_dwordx4 v[222:223], off
	v_lshl_add_u64 v[222:223], s[46:47], 0, v[130:131]
	s_mov_b32 m0, s17
	s_nop 0
	s_mov_b32 m0, s18
	s_nop 0
	s_waitcnt vmcnt(6)
	s_waitcnt lgkmcnt(0)
	s_setprio 1
	s_barrier
; #define PG8_STAGE(bufoff, gbase, voff) do { _Pragma("unroll") for (int _i = 0; _i < 2; ++_i) \
;         __builtin_amdgcn_global_load_lds((const unsigned*)((const char*)(gbase) + (voff)[_i]), (PG8_LAS unsigned*)(lds + (bufoff) + ldsw + _i * 8192), 16, 0, 0); } while (0)
; #define PG8_LDA(dst, b, h) do { _Pragma("unroll") for (int m = 0; m < 4; ++m) _Pragma("unroll") for (int k = 0; k < 2; ++k) dst[m][k] = *(const PG8_LAS bf16x8*)(lds + PG8_SA(b, h) + aoff + m * 2048 + k * 1024); } while (0)
; #define PG8_LDB(dst, b, h) do { _Pragma("unroll") for (int n = 0; n < 2; ++n) _Pragma("unroll") for (int k = 0; k < 2; ++k) dst[n][k] = *(const PG8_LAS bf16x8*)(lds + PG8_SB(b, h) + boff + n * 2048 + k * 1024); } while (0)
; #define PG8_MMA(ai, bj, At, Bt) do { __builtin_amdgcn_s_setprio(1); _Pragma("unroll") for (int m = 0; m < 4; ++m) _Pragma("unroll") for (int n = 0; n < 2; ++n) _Pragma("unroll") for (int k = 0; k < 2; ++k) \
;         acc[ai][bj][m][n] = __builtin_amdgcn_mfma_f32_16x16x32_bf16(Bt[n][k], At[m][k], acc[ai][bj][m][n], 0, 0, 0); __builtin_amdgcn_s_setprio(0); } while (0)
; #define PG8_WAIT_V(n) asm volatile("s_waitcnt vmcnt(" #n ")" ::: "memory")
; #define PG8_WAIT_L(n) asm volatile("s_waitcnt lgkmcnt(" #n ")" ::: "memory")
; #define PG8_BAR __builtin_amdgcn_s_barrier()
; #define PG8_SCHED __builtin_amdgcn_sched_barrier(0)
; template <class Epi, class Sched, bool ALIGN_EPI = false, bool SP2 = false>
; __device__ __forceinline__ void gemm_phase(PG8_LAS unsigned char* lds, const Gemm g, const Sched& S, const Epi& E) {
;     ...
;             PG8_WAIT_V(8); PG8_WAIT_L(0); PG8_BAR; PG8_MMA(1, 0, At, B0); PG8_MMA(1, 1, At, B1); PG8_BAR; PG8_SCHED;
;             PG8_LDB(B0, 1, 0); PG8_LDB(B1, 1, 1); PG8_SCHED; PG8_LDA(At, 1, 0); PG8_STAGE(PG8_SA(0, 1), a2 + hstep, voffA);
;             PG8_WAIT_V(8); PG8_WAIT_L(0); PG8_BAR; PG8_MMA(0, 0, At, B0); PG8_MMA(0, 1, At, B1); PG8_BAR; PG8_SCHED;
	v_mfma_f32_16x16x32_bf16 v[62:65], v[154:157], v[188:191], v[62:65]
	v_mfma_f32_16x16x32_bf16 v[58:61], v[162:165], v[188:191], v[58:61]
	v_mfma_f32_16x16x32_bf16 v[54:57], v[154:157], v[196:199], v[54:57]
	v_mfma_f32_16x16x32_bf16 v[46:49], v[162:165], v[196:199], v[46:49]
	v_mfma_f32_16x16x32_bf16 v[38:41], v[154:157], v[204:207], v[38:41]
	v_mfma_f32_16x16x32_bf16 v[30:33], v[162:165], v[204:207], v[30:33]
	v_mfma_f32_16x16x32_bf16 v[22:25], v[154:157], v[212:215], v[22:25]
	v_mfma_f32_16x16x32_bf16 v[14:17], v[162:165], v[212:215], v[14:17]
	v_mfma_f32_16x16x32_bf16 v[62:65], v[158:161], v[192:195], v[62:65]
	v_mfma_f32_16x16x32_bf16 v[58:61], v[166:169], v[192:195], v[58:61]
	v_mfma_f32_16x16x32_bf16 v[54:57], v[158:161], v[200:203], v[54:57]
	v_mfma_f32_16x16x32_bf16 v[46:49], v[166:169], v[200:203], v[46:49]
	v_mfma_f32_16x16x32_bf16 v[38:41], v[158:161], v[208:211], v[38:41]
	v_mfma_f32_16x16x32_bf16 v[30:33], v[166:169], v[208:211], v[30:33]
	v_mfma_f32_16x16x32_bf16 v[22:25], v[158:161], v[216:219], v[22:25]
	v_mfma_f32_16x16x32_bf16 v[14:17], v[166:169], v[216:219], v[14:17]
	v_mfma_f32_16x16x32_bf16 v[50:53], v[170:173], v[188:191], v[50:53]
	v_mfma_f32_16x16x32_bf16 v[42:45], v[178:181], v[188:191], v[42:45]
	v_mfma_f32_16x16x32_bf16 v[34:37], v[170:173], v[196:199], v[34:37]
	v_mfma_f32_16x16x32_bf16 v[26:29], v[178:181], v[196:199], v[26:29]
	v_mfma_f32_16x16x32_bf16 v[18:21], v[170:173], v[204:207], v[18:21]
	v_mfma_f32_16x16x32_bf16 v[10:13], v[178:181], v[204:207], v[10:13]
	v_mfma_f32_16x16x32_bf16 v[6:9], v[170:173], v[212:215], v[6:9]
	v_mfma_f32_16x16x32_bf16 v[2:5], v[178:181], v[212:215], v[2:5]
	v_mfma_f32_16x16x32_bf16 v[50:53], v[174:177], v[192:195], v[50:53]
	v_mfma_f32_16x16x32_bf16 v[42:45], v[182:185], v[192:195], v[42:45]
	v_mfma_f32_16x16x32_bf16 v[34:37], v[174:177], v[200:203], v[34:37]
	v_mfma_f32_16x16x32_bf16 v[26:29], v[182:185], v[200:203], v[26:29]
	v_mfma_f32_16x16x32_bf16 v[18:21], v[174:177], v[208:211], v[18:21]
	v_mfma_f32_16x16x32_bf16 v[10:13], v[182:185], v[208:211], v[10:13]
	v_mfma_f32_16x16x32_bf16 v[6:9], v[174:177], v[216:219], v[6:9]
	v_mfma_f32_16x16x32_bf16 v[2:5], v[182:185], v[216:219], v[2:5]
	s_setprio 0
	s_barrier
	s_add_i32 s60, 0, 0x18000
	v_add_u32_e32 v153, s60, v149
	s_add_i32 s61, 0, 0x1c000
	ds_read_b128 v[154:157], v153
	ds_read_b128 v[158:161], v153 offset:1024
	ds_read_b128 v[162:165], v153 offset:2048
	ds_read_b128 v[166:169], v153 offset:3072
	v_add_u32_e32 v153, s61, v149
	ds_read_b128 v[170:173], v153
	ds_read_b128 v[174:177], v153 offset:1024
	ds_read_b128 v[178:181], v153 offset:2048
	ds_read_b128 v[182:185], v153 offset:3072
	s_add_u32 s46, s46, 0x80000
	s_addc_u32 s47, s47, 0
	s_mov_b32 m0, s19
	v_lshl_add_u64 v[226:227], s[46:47], 0, v[130:131]
	ds_read_b128 v[188:191], v152 offset:32768
	ds_read_b128 v[192:195], v152 offset:33792
	ds_read_b128 v[196:199], v152 offset:34816
	ds_read_b128 v[200:203], v152 offset:35840
	ds_read_b128 v[204:207], v152 offset:36864
	ds_read_b128 v[208:211], v152 offset:37888
	ds_read_b128 v[212:215], v152 offset:38912
	ds_read_b128 v[216:219], v152 offset:39936
	s_add_u32 s98, s46, 0xfff80000
	s_addc_u32 s99, s47, -1
	s_mov_b32 m0, s17
	s_nop 0
	global_load_lds_dwordx4 v130, s[98:99]
	s_mov_b32 m0, s18
	s_nop 0
	global_load_lds_dwordx4 v134, s[98:99]
	s_mov_b32 m0, s19
	s_nop 0
	global_load_lds_dwordx4 v[226:227], off
	v_lshl_add_u64 v[226:227], s[46:47], 0, v[134:135]
	s_mov_b32 m0, s20
	s_nop 0
	global_load_lds_dwordx4 v[226:227], off
	s_waitcnt vmcnt(8)
	s_waitcnt lgkmcnt(0)
	s_setprio 1
	s_barrier
	v_mfma_f32_16x16x32_bf16 v[126:129], v[154:157], v[188:191], v[126:129]
	v_mfma_f32_16x16x32_bf16 v[122:125], v[162:165], v[188:191], v[122:125]
	v_mfma_f32_16x16x32_bf16 v[118:121], v[154:157], v[196:199], v[118:121]
	v_mfma_f32_16x16x32_bf16 v[110:113], v[162:165], v[196:199], v[110:113]
	v_mfma_f32_16x16x32_bf16 v[102:105], v[154:157], v[204:207], v[102:105]
	v_mfma_f32_16x16x32_bf16 v[94:97], v[162:165], v[204:207], v[94:97]
	v_mfma_f32_16x16x32_bf16 v[86:89], v[154:157], v[212:215], v[86:89]
	v_mfma_f32_16x16x32_bf16 v[78:81], v[162:165], v[212:215], v[78:81]
	v_mfma_f32_16x16x32_bf16 v[126:129], v[158:161], v[192:195], v[126:129]
	v_mfma_f32_16x16x32_bf16 v[122:125], v[166:169], v[192:195], v[122:125]
	v_mfma_f32_16x16x32_bf16 v[118:121], v[158:161], v[200:203], v[118:121]
	v_mfma_f32_16x16x32_bf16 v[110:113], v[166:169], v[200:203], v[110:113]
	v_mfma_f32_16x16x32_bf16 v[102:105], v[158:161], v[208:211], v[102:105]
	v_mfma_f32_16x16x32_bf16 v[94:97], v[166:169], v[208:211], v[94:97]
	v_mfma_f32_16x16x32_bf16 v[86:89], v[158:161], v[216:219], v[86:89]
	v_mfma_f32_16x16x32_bf16 v[78:81], v[166:169], v[216:219], v[78:81]
	v_mfma_f32_16x16x32_bf16 v[114:117], v[170:173], v[188:191], v[114:117]
	v_mfma_f32_16x16x32_bf16 v[106:109], v[178:181], v[188:191], v[106:109]
	v_mfma_f32_16x16x32_bf16 v[98:101], v[170:173], v[196:199], v[98:101]
	v_mfma_f32_16x16x32_bf16 v[90:93], v[178:181], v[196:199], v[90:93]
	v_mfma_f32_16x16x32_bf16 v[82:85], v[170:173], v[204:207], v[82:85]
	v_mfma_f32_16x16x32_bf16 v[74:77], v[178:181], v[204:207], v[74:77]
	v_mfma_f32_16x16x32_bf16 v[70:73], v[170:173], v[212:215], v[70:73]
	v_mfma_f32_16x16x32_bf16 v[66:69], v[178:181], v[212:215], v[66:69]
	v_mfma_f32_16x16x32_bf16 v[114:117], v[174:177], v[192:195], v[114:117]
	v_mfma_f32_16x16x32_bf16 v[106:109], v[182:185], v[192:195], v[106:109]
	v_mfma_f32_16x16x32_bf16 v[98:101], v[174:177], v[200:203], v[98:101]
	v_mfma_f32_16x16x32_bf16 v[90:93], v[182:185], v[200:203], v[90:93]
	v_mfma_f32_16x16x32_bf16 v[82:85], v[174:177], v[208:211], v[82:85]
	v_mfma_f32_16x16x32_bf16 v[74:77], v[182:185], v[208:211], v[74:77]
	v_mfma_f32_16x16x32_bf16 v[70:73], v[174:177], v[216:219], v[70:73]
	v_mfma_f32_16x16x32_bf16 v[66:69], v[182:185], v[216:219], v[66:69]
	s_setprio 0
	s_barrier
; #define PG8_STAGE(bufoff, gbase, voff) do { _Pragma("unroll") for (int _i = 0; _i < 2; ++_i) \
;         __builtin_amdgcn_global_load_lds((const unsigned*)((const char*)(gbase) + (voff)[_i]), (PG8_LAS unsigned*)(lds + (bufoff) + ldsw + _i * 8192), 16, 0, 0); } while (0)
; #define PG8_LDA(dst, b, h) do { _Pragma("unroll") for (int m = 0; m < 4; ++m) _Pragma("unroll") for (int k = 0; k < 2; ++k) dst[m][k] = *(const PG8_LAS bf16x8*)(lds + PG8_SA(b, h) + aoff + m * 2048 + k * 1024); } while (0)
; #define PG8_MMA(ai, bj, At, Bt) do { __builtin_amdgcn_s_setprio(1); _Pragma("unroll") for (int m = 0; m < 4; ++m) _Pragma("unroll") for (int n = 0; n < 2; ++n) _Pragma("unroll") for (int k = 0; k < 2; ++k) \
;         acc[ai][bj][m][n] = __builtin_amdgcn_mfma_f32_16x16x32_bf16(Bt[n][k], At[m][k], acc[ai][bj][m][n], 0, 0, 0); __builtin_amdgcn_s_setprio(0); } while (0)
; #define PG8_WAIT_V(n) asm volatile("s_waitcnt vmcnt(" #n ")" ::: "memory")
; #define PG8_WAIT_L(n) asm volatile("s_waitcnt lgkmcnt(" #n ")" ::: "memory")
; #define PG8_BAR __builtin_amdgcn_s_barrier()
; #define PG8_SCHED __builtin_amdgcn_sched_barrier(0)
; template <class Epi, class Sched, bool ALIGN_EPI = false, bool SP2 = false>
; __device__ __forceinline__ void gemm_phase(PG8_LAS unsigned char* lds, const Gemm g, const Sched& S, const Epi& E) {
;     ...
;             PG8_LDA(At, 1, 1); PG8_STAGE(PG8_SB(1, 0), b3, voffB); PG8_STAGE(PG8_SB(1, 1), b3 + hstep, voffB); PG8_STAGE(PG8_SA(1, 0), a3, voffA);
;             PG8_WAIT_V(8); PG8_WAIT_L(0); PG8_BAR; PG8_MMA(1, 0, At, B0); PG8_MMA(1, 1, At, B1); PG8_BAR; PG8_SCHED;
	s_add_i32 s46, s60, s16
	v_lshl_add_u64 v[146:147], v[146:147], 0, s[26:27]
	s_mov_b32 m0, s46
	ds_read_b128 v[188:191], v152 offset:49152
	ds_read_b128 v[192:195], v152 offset:50176
	ds_read_b128 v[196:199], v152 offset:51200
	ds_read_b128 v[200:203], v152 offset:52224
	ds_read_b128 v[204:207], v152 offset:53248
	ds_read_b128 v[208:211], v152 offset:54272
	ds_read_b128 v[212:215], v152 offset:55296
	ds_read_b128 v[216:219], v152 offset:56320
	global_load_lds_dwordx4 v[146:147], off
	s_add_i32 m0, s46, 0x2000
	s_add_u32 s44, s44, 0x80080
	v_lshl_add_u64 v[146:147], v[220:221], 0, s[26:27]
	s_addc_u32 s45, s45, 0
	s_add_i32 s46, s61, s16
	global_load_lds_dwordx4 v[146:147], off
	v_lshl_add_u64 v[146:147], s[44:45], 0, v[132:133]
	s_mov_b32 m0, s46
	s_nop 0
	global_load_lds_dwordx4 v[146:147], off
	v_lshl_add_u64 v[146:147], s[44:45], 0, v[136:137]
	s_add_i32 m0, s46, 0x2000
	s_nop 0
	global_load_lds_dwordx4 v[146:147], off
	v_lshl_add_u64 v[146:147], v[222:223], 0, s[26:27]
	s_mov_b32 m0, s21
	s_nop 0
	v_lshl_add_u64 v[146:147], v[224:225], 0, s[26:27]
	s_mov_b32 m0, s33
	s_nop 0
	s_waitcnt vmcnt(6)
	s_waitcnt lgkmcnt(0)
	s_setprio 1
	s_barrier
	v_mfma_f32_16x16x32_bf16 v[62:65], v[154:157], v[188:191], v[62:65]
	v_mfma_f32_16x16x32_bf16 v[58:61], v[162:165], v[188:191], v[58:61]
	v_mfma_f32_16x16x32_bf16 v[54:57], v[154:157], v[196:199], v[54:57]
	v_mfma_f32_16x16x32_bf16 v[46:49], v[162:165], v[196:199], v[46:49]
	v_mfma_f32_16x16x32_bf16 v[38:41], v[154:157], v[204:207], v[38:41]
	v_mfma_f32_16x16x32_bf16 v[30:33], v[162:165], v[204:207], v[30:33]
	v_mfma_f32_16x16x32_bf16 v[22:25], v[154:157], v[212:215], v[22:25]
	v_mfma_f32_16x16x32_bf16 v[14:17], v[162:165], v[212:215], v[14:17]
	v_mfma_f32_16x16x32_bf16 v[62:65], v[158:161], v[192:195], v[62:65]
	v_mfma_f32_16x16x32_bf16 v[58:61], v[166:169], v[192:195], v[58:61]
	v_mfma_f32_16x16x32_bf16 v[54:57], v[158:161], v[200:203], v[54:57]
	v_mfma_f32_16x16x32_bf16 v[46:49], v[166:169], v[200:203], v[46:49]
	v_mfma_f32_16x16x32_bf16 v[38:41], v[158:161], v[208:211], v[38:41]
	v_mfma_f32_16x16x32_bf16 v[30:33], v[166:169], v[208:211], v[30:33]
	v_mfma_f32_16x16x32_bf16 v[22:25], v[158:161], v[216:219], v[22:25]
	v_mfma_f32_16x16x32_bf16 v[14:17], v[166:169], v[216:219], v[14:17]
	v_mfma_f32_16x16x32_bf16 v[50:53], v[170:173], v[188:191], v[50:53]
	v_mfma_f32_16x16x32_bf16 v[42:45], v[178:181], v[188:191], v[42:45]
	v_mfma_f32_16x16x32_bf16 v[34:37], v[170:173], v[196:199], v[34:37]
	v_mfma_f32_16x16x32_bf16 v[26:29], v[178:181], v[196:199], v[26:29]
	v_mfma_f32_16x16x32_bf16 v[18:21], v[170:173], v[204:207], v[18:21]
	v_mfma_f32_16x16x32_bf16 v[10:13], v[178:181], v[204:207], v[10:13]
	v_mfma_f32_16x16x32_bf16 v[6:9], v[170:173], v[212:215], v[6:9]
	v_mfma_f32_16x16x32_bf16 v[2:5], v[178:181], v[212:215], v[2:5]
	v_mfma_f32_16x16x32_bf16 v[50:53], v[174:177], v[192:195], v[50:53]
	v_mfma_f32_16x16x32_bf16 v[42:45], v[182:185], v[192:195], v[42:45]
	v_mfma_f32_16x16x32_bf16 v[34:37], v[174:177], v[200:203], v[34:37]
	v_mfma_f32_16x16x32_bf16 v[26:29], v[182:185], v[200:203], v[26:29]
	v_mfma_f32_16x16x32_bf16 v[18:21], v[174:177], v[208:211], v[18:21]
	v_mfma_f32_16x16x32_bf16 v[10:13], v[182:185], v[208:211], v[10:13]
	v_mfma_f32_16x16x32_bf16 v[6:9], v[174:177], v[216:219], v[6:9]
	v_mfma_f32_16x16x32_bf16 v[2:5], v[182:185], v[216:219], v[2:5]
	s_setprio 0
	s_barrier
	s_add_i32 s59, s59, 2
	s_add_u32 s42, s42, 0x100
	s_addc_u32 s43, s43, 0
	s_add_u32 s57, s57, 0x100
	s_addc_u32 s58, s58, 0
	s_cmp_gt_u32 s59, 29
	s_cbranch_scc0 .LBB0_650
	s_and_b64 vcc, exec, s[28:29]
	s_cbranch_vccz .LBB0_653
	s_barrier

; #define PG8_STAGE(bufoff, gbase, voff) do { _Pragma("unroll") for (int _i = 0; _i < 2; ++_i) \
;         __builtin_amdgcn_global_load_lds((const unsigned*)((const char*)(gbase) + (voff)[_i]), (PG8_LAS unsigned*)(lds + (bufoff) + ldsw + _i * 8192), 16, 0, 0); } while (0)
; #define PG8_LDA(dst, b, h) do { _Pragma("unroll") for (int m = 0; m < 4; ++m) _Pragma("unroll") for (int k = 0; k < 2; ++k) dst[m][k] = *(const PG8_LAS bf16x8*)(lds + PG8_SA(b, h) + aoff + m * 2048 + k * 1024); } while (0)
; #define PG8_LDB(dst, b, h) do { _Pragma("unroll") for (int n = 0; n < 2; ++n) _Pragma("unroll") for (int k = 0; k < 2; ++k) dst[n][k] = *(const PG8_LAS bf16x8*)(lds + PG8_SB(b, h) + boff + n * 2048 + k * 1024); } while (0)
; #define PG8_MMA(ai, bj, At, Bt) do { __builtin_amdgcn_s_setprio(1); _Pragma("unroll") for (int m = 0; m < 4; ++m) _Pragma("unroll") for (int n = 0; n < 2; ++n) _Pragma("unroll") for (int k = 0; k < 2; ++k) \
;         acc[ai][bj][m][n] = __builtin_amdgcn_mfma_f32_16x16x32_bf16(Bt[n][k], At[m][k], acc[ai][bj][m][n], 0, 0, 0); __builtin_amdgcn_s_setprio(0); } while (0)
; #define PG8_WAIT_V(n) asm volatile("s_waitcnt vmcnt(" #n ")" ::: "memory")
; #define PG8_WAIT_L(n) asm volatile("s_waitcnt lgkmcnt(" #n ")" ::: "memory")
; #define PG8_BAR __builtin_amdgcn_s_barrier()
; #define PG8_SCHED __builtin_amdgcn_sched_barrier(0)
; template <class Epi, class Sched, bool ALIGN_EPI = false, bool SP2 = false>
; __device__ __forceinline__ void gemm_phase(PG8_LAS unsigned char* lds, const Gemm g, const Sched& S, const Epi& E) {
;     ...
;             PG8_LDB(B0, 0, 0); PG8_LDB(B1, 0, 1); PG8_SCHED; PG8_LDA(At, 0, 0); PG8_STAGE(PG8_SA(1, 1), a1 + hstep, voffA);
;             PG8_WAIT_V(8); PG8_WAIT_L(0); PG8_BAR; PG8_MMA(0, 0, At, B0); PG8_MMA(0, 1, At, B1); PG8_BAR; PG8_SCHED;
;             PG8_LDA(At, 0, 1); PG8_STAGE(PG8_SB(0, 0), b2, voffB); PG8_STAGE(PG8_SB(0, 1), b2 + hstep, voffB); PG8_STAGE(PG8_SA(0, 0), a2, voffA);
;             PG8_WAIT_V(8); PG8_WAIT_L(0); PG8_BAR; PG8_MMA(1, 0, At, B0); PG8_MMA(1, 1, At, B1); PG8_BAR; PG8_SCHED;
.LBB0_816:
	s_add_u32 s46, s44, 0xfffc0080
	s_addc_u32 s47, s45, -1
	s_add_i32 s63, 0, 0x10000
	s_cmp_eq_u32 s62, 12
	s_cselect_b32 s49, s7, s47
	s_cselect_b32 s48, s37, s46
	v_add_u32_e32 v138, s63, v170
	s_cselect_b32 s47, s35, s61
	s_cselect_b32 s46, s59, s60
	s_add_i32 s66, 0, 0x14000
	ds_read_b128 v[130:133], v138
	ds_read_b128 v[134:137], v138 offset:1024
	ds_read_b128 v[156:159], v138 offset:2048
	ds_read_b128 v[160:163], v138 offset:3072
	v_add_u32_e32 v138, s66, v170
	ds_read_b128 v[174:177], v138
	ds_read_b128 v[178:181], v138 offset:1024
	ds_read_b128 v[182:185], v138 offset:2048
	ds_read_b128 v[188:191], v138 offset:3072
	v_lshl_add_u64 v[138:139], s[44:45], 0, v[148:149]
	s_add_i32 m0, s43, 0xc000
	ds_read_b128 v[192:195], v172
	ds_read_b128 v[196:199], v172 offset:1024
	ds_read_b128 v[200:203], v172 offset:2048
	ds_read_b128 v[204:207], v172 offset:3072
	ds_read_b128 v[208:211], v172 offset:4096
	ds_read_b128 v[212:215], v172 offset:5120
	ds_read_b128 v[216:219], v172 offset:6144
	ds_read_b128 v[220:223], v172 offset:7168
	s_add_u32 s98, s44, 0xfffc0000
	s_addc_u32 s99, s45, -1
	s_mov_b32 m0, s56
	s_nop 0
	global_load_lds_dwordx4 v148, s[98:99]
	s_mov_b32 m0, s57
	s_nop 0
	global_load_lds_dwordx4 v150, s[98:99]
	s_add_i32 m0, s43, 0xc000
	s_nop 0
	global_load_lds_dwordx4 v[138:139], off
	v_lshl_add_u64 v[138:139], s[44:45], 0, v[150:151]
	s_add_i32 m0, s43, 0xe000
	s_nop 0
	global_load_lds_dwordx4 v[138:139], off
	s_waitcnt vmcnt(8)
	s_waitcnt lgkmcnt(0)
	s_setprio 1
	s_barrier
	v_mfma_f32_16x16x32_bf16 v[126:129], v[130:133], v[192:195], v[126:129]
	v_mfma_f32_16x16x32_bf16 v[122:125], v[156:159], v[192:195], v[122:125]
	v_mfma_f32_16x16x32_bf16 v[110:113], v[130:133], v[200:203], v[110:113]
	v_mfma_f32_16x16x32_bf16 v[106:109], v[156:159], v[200:203], v[106:109]
	v_mfma_f32_16x16x32_bf16 v[94:97], v[130:133], v[208:211], v[94:97]
	v_mfma_f32_16x16x32_bf16 v[90:93], v[156:159], v[208:211], v[90:93]
	v_mfma_f32_16x16x32_bf16 v[78:81], v[130:133], v[216:219], v[78:81]
	v_mfma_f32_16x16x32_bf16 v[74:77], v[156:159], v[216:219], v[74:77]
	v_mfma_f32_16x16x32_bf16 v[126:129], v[134:137], v[196:199], v[126:129]
	v_mfma_f32_16x16x32_bf16 v[122:125], v[160:163], v[196:199], v[122:125]
	v_mfma_f32_16x16x32_bf16 v[110:113], v[134:137], v[204:207], v[110:113]
	v_mfma_f32_16x16x32_bf16 v[106:109], v[160:163], v[204:207], v[106:109]
	v_mfma_f32_16x16x32_bf16 v[94:97], v[134:137], v[212:215], v[94:97]
	v_mfma_f32_16x16x32_bf16 v[90:93], v[160:163], v[212:215], v[90:93]
	v_mfma_f32_16x16x32_bf16 v[78:81], v[134:137], v[220:223], v[78:81]
	v_mfma_f32_16x16x32_bf16 v[74:77], v[160:163], v[220:223], v[74:77]
	v_mfma_f32_16x16x32_bf16 v[118:121], v[174:177], v[192:195], v[118:121]
	v_mfma_f32_16x16x32_bf16 v[114:117], v[182:185], v[192:195], v[114:117]
	v_mfma_f32_16x16x32_bf16 v[102:105], v[174:177], v[200:203], v[102:105]
	v_mfma_f32_16x16x32_bf16 v[98:101], v[182:185], v[200:203], v[98:101]
	v_mfma_f32_16x16x32_bf16 v[86:89], v[174:177], v[208:211], v[86:89]
	v_mfma_f32_16x16x32_bf16 v[82:85], v[182:185], v[208:211], v[82:85]
	v_mfma_f32_16x16x32_bf16 v[70:73], v[174:177], v[216:219], v[70:73]
	v_mfma_f32_16x16x32_bf16 v[66:69], v[182:185], v[216:219], v[66:69]
	v_mfma_f32_16x16x32_bf16 v[118:121], v[178:181], v[196:199], v[118:121]
	v_mfma_f32_16x16x32_bf16 v[114:117], v[188:191], v[196:199], v[114:117]
	v_mfma_f32_16x16x32_bf16 v[102:105], v[178:181], v[204:207], v[102:105]
	v_mfma_f32_16x16x32_bf16 v[98:101], v[188:191], v[204:207], v[98:101]
	v_mfma_f32_16x16x32_bf16 v[86:89], v[178:181], v[212:215], v[86:89]
	v_mfma_f32_16x16x32_bf16 v[82:85], v[188:191], v[212:215], v[82:85]
	v_mfma_f32_16x16x32_bf16 v[70:73], v[178:181], v[220:223], v[70:73]
	v_mfma_f32_16x16x32_bf16 v[66:69], v[188:191], v[220:223], v[66:69]
	s_setprio 0
	s_barrier
	s_add_i32 s63, s63, s52
	v_lshl_add_u64 v[138:139], s[46:47], 0, v[142:143]
	s_mov_b32 m0, s63
	ds_read_b128 v[192:195], v172 offset:16384
	ds_read_b128 v[196:199], v172 offset:17408
	ds_read_b128 v[200:203], v172 offset:18432
	ds_read_b128 v[204:207], v172 offset:19456
	ds_read_b128 v[208:211], v172 offset:20480
	ds_read_b128 v[212:215], v172 offset:21504
	ds_read_b128 v[216:219], v172 offset:22528
	ds_read_b128 v[220:223], v172 offset:23552
	global_load_lds_dwordx4 v[138:139], off
	s_add_i32 m0, s63, 0x2000
	s_add_u32 s64, s46, 0x40000
	v_lshl_add_u64 v[224:225], s[46:47], 0, v[146:147]
	s_addc_u32 s65, s47, 0
	s_add_i32 s63, s66, s52
	global_load_lds_dwordx4 v[224:225], off
	v_lshl_add_u64 v[226:227], s[64:65], 0, v[142:143]
	s_mov_b32 m0, s63
	v_lshl_add_u64 v[228:229], s[48:49], 0, v[144:145]
	global_load_lds_dwordx4 v[226:227], off
	v_lshl_add_u64 v[226:227], s[64:65], 0, v[146:147]
	s_add_i32 m0, s63, 0x2000
	s_nop 0
	global_load_lds_dwordx4 v[226:227], off
	v_lshl_add_u64 v[226:227], s[48:49], 0, v[140:141]
	s_mov_b32 m0, s43
	s_nop 0
	s_mov_b32 m0, s53
	s_nop 0
	s_waitcnt vmcnt(6)
	s_waitcnt lgkmcnt(0)
	s_setprio 1
	s_barrier
; #define PG8_STAGE(bufoff, gbase, voff) do { _Pragma("unroll") for (int _i = 0; _i < 2; ++_i) \
;         __builtin_amdgcn_global_load_lds((const unsigned*)((const char*)(gbase) + (voff)[_i]), (PG8_LAS unsigned*)(lds + (bufoff) + ldsw + _i * 8192), 16, 0, 0); } while (0)
; #define PG8_LDA(dst, b, h) do { _Pragma("unroll") for (int m = 0; m < 4; ++m) _Pragma("unroll") for (int k = 0; k < 2; ++k) dst[m][k] = *(const PG8_LAS bf16x8*)(lds + PG8_SA(b, h) + aoff + m * 2048 + k * 1024); } while (0)
; #define PG8_LDB(dst, b, h) do { _Pragma("unroll") for (int n = 0; n < 2; ++n) _Pragma("unroll") for (int k = 0; k < 2; ++k) dst[n][k] = *(const PG8_LAS bf16x8*)(lds + PG8_SB(b, h) + boff + n * 2048 + k * 1024); } while (0)
; #define PG8_MMA(ai, bj, At, Bt) do { __builtin_amdgcn_s_setprio(1); _Pragma("unroll") for (int m = 0; m < 4; ++m) _Pragma("unroll") for (int n = 0; n < 2; ++n) _Pragma("unroll") for (int k = 0; k < 2; ++k) \
;         acc[ai][bj][m][n] = __builtin_amdgcn_mfma_f32_16x16x32_bf16(Bt[n][k], At[m][k], acc[ai][bj][m][n], 0, 0, 0); __builtin_amdgcn_s_setprio(0); } while (0)
; #define PG8_WAIT_V(n) asm volatile("s_waitcnt vmcnt(" #n ")" ::: "memory")
; #define PG8_WAIT_L(n) asm volatile("s_waitcnt lgkmcnt(" #n ")" ::: "memory")
; #define PG8_BAR __builtin_amdgcn_s_barrier()
; #define PG8_SCHED __builtin_amdgcn_sched_barrier(0)
; template <class Epi, class Sched, bool ALIGN_EPI = false, bool SP2 = false>
; __device__ __forceinline__ void gemm_phase(PG8_LAS unsigned char* lds, const Gemm g, const Sched& S, const Epi& E) {
;     ...
;             PG8_WAIT_V(8); PG8_WAIT_L(0); PG8_BAR; PG8_MMA(1, 0, At, B0); PG8_MMA(1, 1, At, B1); PG8_BAR; PG8_SCHED;
;             PG8_LDB(B0, 1, 0); PG8_LDB(B1, 1, 1); PG8_SCHED; PG8_LDA(At, 1, 0); PG8_STAGE(PG8_SA(0, 1), a2 + hstep, voffA);
;             PG8_WAIT_V(8); PG8_WAIT_L(0); PG8_BAR; PG8_MMA(0, 0, At, B0); PG8_MMA(0, 1, At, B1); PG8_BAR; PG8_SCHED;
	v_mfma_f32_16x16x32_bf16 v[62:65], v[130:133], v[192:195], v[62:65]
	v_mfma_f32_16x16x32_bf16 v[58:61], v[156:159], v[192:195], v[58:61]
	v_mfma_f32_16x16x32_bf16 v[46:49], v[130:133], v[200:203], v[46:49]
	v_mfma_f32_16x16x32_bf16 v[42:45], v[156:159], v[200:203], v[42:45]
	v_mfma_f32_16x16x32_bf16 v[30:33], v[130:133], v[208:211], v[30:33]
	v_mfma_f32_16x16x32_bf16 v[26:29], v[156:159], v[208:211], v[26:29]
	v_mfma_f32_16x16x32_bf16 v[14:17], v[130:133], v[216:219], v[14:17]
	v_mfma_f32_16x16x32_bf16 v[10:13], v[156:159], v[216:219], v[10:13]
	v_mfma_f32_16x16x32_bf16 v[62:65], v[134:137], v[196:199], v[62:65]
	v_mfma_f32_16x16x32_bf16 v[58:61], v[160:163], v[196:199], v[58:61]
	v_mfma_f32_16x16x32_bf16 v[46:49], v[134:137], v[204:207], v[46:49]
	v_mfma_f32_16x16x32_bf16 v[42:45], v[160:163], v[204:207], v[42:45]
	v_mfma_f32_16x16x32_bf16 v[30:33], v[134:137], v[212:215], v[30:33]
	v_mfma_f32_16x16x32_bf16 v[26:29], v[160:163], v[212:215], v[26:29]
	v_mfma_f32_16x16x32_bf16 v[14:17], v[134:137], v[220:223], v[14:17]
	v_mfma_f32_16x16x32_bf16 v[10:13], v[160:163], v[220:223], v[10:13]
	v_mfma_f32_16x16x32_bf16 v[54:57], v[174:177], v[192:195], v[54:57]
	v_mfma_f32_16x16x32_bf16 v[50:53], v[182:185], v[192:195], v[50:53]
	v_mfma_f32_16x16x32_bf16 v[38:41], v[174:177], v[200:203], v[38:41]
	v_mfma_f32_16x16x32_bf16 v[34:37], v[182:185], v[200:203], v[34:37]
	v_mfma_f32_16x16x32_bf16 v[22:25], v[174:177], v[208:211], v[22:25]
	v_mfma_f32_16x16x32_bf16 v[18:21], v[182:185], v[208:211], v[18:21]
	v_mfma_f32_16x16x32_bf16 v[6:9], v[174:177], v[216:219], v[6:9]
	v_mfma_f32_16x16x32_bf16 v[2:5], v[182:185], v[216:219], v[2:5]
	v_mfma_f32_16x16x32_bf16 v[54:57], v[178:181], v[196:199], v[54:57]
	v_mfma_f32_16x16x32_bf16 v[50:53], v[188:191], v[196:199], v[50:53]
	v_mfma_f32_16x16x32_bf16 v[38:41], v[178:181], v[204:207], v[38:41]
	v_mfma_f32_16x16x32_bf16 v[34:37], v[188:191], v[204:207], v[34:37]
	v_mfma_f32_16x16x32_bf16 v[22:25], v[178:181], v[212:215], v[22:25]
	v_mfma_f32_16x16x32_bf16 v[18:21], v[188:191], v[212:215], v[18:21]
	v_mfma_f32_16x16x32_bf16 v[6:9], v[178:181], v[220:223], v[6:9]
	v_mfma_f32_16x16x32_bf16 v[2:5], v[188:191], v[220:223], v[2:5]
	s_setprio 0
	s_barrier
	s_add_i32 s63, 0, 0x18000
	s_add_i32 s64, 0, 0x1c000
	v_add_u32_e32 v160, s63, v170
	v_add_u32_e32 v173, s64, v170
	ds_read_b128 v[130:133], v160
	ds_read_b128 v[134:137], v160 offset:1024
	ds_read_b128 v[156:159], v160 offset:2048
	ds_read_b128 v[160:163], v160 offset:3072
	ds_read_b128 v[174:177], v173
	ds_read_b128 v[178:181], v173 offset:1024
	ds_read_b128 v[182:185], v173 offset:2048
	ds_read_b128 v[188:191], v173 offset:3072
	s_add_u32 s48, s48, 0x40000
	s_addc_u32 s49, s49, 0
	s_mov_b32 m0, s54
	v_lshl_add_u64 v[230:231], s[48:49], 0, v[140:141]
	ds_read_b128 v[192:195], v172 offset:32768
	ds_read_b128 v[196:199], v172 offset:33792
	ds_read_b128 v[200:203], v172 offset:34816
	ds_read_b128 v[204:207], v172 offset:35840
	ds_read_b128 v[208:211], v172 offset:36864
	ds_read_b128 v[212:215], v172 offset:37888
	ds_read_b128 v[216:219], v172 offset:38912
	ds_read_b128 v[220:223], v172 offset:39936
	s_add_u32 s98, s48, 0xfffc0000
	s_addc_u32 s99, s49, -1
	s_mov_b32 m0, s43
	s_nop 0
	global_load_lds_dwordx4 v140, s[98:99]
	s_mov_b32 m0, s53
	s_nop 0
	global_load_lds_dwordx4 v144, s[98:99]
	s_mov_b32 m0, s54
	s_nop 0
	global_load_lds_dwordx4 v[230:231], off
	v_lshl_add_u64 v[230:231], s[48:49], 0, v[144:145]
	s_mov_b32 m0, s55
	s_nop 0
	global_load_lds_dwordx4 v[230:231], off
	s_waitcnt vmcnt(8)
	s_waitcnt lgkmcnt(0)
	s_setprio 1
	s_barrier
	v_mfma_f32_16x16x32_bf16 v[126:129], v[130:133], v[192:195], v[126:129]
	v_mfma_f32_16x16x32_bf16 v[122:125], v[156:159], v[192:195], v[122:125]
	v_mfma_f32_16x16x32_bf16 v[110:113], v[130:133], v[200:203], v[110:113]
	v_mfma_f32_16x16x32_bf16 v[106:109], v[156:159], v[200:203], v[106:109]
	v_mfma_f32_16x16x32_bf16 v[94:97], v[130:133], v[208:211], v[94:97]
	v_mfma_f32_16x16x32_bf16 v[90:93], v[156:159], v[208:211], v[90:93]
	v_mfma_f32_16x16x32_bf16 v[78:81], v[130:133], v[216:219], v[78:81]
	v_mfma_f32_16x16x32_bf16 v[74:77], v[156:159], v[216:219], v[74:77]
	v_mfma_f32_16x16x32_bf16 v[126:129], v[134:137], v[196:199], v[126:129]
	v_mfma_f32_16x16x32_bf16 v[122:125], v[160:163], v[196:199], v[122:125]
	v_mfma_f32_16x16x32_bf16 v[110:113], v[134:137], v[204:207], v[110:113]
	v_mfma_f32_16x16x32_bf16 v[106:109], v[160:163], v[204:207], v[106:109]
	v_mfma_f32_16x16x32_bf16 v[94:97], v[134:137], v[212:215], v[94:97]
	v_mfma_f32_16x16x32_bf16 v[90:93], v[160:163], v[212:215], v[90:93]
	v_mfma_f32_16x16x32_bf16 v[78:81], v[134:137], v[220:223], v[78:81]
	v_mfma_f32_16x16x32_bf16 v[74:77], v[160:163], v[220:223], v[74:77]
	v_mfma_f32_16x16x32_bf16 v[118:121], v[174:177], v[192:195], v[118:121]
	v_mfma_f32_16x16x32_bf16 v[114:117], v[182:185], v[192:195], v[114:117]
	v_mfma_f32_16x16x32_bf16 v[102:105], v[174:177], v[200:203], v[102:105]
	v_mfma_f32_16x16x32_bf16 v[98:101], v[182:185], v[200:203], v[98:101]
	v_mfma_f32_16x16x32_bf16 v[86:89], v[174:177], v[208:211], v[86:89]
	v_mfma_f32_16x16x32_bf16 v[82:85], v[182:185], v[208:211], v[82:85]
	v_mfma_f32_16x16x32_bf16 v[70:73], v[174:177], v[216:219], v[70:73]
	v_mfma_f32_16x16x32_bf16 v[66:69], v[182:185], v[216:219], v[66:69]
	v_mfma_f32_16x16x32_bf16 v[118:121], v[178:181], v[196:199], v[118:121]
	v_mfma_f32_16x16x32_bf16 v[114:117], v[188:191], v[196:199], v[114:117]
	v_mfma_f32_16x16x32_bf16 v[102:105], v[178:181], v[204:207], v[102:105]
	v_mfma_f32_16x16x32_bf16 v[98:101], v[188:191], v[204:207], v[98:101]
	v_mfma_f32_16x16x32_bf16 v[86:89], v[178:181], v[212:215], v[86:89]
	v_mfma_f32_16x16x32_bf16 v[82:85], v[188:191], v[212:215], v[82:85]
	v_mfma_f32_16x16x32_bf16 v[70:73], v[178:181], v[220:223], v[70:73]
	v_mfma_f32_16x16x32_bf16 v[66:69], v[188:191], v[220:223], v[66:69]
	s_setprio 0
	s_barrier
; #define PG8_STAGE(bufoff, gbase, voff) do { _Pragma("unroll") for (int _i = 0; _i < 2; ++_i) \
;         __builtin_amdgcn_global_load_lds((const unsigned*)((const char*)(gbase) + (voff)[_i]), (PG8_LAS unsigned*)(lds + (bufoff) + ldsw + _i * 8192), 16, 0, 0); } while (0)
; #define PG8_LDA(dst, b, h) do { _Pragma("unroll") for (int m = 0; m < 4; ++m) _Pragma("unroll") for (int k = 0; k < 2; ++k) dst[m][k] = *(const PG8_LAS bf16x8*)(lds + PG8_SA(b, h) + aoff + m * 2048 + k * 1024); } while (0)
; #define PG8_MMA(ai, bj, At, Bt) do { __builtin_amdgcn_s_setprio(1); _Pragma("unroll") for (int m = 0; m < 4; ++m) _Pragma("unroll") for (int n = 0; n < 2; ++n) _Pragma("unroll") for (int k = 0; k < 2; ++k) \
;         acc[ai][bj][m][n] = __builtin_amdgcn_mfma_f32_16x16x32_bf16(Bt[n][k], At[m][k], acc[ai][bj][m][n], 0, 0, 0); __builtin_amdgcn_s_setprio(0); } while (0)
; #define PG8_WAIT_V(n) asm volatile("s_waitcnt vmcnt(" #n ")" ::: "memory")
; #define PG8_WAIT_L(n) asm volatile("s_waitcnt lgkmcnt(" #n ")" ::: "memory")
; #define PG8_BAR __builtin_amdgcn_s_barrier()
; #define PG8_SCHED __builtin_amdgcn_sched_barrier(0)
; template <class Epi, class Sched, bool ALIGN_EPI = false, bool SP2 = false>
; __device__ __forceinline__ void gemm_phase(PG8_LAS unsigned char* lds, const Gemm g, const Sched& S, const Epi& E) {
;     ...
;             PG8_LDA(At, 1, 1); PG8_STAGE(PG8_SB(1, 0), b3, voffB); PG8_STAGE(PG8_SB(1, 1), b3 + hstep, voffB); PG8_STAGE(PG8_SA(1, 0), a3, voffA);
;             PG8_WAIT_V(8); PG8_WAIT_L(0); PG8_BAR; PG8_MMA(1, 0, At, B0); PG8_MMA(1, 1, At, B1); PG8_BAR; PG8_SCHED;
	s_add_i32 s48, s63, s52
	v_lshl_add_u64 v[138:139], v[138:139], 0, s[22:23]
	s_mov_b32 m0, s48
	ds_read_b128 v[192:195], v172 offset:49152
	ds_read_b128 v[196:199], v172 offset:50176
	ds_read_b128 v[200:203], v172 offset:51200
	ds_read_b128 v[204:207], v172 offset:52224
	ds_read_b128 v[208:211], v172 offset:53248
	ds_read_b128 v[212:215], v172 offset:54272
	ds_read_b128 v[216:219], v172 offset:55296
	ds_read_b128 v[220:223], v172 offset:56320
	global_load_lds_dwordx4 v[138:139], off
	s_add_i32 m0, s48, 0x2000
	s_add_u32 s46, s46, 0x40080
	v_lshl_add_u64 v[138:139], v[224:225], 0, s[22:23]
	s_addc_u32 s47, s47, 0
	s_add_i32 s48, s64, s52
	global_load_lds_dwordx4 v[138:139], off
	v_lshl_add_u64 v[138:139], s[46:47], 0, v[142:143]
	s_mov_b32 m0, s48
	s_nop 0
	global_load_lds_dwordx4 v[138:139], off
	v_lshl_add_u64 v[138:139], s[46:47], 0, v[146:147]
	s_add_i32 m0, s48, 0x2000
	s_nop 0
	global_load_lds_dwordx4 v[138:139], off
	v_lshl_add_u64 v[138:139], v[226:227], 0, s[22:23]
	s_mov_b32 m0, s56
	s_nop 0
	v_lshl_add_u64 v[138:139], v[228:229], 0, s[22:23]
	s_mov_b32 m0, s57
	s_nop 0
	s_waitcnt vmcnt(6)
	s_waitcnt lgkmcnt(0)
	s_setprio 1
	s_barrier
	v_mfma_f32_16x16x32_bf16 v[62:65], v[130:133], v[192:195], v[62:65]
	v_mfma_f32_16x16x32_bf16 v[58:61], v[156:159], v[192:195], v[58:61]
	v_mfma_f32_16x16x32_bf16 v[46:49], v[130:133], v[200:203], v[46:49]
	v_mfma_f32_16x16x32_bf16 v[42:45], v[156:159], v[200:203], v[42:45]
	v_mfma_f32_16x16x32_bf16 v[30:33], v[130:133], v[208:211], v[30:33]
	v_mfma_f32_16x16x32_bf16 v[26:29], v[156:159], v[208:211], v[26:29]
	v_mfma_f32_16x16x32_bf16 v[14:17], v[130:133], v[216:219], v[14:17]
	v_mfma_f32_16x16x32_bf16 v[10:13], v[156:159], v[216:219], v[10:13]
	v_mfma_f32_16x16x32_bf16 v[62:65], v[134:137], v[196:199], v[62:65]
	v_mfma_f32_16x16x32_bf16 v[58:61], v[160:163], v[196:199], v[58:61]
	v_mfma_f32_16x16x32_bf16 v[46:49], v[134:137], v[204:207], v[46:49]
	v_mfma_f32_16x16x32_bf16 v[42:45], v[160:163], v[204:207], v[42:45]
	v_mfma_f32_16x16x32_bf16 v[30:33], v[134:137], v[212:215], v[30:33]
	v_mfma_f32_16x16x32_bf16 v[26:29], v[160:163], v[212:215], v[26:29]
	v_mfma_f32_16x16x32_bf16 v[14:17], v[134:137], v[220:223], v[14:17]
	v_mfma_f32_16x16x32_bf16 v[10:13], v[160:163], v[220:223], v[10:13]
	v_mfma_f32_16x16x32_bf16 v[54:57], v[174:177], v[192:195], v[54:57]
	v_mfma_f32_16x16x32_bf16 v[50:53], v[182:185], v[192:195], v[50:53]
	v_mfma_f32_16x16x32_bf16 v[38:41], v[174:177], v[200:203], v[38:41]
	v_mfma_f32_16x16x32_bf16 v[34:37], v[182:185], v[200:203], v[34:37]
	v_mfma_f32_16x16x32_bf16 v[22:25], v[174:177], v[208:211], v[22:25]
	v_mfma_f32_16x16x32_bf16 v[18:21], v[182:185], v[208:211], v[18:21]
	v_mfma_f32_16x16x32_bf16 v[6:9], v[174:177], v[216:219], v[6:9]
	v_mfma_f32_16x16x32_bf16 v[2:5], v[182:185], v[216:219], v[2:5]
	v_mfma_f32_16x16x32_bf16 v[54:57], v[178:181], v[196:199], v[54:57]
	v_mfma_f32_16x16x32_bf16 v[50:53], v[188:191], v[196:199], v[50:53]
	v_mfma_f32_16x16x32_bf16 v[38:41], v[178:181], v[204:207], v[38:41]
	v_mfma_f32_16x16x32_bf16 v[34:37], v[188:191], v[204:207], v[34:37]
	v_mfma_f32_16x16x32_bf16 v[22:25], v[178:181], v[212:215], v[22:25]
	v_mfma_f32_16x16x32_bf16 v[18:21], v[188:191], v[212:215], v[18:21]
	v_mfma_f32_16x16x32_bf16 v[6:9], v[178:181], v[220:223], v[6:9]
	v_mfma_f32_16x16x32_bf16 v[2:5], v[188:191], v[220:223], v[2:5]
	s_setprio 0
	s_barrier
	s_add_i32 s62, s62, 2
	s_add_u32 s44, s44, 0x100
	s_addc_u32 s45, s45, 0
	s_add_u32 s60, s60, 0x100
	s_addc_u32 s61, s61, 0
	s_cmp_gt_u32 s62, 13
	s_cbranch_scc0 .LBB0_816
	s_and_b64 vcc, exec, s[30:31]
	s_cbranch_vccz .LBB0_819
	s_barrier

; #define PG8_STAGE(bufoff, gbase, voff) do { _Pragma("unroll") for (int _i = 0; _i < 2; ++_i) \
;         __builtin_amdgcn_global_load_lds((const unsigned*)((const char*)(gbase) + (voff)[_i]), (PG8_LAS unsigned*)(lds + (bufoff) + ldsw + _i * 8192), 16, 0, 0); } while (0)
; #define PG8_LDA(dst, b, h) do { _Pragma("unroll") for (int m = 0; m < 4; ++m) _Pragma("unroll") for (int k = 0; k < 2; ++k) dst[m][k] = *(const PG8_LAS bf16x8*)(lds + PG8_SA(b, h) + aoff + m * 2048 + k * 1024); } while (0)
; #define PG8_LDB(dst, b, h) do { _Pragma("unroll") for (int n = 0; n < 2; ++n) _Pragma("unroll") for (int k = 0; k < 2; ++k) dst[n][k] = *(const PG8_LAS bf16x8*)(lds + PG8_SB(b, h) + boff + n * 2048 + k * 1024); } while (0)
; #define PG8_MMA(ai, bj, At, Bt) do { __builtin_amdgcn_s_setprio(1); _Pragma("unroll") for (int m = 0; m < 4; ++m) _Pragma("unroll") for (int n = 0; n < 2; ++n) _Pragma("unroll") for (int k = 0; k < 2; ++k) \
;         acc[ai][bj][m][n] = __builtin_amdgcn_mfma_f32_16x16x32_bf16(Bt[n][k], At[m][k], acc[ai][bj][m][n], 0, 0, 0); __builtin_amdgcn_s_setprio(0); } while (0)
; #define PG8_WAIT_V(n) asm volatile("s_waitcnt vmcnt(" #n ")" ::: "memory")
; #define PG8_WAIT_L(n) asm volatile("s_waitcnt lgkmcnt(" #n ")" ::: "memory")
; #define PG8_BAR __builtin_amdgcn_s_barrier()
; #define PG8_SCHED __builtin_amdgcn_sched_barrier(0)
; template <class Epi, class Sched, bool ALIGN_EPI = false, bool SP2 = false>
; __device__ __forceinline__ void gemm_phase(PG8_LAS unsigned char* lds, const Gemm g, const Sched& S, const Epi& E) {
;     ...
;             PG8_LDB(B0, 0, 0); PG8_LDB(B1, 0, 1); PG8_SCHED; PG8_LDA(At, 0, 0); PG8_STAGE(PG8_SA(1, 1), a1 + hstep, voffA);
;             PG8_WAIT_V(8); PG8_WAIT_L(0); PG8_BAR; PG8_MMA(0, 0, At, B0); PG8_MMA(0, 1, At, B1); PG8_BAR; PG8_SCHED;
;             PG8_LDA(At, 0, 1); PG8_STAGE(PG8_SB(0, 0), b2, voffB); PG8_STAGE(PG8_SB(0, 1), b2 + hstep, voffB); PG8_STAGE(PG8_SA(0, 0), a2, voffA);
;             PG8_WAIT_V(8); PG8_WAIT_L(0); PG8_BAR; PG8_MMA(1, 0, At, B0); PG8_MMA(1, 1, At, B1); PG8_BAR; PG8_SCHED;
.LBB0_941:
	ds_read_b128 v[130:133], v165
	ds_read_b128 v[134:137], v165 offset:1024
	ds_read_b128 v[138:141], v165 offset:2048
	ds_read_b128 v[142:145], v165 offset:3072
	ds_read_b128 v[158:161], v166
	ds_read_b128 v[168:171], v166 offset:1024
	ds_read_b128 v[172:175], v166 offset:2048
	ds_read_b128 v[176:179], v166 offset:3072
	s_add_u32 s34, s30, 0xfff80080
	s_addc_u32 s35, s31, -1
	s_cmp_eq_u32 s53, 28
	s_cselect_b32 s37, s23, s35
	s_cselect_b32 s36, s49, s34
	s_cselect_b32 s35, s21, s52
	s_cselect_b32 s34, s50, s51
	v_lshl_add_u64 v[184:185], s[30:31], 0, v[150:151]
	s_add_i32 m0, s17, 0xc000
	ds_read_b128 v[180:183], v167
	ds_read_b128 v[188:191], v167 offset:1024
	ds_read_b128 v[192:195], v167 offset:2048
	ds_read_b128 v[196:199], v167 offset:3072
	ds_read_b128 v[200:203], v167 offset:4096
	ds_read_b128 v[204:207], v167 offset:5120
	ds_read_b128 v[208:211], v167 offset:6144
	ds_read_b128 v[212:215], v167 offset:7168
	s_add_u32 s98, s30, 0xfff80000
	s_addc_u32 s99, s31, -1
	s_mov_b32 m0, s42
	s_nop 0
	global_load_lds_dwordx4 v150, s[98:99]
	s_mov_b32 m0, s43
	s_nop 0
	global_load_lds_dwordx4 v152, s[98:99]
	s_add_i32 m0, s17, 0xc000
	s_nop 0
	global_load_lds_dwordx4 v[184:185], off
	v_lshl_add_u64 v[184:185], s[30:31], 0, v[152:153]
	s_add_i32 m0, s17, 0xe000
	s_nop 0
	global_load_lds_dwordx4 v[184:185], off
	s_waitcnt vmcnt(8)
	s_waitcnt lgkmcnt(0)
	s_setprio 1
	s_barrier
	v_mfma_f32_16x16x32_bf16 v[126:129], v[130:133], v[180:183], v[126:129]
	v_mfma_f32_16x16x32_bf16 v[122:125], v[138:141], v[180:183], v[122:125]
	v_mfma_f32_16x16x32_bf16 v[114:117], v[130:133], v[192:195], v[114:117]
	v_mfma_f32_16x16x32_bf16 v[110:113], v[138:141], v[192:195], v[110:113]
	v_mfma_f32_16x16x32_bf16 v[98:101], v[130:133], v[200:203], v[98:101]
	v_mfma_f32_16x16x32_bf16 v[94:97], v[138:141], v[200:203], v[94:97]
	v_mfma_f32_16x16x32_bf16 v[82:85], v[130:133], v[208:211], v[82:85]
	v_mfma_f32_16x16x32_bf16 v[78:81], v[138:141], v[208:211], v[78:81]
	v_mfma_f32_16x16x32_bf16 v[126:129], v[134:137], v[188:191], v[126:129]
	v_mfma_f32_16x16x32_bf16 v[122:125], v[142:145], v[188:191], v[122:125]
	v_mfma_f32_16x16x32_bf16 v[114:117], v[134:137], v[196:199], v[114:117]
	v_mfma_f32_16x16x32_bf16 v[110:113], v[142:145], v[196:199], v[110:113]
	v_mfma_f32_16x16x32_bf16 v[98:101], v[134:137], v[204:207], v[98:101]
	v_mfma_f32_16x16x32_bf16 v[94:97], v[142:145], v[204:207], v[94:97]
	v_mfma_f32_16x16x32_bf16 v[82:85], v[134:137], v[212:215], v[82:85]
	v_mfma_f32_16x16x32_bf16 v[78:81], v[142:145], v[212:215], v[78:81]
	v_mfma_f32_16x16x32_bf16 v[118:121], v[158:161], v[180:183], v[118:121]
	v_mfma_f32_16x16x32_bf16 v[106:109], v[172:175], v[180:183], v[106:109]
	v_mfma_f32_16x16x32_bf16 v[102:105], v[158:161], v[192:195], v[102:105]
	v_mfma_f32_16x16x32_bf16 v[90:93], v[172:175], v[192:195], v[90:93]
	v_mfma_f32_16x16x32_bf16 v[86:89], v[158:161], v[200:203], v[86:89]
	v_mfma_f32_16x16x32_bf16 v[74:77], v[172:175], v[200:203], v[74:77]
	v_mfma_f32_16x16x32_bf16 v[70:73], v[158:161], v[208:211], v[70:73]
	v_mfma_f32_16x16x32_bf16 v[66:69], v[172:175], v[208:211], v[66:69]
	v_mfma_f32_16x16x32_bf16 v[118:121], v[168:171], v[188:191], v[118:121]
	v_mfma_f32_16x16x32_bf16 v[106:109], v[176:179], v[188:191], v[106:109]
	v_mfma_f32_16x16x32_bf16 v[102:105], v[168:171], v[196:199], v[102:105]
	v_mfma_f32_16x16x32_bf16 v[90:93], v[176:179], v[196:199], v[90:93]
	v_mfma_f32_16x16x32_bf16 v[86:89], v[168:171], v[204:207], v[86:89]
	v_mfma_f32_16x16x32_bf16 v[74:77], v[176:179], v[204:207], v[74:77]
	v_mfma_f32_16x16x32_bf16 v[70:73], v[168:171], v[212:215], v[70:73]
	v_mfma_f32_16x16x32_bf16 v[66:69], v[176:179], v[212:215], v[66:69]
	s_setprio 0
	s_barrier
	s_add_i32 s54, s46, s16
	v_lshl_add_u64 v[184:185], s[34:35], 0, v[146:147]
	s_mov_b32 m0, s54
	ds_read_b128 v[180:183], v167 offset:16384
	ds_read_b128 v[188:191], v167 offset:17408
	ds_read_b128 v[192:195], v167 offset:18432
	ds_read_b128 v[196:199], v167 offset:19456
	ds_read_b128 v[200:203], v167 offset:20480
	ds_read_b128 v[204:207], v167 offset:21504
	ds_read_b128 v[208:211], v167 offset:22528
	ds_read_b128 v[212:215], v167 offset:23552
	global_load_lds_dwordx4 v[184:185], off
	s_add_i32 m0, s54, 0x2000
	s_add_u32 s54, s34, 0x80000
	v_lshl_add_u64 v[216:217], s[34:35], 0, v[148:149]
	s_addc_u32 s55, s35, 0
	s_add_i32 s56, s47, s16
	global_load_lds_dwordx4 v[216:217], off
	v_lshl_add_u64 v[218:219], s[54:55], 0, v[146:147]
	s_mov_b32 m0, s56
	v_lshl_add_u64 v[220:221], s[36:37], 0, v[148:149]
	global_load_lds_dwordx4 v[218:219], off
	v_lshl_add_u64 v[218:219], s[54:55], 0, v[148:149]
	s_add_i32 m0, s56, 0x2000
	s_nop 0
	global_load_lds_dwordx4 v[218:219], off
	v_lshl_add_u64 v[218:219], s[36:37], 0, v[146:147]
	s_mov_b32 m0, s17
	s_nop 0
	s_mov_b32 m0, s29
	s_nop 0
	s_waitcnt vmcnt(6)
	s_waitcnt lgkmcnt(0)
	s_setprio 1
	s_barrier
; #define PG8_STAGE(bufoff, gbase, voff) do { _Pragma("unroll") for (int _i = 0; _i < 2; ++_i) \
;         __builtin_amdgcn_global_load_lds((const unsigned*)((const char*)(gbase) + (voff)[_i]), (PG8_LAS unsigned*)(lds + (bufoff) + ldsw + _i * 8192), 16, 0, 0); } while (0)
; #define PG8_LDA(dst, b, h) do { _Pragma("unroll") for (int m = 0; m < 4; ++m) _Pragma("unroll") for (int k = 0; k < 2; ++k) dst[m][k] = *(const PG8_LAS bf16x8*)(lds + PG8_SA(b, h) + aoff + m * 2048 + k * 1024); } while (0)
; #define PG8_LDB(dst, b, h) do { _Pragma("unroll") for (int n = 0; n < 2; ++n) _Pragma("unroll") for (int k = 0; k < 2; ++k) dst[n][k] = *(const PG8_LAS bf16x8*)(lds + PG8_SB(b, h) + boff + n * 2048 + k * 1024); } while (0)
; #define PG8_MMA(ai, bj, At, Bt) do { __builtin_amdgcn_s_setprio(1); _Pragma("unroll") for (int m = 0; m < 4; ++m) _Pragma("unroll") for (int n = 0; n < 2; ++n) _Pragma("unroll") for (int k = 0; k < 2; ++k) \
;         acc[ai][bj][m][n] = __builtin_amdgcn_mfma_f32_16x16x32_bf16(Bt[n][k], At[m][k], acc[ai][bj][m][n], 0, 0, 0); __builtin_amdgcn_s_setprio(0); } while (0)
; #define PG8_WAIT_V(n) asm volatile("s_waitcnt vmcnt(" #n ")" ::: "memory")
; #define PG8_WAIT_L(n) asm volatile("s_waitcnt lgkmcnt(" #n ")" ::: "memory")
; #define PG8_BAR __builtin_amdgcn_s_barrier()
; #define PG8_SCHED __builtin_amdgcn_sched_barrier(0)
; template <class Epi, class Sched, bool ALIGN_EPI = false, bool SP2 = false>
; __device__ __forceinline__ void gemm_phase(PG8_LAS unsigned char* lds, const Gemm g, const Sched& S, const Epi& E) {
;     ...
;             PG8_WAIT_V(8); PG8_WAIT_L(0); PG8_BAR; PG8_MMA(1, 0, At, B0); PG8_MMA(1, 1, At, B1); PG8_BAR; PG8_SCHED;
;             PG8_LDB(B0, 1, 0); PG8_LDB(B1, 1, 1); PG8_SCHED; PG8_LDA(At, 1, 0); PG8_STAGE(PG8_SA(0, 1), a2 + hstep, voffA);
;             PG8_WAIT_V(8); PG8_WAIT_L(0); PG8_BAR; PG8_MMA(0, 0, At, B0); PG8_MMA(0, 1, At, B1); PG8_BAR; PG8_SCHED;
	v_mfma_f32_16x16x32_bf16 v[62:65], v[130:133], v[180:183], v[62:65]
	v_mfma_f32_16x16x32_bf16 v[58:61], v[138:141], v[180:183], v[58:61]
	v_mfma_f32_16x16x32_bf16 v[50:53], v[130:133], v[192:195], v[50:53]
	v_mfma_f32_16x16x32_bf16 v[46:49], v[138:141], v[192:195], v[46:49]
	v_mfma_f32_16x16x32_bf16 v[34:37], v[130:133], v[200:203], v[34:37]
	v_mfma_f32_16x16x32_bf16 v[30:33], v[138:141], v[200:203], v[30:33]
	v_mfma_f32_16x16x32_bf16 v[18:21], v[130:133], v[208:211], v[18:21]
	v_mfma_f32_16x16x32_bf16 v[14:17], v[138:141], v[208:211], v[14:17]
	v_mfma_f32_16x16x32_bf16 v[62:65], v[134:137], v[188:191], v[62:65]
	v_mfma_f32_16x16x32_bf16 v[58:61], v[142:145], v[188:191], v[58:61]
	v_mfma_f32_16x16x32_bf16 v[50:53], v[134:137], v[196:199], v[50:53]
	v_mfma_f32_16x16x32_bf16 v[46:49], v[142:145], v[196:199], v[46:49]
	v_mfma_f32_16x16x32_bf16 v[34:37], v[134:137], v[204:207], v[34:37]
	v_mfma_f32_16x16x32_bf16 v[30:33], v[142:145], v[204:207], v[30:33]
	v_mfma_f32_16x16x32_bf16 v[18:21], v[134:137], v[212:215], v[18:21]
	v_mfma_f32_16x16x32_bf16 v[14:17], v[142:145], v[212:215], v[14:17]
	v_mfma_f32_16x16x32_bf16 v[54:57], v[158:161], v[180:183], v[54:57]
	v_mfma_f32_16x16x32_bf16 v[42:45], v[172:175], v[180:183], v[42:45]
	v_mfma_f32_16x16x32_bf16 v[38:41], v[158:161], v[192:195], v[38:41]
	v_mfma_f32_16x16x32_bf16 v[26:29], v[172:175], v[192:195], v[26:29]
	v_mfma_f32_16x16x32_bf16 v[22:25], v[158:161], v[200:203], v[22:25]
	v_mfma_f32_16x16x32_bf16 v[10:13], v[172:175], v[200:203], v[10:13]
	v_mfma_f32_16x16x32_bf16 v[6:9], v[158:161], v[208:211], v[6:9]
	v_mfma_f32_16x16x32_bf16 v[2:5], v[172:175], v[208:211], v[2:5]
	v_mfma_f32_16x16x32_bf16 v[54:57], v[168:171], v[188:191], v[54:57]
	v_mfma_f32_16x16x32_bf16 v[42:45], v[176:179], v[188:191], v[42:45]
	v_mfma_f32_16x16x32_bf16 v[38:41], v[168:171], v[196:199], v[38:41]
	v_mfma_f32_16x16x32_bf16 v[26:29], v[176:179], v[196:199], v[26:29]
	v_mfma_f32_16x16x32_bf16 v[22:25], v[168:171], v[204:207], v[22:25]
	v_mfma_f32_16x16x32_bf16 v[10:13], v[176:179], v[204:207], v[10:13]
	v_mfma_f32_16x16x32_bf16 v[6:9], v[168:171], v[212:215], v[6:9]
	v_mfma_f32_16x16x32_bf16 v[2:5], v[176:179], v[212:215], v[2:5]
	s_setprio 0
	s_barrier
	s_add_i32 s54, 0, 0x18000
	s_add_i32 s55, 0, 0x1c000
	v_add_u32_e32 v142, s54, v163
	v_add_u32_e32 v176, s55, v163
	ds_read_b128 v[130:133], v142
	ds_read_b128 v[134:137], v142 offset:1024
	ds_read_b128 v[138:141], v142 offset:2048
	ds_read_b128 v[142:145], v142 offset:3072
	ds_read_b128 v[158:161], v176
	ds_read_b128 v[168:171], v176 offset:1024
	ds_read_b128 v[172:175], v176 offset:2048
	ds_read_b128 v[176:179], v176 offset:3072
	s_add_u32 s36, s36, 0x80000
	s_addc_u32 s37, s37, 0
	s_mov_b32 m0, s33
	v_lshl_add_u64 v[222:223], s[36:37], 0, v[146:147]
	ds_read_b128 v[180:183], v167 offset:32768
	ds_read_b128 v[188:191], v167 offset:33792
	ds_read_b128 v[192:195], v167 offset:34816
	ds_read_b128 v[196:199], v167 offset:35840
	ds_read_b128 v[200:203], v167 offset:36864
	ds_read_b128 v[204:207], v167 offset:37888
	ds_read_b128 v[208:211], v167 offset:38912
	ds_read_b128 v[212:215], v167 offset:39936
	s_add_u32 s98, s36, 0xfff80000
	s_addc_u32 s99, s37, -1
	s_mov_b32 m0, s17
	s_nop 0
	global_load_lds_dwordx4 v146, s[98:99]
	s_mov_b32 m0, s29
	s_nop 0
	global_load_lds_dwordx4 v148, s[98:99]
	s_mov_b32 m0, s33
	s_nop 0
	global_load_lds_dwordx4 v[222:223], off
	v_lshl_add_u64 v[222:223], s[36:37], 0, v[148:149]
	s_mov_b32 m0, s38
	s_nop 0
	global_load_lds_dwordx4 v[222:223], off
	s_waitcnt vmcnt(8)
	s_waitcnt lgkmcnt(0)
	s_setprio 1
	s_barrier
	v_mfma_f32_16x16x32_bf16 v[126:129], v[130:133], v[180:183], v[126:129]
	v_mfma_f32_16x16x32_bf16 v[122:125], v[138:141], v[180:183], v[122:125]
	v_mfma_f32_16x16x32_bf16 v[114:117], v[130:133], v[192:195], v[114:117]
	v_mfma_f32_16x16x32_bf16 v[110:113], v[138:141], v[192:195], v[110:113]
	v_mfma_f32_16x16x32_bf16 v[98:101], v[130:133], v[200:203], v[98:101]
	v_mfma_f32_16x16x32_bf16 v[94:97], v[138:141], v[200:203], v[94:97]
	v_mfma_f32_16x16x32_bf16 v[82:85], v[130:133], v[208:211], v[82:85]
	v_mfma_f32_16x16x32_bf16 v[78:81], v[138:141], v[208:211], v[78:81]
	v_mfma_f32_16x16x32_bf16 v[126:129], v[134:137], v[188:191], v[126:129]
	v_mfma_f32_16x16x32_bf16 v[122:125], v[142:145], v[188:191], v[122:125]
	v_mfma_f32_16x16x32_bf16 v[114:117], v[134:137], v[196:199], v[114:117]
	v_mfma_f32_16x16x32_bf16 v[110:113], v[142:145], v[196:199], v[110:113]
	v_mfma_f32_16x16x32_bf16 v[98:101], v[134:137], v[204:207], v[98:101]
	v_mfma_f32_16x16x32_bf16 v[94:97], v[142:145], v[204:207], v[94:97]
	v_mfma_f32_16x16x32_bf16 v[82:85], v[134:137], v[212:215], v[82:85]
	v_mfma_f32_16x16x32_bf16 v[78:81], v[142:145], v[212:215], v[78:81]
	v_mfma_f32_16x16x32_bf16 v[118:121], v[158:161], v[180:183], v[118:121]
	v_mfma_f32_16x16x32_bf16 v[106:109], v[172:175], v[180:183], v[106:109]
	v_mfma_f32_16x16x32_bf16 v[102:105], v[158:161], v[192:195], v[102:105]
	v_mfma_f32_16x16x32_bf16 v[90:93], v[172:175], v[192:195], v[90:93]
	v_mfma_f32_16x16x32_bf16 v[86:89], v[158:161], v[200:203], v[86:89]
	v_mfma_f32_16x16x32_bf16 v[74:77], v[172:175], v[200:203], v[74:77]
	v_mfma_f32_16x16x32_bf16 v[70:73], v[158:161], v[208:211], v[70:73]
	v_mfma_f32_16x16x32_bf16 v[66:69], v[172:175], v[208:211], v[66:69]
	v_mfma_f32_16x16x32_bf16 v[118:121], v[168:171], v[188:191], v[118:121]
	v_mfma_f32_16x16x32_bf16 v[106:109], v[176:179], v[188:191], v[106:109]
	v_mfma_f32_16x16x32_bf16 v[102:105], v[168:171], v[196:199], v[102:105]
	v_mfma_f32_16x16x32_bf16 v[90:93], v[176:179], v[196:199], v[90:93]
	v_mfma_f32_16x16x32_bf16 v[86:89], v[168:171], v[204:207], v[86:89]
	v_mfma_f32_16x16x32_bf16 v[74:77], v[176:179], v[204:207], v[74:77]
	v_mfma_f32_16x16x32_bf16 v[70:73], v[168:171], v[212:215], v[70:73]
	v_mfma_f32_16x16x32_bf16 v[66:69], v[176:179], v[212:215], v[66:69]
	s_setprio 0
	s_barrier
; #define PG8_STAGE(bufoff, gbase, voff) do { _Pragma("unroll") for (int _i = 0; _i < 2; ++_i) \
;         __builtin_amdgcn_global_load_lds((const unsigned*)((const char*)(gbase) + (voff)[_i]), (PG8_LAS unsigned*)(lds + (bufoff) + ldsw + _i * 8192), 16, 0, 0); } while (0)
; #define PG8_LDA(dst, b, h) do { _Pragma("unroll") for (int m = 0; m < 4; ++m) _Pragma("unroll") for (int k = 0; k < 2; ++k) dst[m][k] = *(const PG8_LAS bf16x8*)(lds + PG8_SA(b, h) + aoff + m * 2048 + k * 1024); } while (0)
; #define PG8_MMA(ai, bj, At, Bt) do { __builtin_amdgcn_s_setprio(1); _Pragma("unroll") for (int m = 0; m < 4; ++m) _Pragma("unroll") for (int n = 0; n < 2; ++n) _Pragma("unroll") for (int k = 0; k < 2; ++k) \
;         acc[ai][bj][m][n] = __builtin_amdgcn_mfma_f32_16x16x32_bf16(Bt[n][k], At[m][k], acc[ai][bj][m][n], 0, 0, 0); __builtin_amdgcn_s_setprio(0); } while (0)
; #define PG8_WAIT_V(n) asm volatile("s_waitcnt vmcnt(" #n ")" ::: "memory")
; #define PG8_WAIT_L(n) asm volatile("s_waitcnt lgkmcnt(" #n ")" ::: "memory")
; #define PG8_BAR __builtin_amdgcn_s_barrier()
; #define PG8_SCHED __builtin_amdgcn_sched_barrier(0)
; template <class Epi, class Sched, bool ALIGN_EPI = false, bool SP2 = false>
; __device__ __forceinline__ void gemm_phase(PG8_LAS unsigned char* lds, const Gemm g, const Sched& S, const Epi& E) {
;     ...
;             PG8_LDA(At, 1, 1); PG8_STAGE(PG8_SB(1, 0), b3, voffB); PG8_STAGE(PG8_SB(1, 1), b3 + hstep, voffB); PG8_STAGE(PG8_SA(1, 0), a3, voffA);
;             PG8_WAIT_V(8); PG8_WAIT_L(0); PG8_BAR; PG8_MMA(1, 0, At, B0); PG8_MMA(1, 1, At, B1); PG8_BAR; PG8_SCHED;
	s_add_i32 s36, s54, s16
	v_lshl_add_u64 v[184:185], v[184:185], 0, s[8:9]
	s_mov_b32 m0, s36
	ds_read_b128 v[180:183], v167 offset:49152
	ds_read_b128 v[188:191], v167 offset:50176
	ds_read_b128 v[192:195], v167 offset:51200
	ds_read_b128 v[196:199], v167 offset:52224
	ds_read_b128 v[200:203], v167 offset:53248
	ds_read_b128 v[204:207], v167 offset:54272
	ds_read_b128 v[208:211], v167 offset:55296
	ds_read_b128 v[212:215], v167 offset:56320
	global_load_lds_dwordx4 v[184:185], off
	s_add_i32 m0, s36, 0x2000
	s_add_u32 s34, s34, 0x80080
	v_lshl_add_u64 v[184:185], v[216:217], 0, s[8:9]
	s_addc_u32 s35, s35, 0
	s_add_i32 s36, s55, s16
	global_load_lds_dwordx4 v[184:185], off
	v_lshl_add_u64 v[184:185], s[34:35], 0, v[146:147]
	s_mov_b32 m0, s36
	s_nop 0
	global_load_lds_dwordx4 v[184:185], off
	v_lshl_add_u64 v[184:185], s[34:35], 0, v[148:149]
	s_add_i32 m0, s36, 0x2000
	s_nop 0
	global_load_lds_dwordx4 v[184:185], off
	v_lshl_add_u64 v[184:185], v[218:219], 0, s[8:9]
	s_mov_b32 m0, s42
	s_nop 0
	v_lshl_add_u64 v[184:185], v[220:221], 0, s[8:9]
	s_mov_b32 m0, s43
	s_nop 0
	s_waitcnt vmcnt(6)
	s_waitcnt lgkmcnt(0)
	s_setprio 1
	s_barrier
	v_mfma_f32_16x16x32_bf16 v[62:65], v[130:133], v[180:183], v[62:65]
	v_mfma_f32_16x16x32_bf16 v[58:61], v[138:141], v[180:183], v[58:61]
	v_mfma_f32_16x16x32_bf16 v[50:53], v[130:133], v[192:195], v[50:53]
	v_mfma_f32_16x16x32_bf16 v[46:49], v[138:141], v[192:195], v[46:49]
	v_mfma_f32_16x16x32_bf16 v[34:37], v[130:133], v[200:203], v[34:37]
	v_mfma_f32_16x16x32_bf16 v[30:33], v[138:141], v[200:203], v[30:33]
	v_mfma_f32_16x16x32_bf16 v[18:21], v[130:133], v[208:211], v[18:21]
	v_mfma_f32_16x16x32_bf16 v[14:17], v[138:141], v[208:211], v[14:17]
	v_mfma_f32_16x16x32_bf16 v[62:65], v[134:137], v[188:191], v[62:65]
	v_mfma_f32_16x16x32_bf16 v[58:61], v[142:145], v[188:191], v[58:61]
	v_mfma_f32_16x16x32_bf16 v[50:53], v[134:137], v[196:199], v[50:53]
	v_mfma_f32_16x16x32_bf16 v[46:49], v[142:145], v[196:199], v[46:49]
	v_mfma_f32_16x16x32_bf16 v[34:37], v[134:137], v[204:207], v[34:37]
	v_mfma_f32_16x16x32_bf16 v[30:33], v[142:145], v[204:207], v[30:33]
	v_mfma_f32_16x16x32_bf16 v[18:21], v[134:137], v[212:215], v[18:21]
	v_mfma_f32_16x16x32_bf16 v[14:17], v[142:145], v[212:215], v[14:17]
	v_mfma_f32_16x16x32_bf16 v[54:57], v[158:161], v[180:183], v[54:57]
	v_mfma_f32_16x16x32_bf16 v[42:45], v[172:175], v[180:183], v[42:45]
	v_mfma_f32_16x16x32_bf16 v[38:41], v[158:161], v[192:195], v[38:41]
	v_mfma_f32_16x16x32_bf16 v[26:29], v[172:175], v[192:195], v[26:29]
	v_mfma_f32_16x16x32_bf16 v[22:25], v[158:161], v[200:203], v[22:25]
	v_mfma_f32_16x16x32_bf16 v[10:13], v[172:175], v[200:203], v[10:13]
	v_mfma_f32_16x16x32_bf16 v[6:9], v[158:161], v[208:211], v[6:9]
	v_mfma_f32_16x16x32_bf16 v[2:5], v[172:175], v[208:211], v[2:5]
	v_mfma_f32_16x16x32_bf16 v[54:57], v[168:171], v[188:191], v[54:57]
	v_mfma_f32_16x16x32_bf16 v[42:45], v[176:179], v[188:191], v[42:45]
	v_mfma_f32_16x16x32_bf16 v[38:41], v[168:171], v[196:199], v[38:41]
	v_mfma_f32_16x16x32_bf16 v[26:29], v[176:179], v[196:199], v[26:29]
	v_mfma_f32_16x16x32_bf16 v[22:25], v[168:171], v[204:207], v[22:25]
	v_mfma_f32_16x16x32_bf16 v[10:13], v[176:179], v[204:207], v[10:13]
	v_mfma_f32_16x16x32_bf16 v[6:9], v[168:171], v[212:215], v[6:9]
	v_mfma_f32_16x16x32_bf16 v[2:5], v[176:179], v[212:215], v[2:5]
	s_setprio 0
	s_barrier
	s_add_i32 s53, s53, 2
	s_add_u32 s30, s30, 0x100
	s_addc_u32 s31, s31, 0
	s_add_u32 s51, s51, 0x100
	s_addc_u32 s52, s52, 0
	s_cmp_gt_u32 s53, 29
	s_cbranch_scc0 .LBB0_941
	s_and_b64 vcc, exec, s[18:19]
	s_cbranch_vccz .LBB0_944
	s_barrier

; #define PG8_STAGE(bufoff, gbase, voff) do { _Pragma("unroll") for (int _i = 0; _i < 2; ++_i) \
;         __builtin_amdgcn_global_load_lds((const unsigned*)((const char*)(gbase) + (voff)[_i]), (PG8_LAS unsigned*)(lds + (bufoff) + ldsw + _i * 8192), 16, 0, 0); } while (0)
; #define PG8_LDA(dst, b, h) do { _Pragma("unroll") for (int m = 0; m < 4; ++m) _Pragma("unroll") for (int k = 0; k < 2; ++k) dst[m][k] = *(const PG8_LAS bf16x8*)(lds + PG8_SA(b, h) + aoff + m * 2048 + k * 1024); } while (0)
; #define PG8_LDB(dst, b, h) do { _Pragma("unroll") for (int n = 0; n < 2; ++n) _Pragma("unroll") for (int k = 0; k < 2; ++k) dst[n][k] = *(const PG8_LAS bf16x8*)(lds + PG8_SB(b, h) + boff + n * 2048 + k * 1024); } while (0)
; #define PG8_MMA(ai, bj, At, Bt) do { __builtin_amdgcn_s_setprio(1); _Pragma("unroll") for (int m = 0; m < 4; ++m) _Pragma("unroll") for (int n = 0; n < 2; ++n) _Pragma("unroll") for (int k = 0; k < 2; ++k) \
;         acc[ai][bj][m][n] = __builtin_amdgcn_mfma_f32_16x16x32_bf16(Bt[n][k], At[m][k], acc[ai][bj][m][n], 0, 0, 0); __builtin_amdgcn_s_setprio(0); } while (0)
; #define PG8_WAIT_V(n) asm volatile("s_waitcnt vmcnt(" #n ")" ::: "memory")
; #define PG8_WAIT_L(n) asm volatile("s_waitcnt lgkmcnt(" #n ")" ::: "memory")
; #define PG8_BAR __builtin_amdgcn_s_barrier()
; #define PG8_SCHED __builtin_amdgcn_sched_barrier(0)
; template <class Epi, class Sched, bool ALIGN_EPI = false, bool SP2 = false>
; __device__ __forceinline__ void gemm_phase(PG8_LAS unsigned char* lds, const Gemm g, const Sched& S, const Epi& E) {
;     ...
;             PG8_LDB(B0, 0, 0); PG8_LDB(B1, 0, 1); PG8_SCHED; PG8_LDA(At, 0, 0); PG8_STAGE(PG8_SA(1, 1), a1 + hstep, voffA);
;             PG8_WAIT_V(8); PG8_WAIT_L(0); PG8_BAR; PG8_MMA(0, 0, At, B0); PG8_MMA(0, 1, At, B1); PG8_BAR; PG8_SCHED;
;             PG8_LDA(At, 0, 1); PG8_STAGE(PG8_SB(0, 0), b2, voffB); PG8_STAGE(PG8_SB(0, 1), b2 + hstep, voffB); PG8_STAGE(PG8_SA(0, 0), a2, voffA);
;             PG8_WAIT_V(8); PG8_WAIT_L(0); PG8_BAR; PG8_MMA(1, 0, At, B0); PG8_MMA(1, 1, At, B1); PG8_BAR; PG8_SCHED;
.LBB0_1098:
	ds_read_b128 v[154:157], v151
	ds_read_b128 v[158:161], v151 offset:1024
	ds_read_b128 v[162:165], v151 offset:2048
	ds_read_b128 v[166:169], v151 offset:3072
	ds_read_b128 v[170:173], v152
	ds_read_b128 v[174:177], v152 offset:1024
	ds_read_b128 v[178:181], v152 offset:2048
	ds_read_b128 v[182:185], v152 offset:3072
	s_add_u32 s30, s28, 0xfff80080
	s_addc_u32 s31, s29, -1
	s_cmp_eq_u32 s53, 28
	s_cselect_b32 s35, s21, s31
	s_cselect_b32 s34, s49, s30
	s_cselect_b32 s31, s19, s52
	s_cselect_b32 s30, s50, s51
	v_lshl_add_u64 v[146:147], s[28:29], 0, v[138:139]
	s_add_i32 m0, s27, 0xc000
	ds_read_b128 v[188:191], v153
	ds_read_b128 v[192:195], v153 offset:1024
	ds_read_b128 v[196:199], v153 offset:2048
	ds_read_b128 v[200:203], v153 offset:3072
	ds_read_b128 v[204:207], v153 offset:4096
	ds_read_b128 v[208:211], v153 offset:5120
	ds_read_b128 v[212:215], v153 offset:6144
	ds_read_b128 v[216:219], v153 offset:7168
	s_add_u32 s98, s28, 0xfff80000
	s_addc_u32 s99, s29, -1
	s_mov_b32 m0, s41
	s_nop 0
	global_load_lds_dwordx4 v138, s[98:99]
	s_mov_b32 m0, s42
	s_nop 0
	global_load_lds_dwordx4 v140, s[98:99]
	s_add_i32 m0, s27, 0xc000
	s_nop 0
	global_load_lds_dwordx4 v[146:147], off
	v_lshl_add_u64 v[146:147], s[28:29], 0, v[140:141]
	s_add_i32 m0, s27, 0xe000
	s_nop 0
	global_load_lds_dwordx4 v[146:147], off
	s_waitcnt vmcnt(8)
	s_waitcnt lgkmcnt(0)
	s_setprio 1
	s_barrier
	v_mfma_f32_16x16x32_bf16 v[126:129], v[154:157], v[188:191], v[126:129]
	v_mfma_f32_16x16x32_bf16 v[122:125], v[162:165], v[188:191], v[122:125]
	v_mfma_f32_16x16x32_bf16 v[110:113], v[154:157], v[196:199], v[110:113]
	v_mfma_f32_16x16x32_bf16 v[106:109], v[162:165], v[196:199], v[106:109]
	v_mfma_f32_16x16x32_bf16 v[94:97], v[154:157], v[204:207], v[94:97]
	v_mfma_f32_16x16x32_bf16 v[90:93], v[162:165], v[204:207], v[90:93]
	v_mfma_f32_16x16x32_bf16 v[78:81], v[154:157], v[212:215], v[78:81]
	v_mfma_f32_16x16x32_bf16 v[74:77], v[162:165], v[212:215], v[74:77]
	v_mfma_f32_16x16x32_bf16 v[126:129], v[158:161], v[192:195], v[126:129]
	v_mfma_f32_16x16x32_bf16 v[122:125], v[166:169], v[192:195], v[122:125]
	v_mfma_f32_16x16x32_bf16 v[110:113], v[158:161], v[200:203], v[110:113]
	v_mfma_f32_16x16x32_bf16 v[106:109], v[166:169], v[200:203], v[106:109]
	v_mfma_f32_16x16x32_bf16 v[94:97], v[158:161], v[208:211], v[94:97]
	v_mfma_f32_16x16x32_bf16 v[90:93], v[166:169], v[208:211], v[90:93]
	v_mfma_f32_16x16x32_bf16 v[78:81], v[158:161], v[216:219], v[78:81]
	v_mfma_f32_16x16x32_bf16 v[74:77], v[166:169], v[216:219], v[74:77]
	v_mfma_f32_16x16x32_bf16 v[118:121], v[170:173], v[188:191], v[118:121]
	v_mfma_f32_16x16x32_bf16 v[114:117], v[178:181], v[188:191], v[114:117]
	v_mfma_f32_16x16x32_bf16 v[102:105], v[170:173], v[196:199], v[102:105]
	v_mfma_f32_16x16x32_bf16 v[98:101], v[178:181], v[196:199], v[98:101]
	v_mfma_f32_16x16x32_bf16 v[86:89], v[170:173], v[204:207], v[86:89]
	v_mfma_f32_16x16x32_bf16 v[82:85], v[178:181], v[204:207], v[82:85]
	v_mfma_f32_16x16x32_bf16 v[70:73], v[170:173], v[212:215], v[70:73]
	v_mfma_f32_16x16x32_bf16 v[66:69], v[178:181], v[212:215], v[66:69]
	v_mfma_f32_16x16x32_bf16 v[118:121], v[174:177], v[192:195], v[118:121]
	v_mfma_f32_16x16x32_bf16 v[114:117], v[182:185], v[192:195], v[114:117]
	v_mfma_f32_16x16x32_bf16 v[102:105], v[174:177], v[200:203], v[102:105]
	v_mfma_f32_16x16x32_bf16 v[98:101], v[182:185], v[200:203], v[98:101]
	v_mfma_f32_16x16x32_bf16 v[86:89], v[174:177], v[208:211], v[86:89]
	v_mfma_f32_16x16x32_bf16 v[82:85], v[182:185], v[208:211], v[82:85]
	v_mfma_f32_16x16x32_bf16 v[70:73], v[174:177], v[216:219], v[70:73]
	v_mfma_f32_16x16x32_bf16 v[66:69], v[182:185], v[216:219], v[66:69]
	s_setprio 0
	s_barrier
	s_add_i32 s54, s45, s3
	v_lshl_add_u64 v[146:147], s[30:31], 0, v[134:135]
	s_mov_b32 m0, s54
	ds_read_b128 v[188:191], v153 offset:16384
	ds_read_b128 v[192:195], v153 offset:17408
	ds_read_b128 v[196:199], v153 offset:18432
	ds_read_b128 v[200:203], v153 offset:19456
	ds_read_b128 v[204:207], v153 offset:20480
	ds_read_b128 v[208:211], v153 offset:21504
	ds_read_b128 v[212:215], v153 offset:22528
	ds_read_b128 v[216:219], v153 offset:23552
	global_load_lds_dwordx4 v[146:147], off
	s_add_i32 m0, s54, 0x2000
	s_add_u32 s54, s30, 0x80000
	v_lshl_add_u64 v[220:221], s[30:31], 0, v[130:131]
	s_addc_u32 s55, s31, 0
	s_add_i32 s56, s46, s3
	global_load_lds_dwordx4 v[220:221], off
	v_lshl_add_u64 v[222:223], s[54:55], 0, v[134:135]
	s_mov_b32 m0, s56
	v_lshl_add_u64 v[224:225], s[34:35], 0, v[132:133]
	global_load_lds_dwordx4 v[222:223], off
	v_lshl_add_u64 v[222:223], s[54:55], 0, v[130:131]
	s_add_i32 m0, s56, 0x2000
	s_nop 0
	global_load_lds_dwordx4 v[222:223], off
	v_lshl_add_u64 v[222:223], s[34:35], 0, v[136:137]
	s_mov_b32 m0, s27
	s_nop 0
	s_mov_b32 m0, s37
	s_nop 0
	s_waitcnt vmcnt(6)
	s_waitcnt lgkmcnt(0)
	s_setprio 1
	s_barrier
; #define PG8_STAGE(bufoff, gbase, voff) do { _Pragma("unroll") for (int _i = 0; _i < 2; ++_i) \
;         __builtin_amdgcn_global_load_lds((const unsigned*)((const char*)(gbase) + (voff)[_i]), (PG8_LAS unsigned*)(lds + (bufoff) + ldsw + _i * 8192), 16, 0, 0); } while (0)
; #define PG8_LDA(dst, b, h) do { _Pragma("unroll") for (int m = 0; m < 4; ++m) _Pragma("unroll") for (int k = 0; k < 2; ++k) dst[m][k] = *(const PG8_LAS bf16x8*)(lds + PG8_SA(b, h) + aoff + m * 2048 + k * 1024); } while (0)
; #define PG8_LDB(dst, b, h) do { _Pragma("unroll") for (int n = 0; n < 2; ++n) _Pragma("unroll") for (int k = 0; k < 2; ++k) dst[n][k] = *(const PG8_LAS bf16x8*)(lds + PG8_SB(b, h) + boff + n * 2048 + k * 1024); } while (0)
; #define PG8_MMA(ai, bj, At, Bt) do { __builtin_amdgcn_s_setprio(1); _Pragma("unroll") for (int m = 0; m < 4; ++m) _Pragma("unroll") for (int n = 0; n < 2; ++n) _Pragma("unroll") for (int k = 0; k < 2; ++k) \
;         acc[ai][bj][m][n] = __builtin_amdgcn_mfma_f32_16x16x32_bf16(Bt[n][k], At[m][k], acc[ai][bj][m][n], 0, 0, 0); __builtin_amdgcn_s_setprio(0); } while (0)
; #define PG8_WAIT_V(n) asm volatile("s_waitcnt vmcnt(" #n ")" ::: "memory")
; #define PG8_WAIT_L(n) asm volatile("s_waitcnt lgkmcnt(" #n ")" ::: "memory")
; #define PG8_BAR __builtin_amdgcn_s_barrier()
; #define PG8_SCHED __builtin_amdgcn_sched_barrier(0)
; template <class Epi, class Sched, bool ALIGN_EPI = false, bool SP2 = false>
; __device__ __forceinline__ void gemm_phase(PG8_LAS unsigned char* lds, const Gemm g, const Sched& S, const Epi& E) {
;     ...
;             PG8_WAIT_V(8); PG8_WAIT_L(0); PG8_BAR; PG8_MMA(1, 0, At, B0); PG8_MMA(1, 1, At, B1); PG8_BAR; PG8_SCHED;
;             PG8_LDB(B0, 1, 0); PG8_LDB(B1, 1, 1); PG8_SCHED; PG8_LDA(At, 1, 0); PG8_STAGE(PG8_SA(0, 1), a2 + hstep, voffA);
;             PG8_WAIT_V(8); PG8_WAIT_L(0); PG8_BAR; PG8_MMA(0, 0, At, B0); PG8_MMA(0, 1, At, B1); PG8_BAR; PG8_SCHED;
	v_mfma_f32_16x16x32_bf16 v[62:65], v[154:157], v[188:191], v[62:65]
	v_mfma_f32_16x16x32_bf16 v[58:61], v[162:165], v[188:191], v[58:61]
	v_mfma_f32_16x16x32_bf16 v[46:49], v[154:157], v[196:199], v[46:49]
	v_mfma_f32_16x16x32_bf16 v[42:45], v[162:165], v[196:199], v[42:45]
	v_mfma_f32_16x16x32_bf16 v[30:33], v[154:157], v[204:207], v[30:33]
	v_mfma_f32_16x16x32_bf16 v[26:29], v[162:165], v[204:207], v[26:29]
	v_mfma_f32_16x16x32_bf16 v[14:17], v[154:157], v[212:215], v[14:17]
	v_mfma_f32_16x16x32_bf16 v[10:13], v[162:165], v[212:215], v[10:13]
	v_mfma_f32_16x16x32_bf16 v[62:65], v[158:161], v[192:195], v[62:65]
	v_mfma_f32_16x16x32_bf16 v[58:61], v[166:169], v[192:195], v[58:61]
	v_mfma_f32_16x16x32_bf16 v[46:49], v[158:161], v[200:203], v[46:49]
	v_mfma_f32_16x16x32_bf16 v[42:45], v[166:169], v[200:203], v[42:45]
	v_mfma_f32_16x16x32_bf16 v[30:33], v[158:161], v[208:211], v[30:33]
	v_mfma_f32_16x16x32_bf16 v[26:29], v[166:169], v[208:211], v[26:29]
	v_mfma_f32_16x16x32_bf16 v[14:17], v[158:161], v[216:219], v[14:17]
	v_mfma_f32_16x16x32_bf16 v[10:13], v[166:169], v[216:219], v[10:13]
	v_mfma_f32_16x16x32_bf16 v[54:57], v[170:173], v[188:191], v[54:57]
	v_mfma_f32_16x16x32_bf16 v[50:53], v[178:181], v[188:191], v[50:53]
	v_mfma_f32_16x16x32_bf16 v[38:41], v[170:173], v[196:199], v[38:41]
	v_mfma_f32_16x16x32_bf16 v[34:37], v[178:181], v[196:199], v[34:37]
	v_mfma_f32_16x16x32_bf16 v[22:25], v[170:173], v[204:207], v[22:25]
	v_mfma_f32_16x16x32_bf16 v[18:21], v[178:181], v[204:207], v[18:21]
	v_mfma_f32_16x16x32_bf16 v[6:9], v[170:173], v[212:215], v[6:9]
	v_mfma_f32_16x16x32_bf16 v[2:5], v[178:181], v[212:215], v[2:5]
	v_mfma_f32_16x16x32_bf16 v[54:57], v[174:177], v[192:195], v[54:57]
	v_mfma_f32_16x16x32_bf16 v[50:53], v[182:185], v[192:195], v[50:53]
	v_mfma_f32_16x16x32_bf16 v[38:41], v[174:177], v[200:203], v[38:41]
	v_mfma_f32_16x16x32_bf16 v[34:37], v[182:185], v[200:203], v[34:37]
	v_mfma_f32_16x16x32_bf16 v[22:25], v[174:177], v[208:211], v[22:25]
	v_mfma_f32_16x16x32_bf16 v[18:21], v[182:185], v[208:211], v[18:21]
	v_mfma_f32_16x16x32_bf16 v[6:9], v[174:177], v[216:219], v[6:9]
	v_mfma_f32_16x16x32_bf16 v[2:5], v[182:185], v[216:219], v[2:5]
	s_setprio 0
	s_barrier
	s_add_i32 s54, 0, 0x18000
	s_add_i32 s55, 0, 0x1c000
	v_add_u32_e32 v166, s54, v149
	v_add_u32_e32 v182, s55, v149
	ds_read_b128 v[154:157], v166
	ds_read_b128 v[158:161], v166 offset:1024
	ds_read_b128 v[162:165], v166 offset:2048
	ds_read_b128 v[166:169], v166 offset:3072
	ds_read_b128 v[170:173], v182
	ds_read_b128 v[174:177], v182 offset:1024
	ds_read_b128 v[178:181], v182 offset:2048
	ds_read_b128 v[182:185], v182 offset:3072
	s_add_u32 s34, s34, 0x80000
	s_addc_u32 s35, s35, 0
	s_mov_b32 m0, s38
	v_lshl_add_u64 v[226:227], s[34:35], 0, v[136:137]
	ds_read_b128 v[188:191], v153 offset:32768
	ds_read_b128 v[192:195], v153 offset:33792
	ds_read_b128 v[196:199], v153 offset:34816
	ds_read_b128 v[200:203], v153 offset:35840
	ds_read_b128 v[204:207], v153 offset:36864
	ds_read_b128 v[208:211], v153 offset:37888
	ds_read_b128 v[212:215], v153 offset:38912
	ds_read_b128 v[216:219], v153 offset:39936
	s_add_u32 s98, s34, 0xfff80000
	s_addc_u32 s99, s35, -1
	s_mov_b32 m0, s27
	s_nop 0
	global_load_lds_dwordx4 v136, s[98:99]
	s_mov_b32 m0, s37
	s_nop 0
	global_load_lds_dwordx4 v132, s[98:99]
	s_mov_b32 m0, s38
	s_nop 0
	global_load_lds_dwordx4 v[226:227], off
	v_lshl_add_u64 v[226:227], s[34:35], 0, v[132:133]
	s_mov_b32 m0, s39
	s_nop 0
	global_load_lds_dwordx4 v[226:227], off
	s_waitcnt vmcnt(8)
	s_waitcnt lgkmcnt(0)
	s_setprio 1
	s_barrier
	v_mfma_f32_16x16x32_bf16 v[126:129], v[154:157], v[188:191], v[126:129]
	v_mfma_f32_16x16x32_bf16 v[122:125], v[162:165], v[188:191], v[122:125]
	v_mfma_f32_16x16x32_bf16 v[110:113], v[154:157], v[196:199], v[110:113]
	v_mfma_f32_16x16x32_bf16 v[106:109], v[162:165], v[196:199], v[106:109]
	v_mfma_f32_16x16x32_bf16 v[94:97], v[154:157], v[204:207], v[94:97]
	v_mfma_f32_16x16x32_bf16 v[90:93], v[162:165], v[204:207], v[90:93]
	v_mfma_f32_16x16x32_bf16 v[78:81], v[154:157], v[212:215], v[78:81]
	v_mfma_f32_16x16x32_bf16 v[74:77], v[162:165], v[212:215], v[74:77]
	v_mfma_f32_16x16x32_bf16 v[126:129], v[158:161], v[192:195], v[126:129]
	v_mfma_f32_16x16x32_bf16 v[122:125], v[166:169], v[192:195], v[122:125]
	v_mfma_f32_16x16x32_bf16 v[110:113], v[158:161], v[200:203], v[110:113]
	v_mfma_f32_16x16x32_bf16 v[106:109], v[166:169], v[200:203], v[106:109]
	v_mfma_f32_16x16x32_bf16 v[94:97], v[158:161], v[208:211], v[94:97]
	v_mfma_f32_16x16x32_bf16 v[90:93], v[166:169], v[208:211], v[90:93]
	v_mfma_f32_16x16x32_bf16 v[78:81], v[158:161], v[216:219], v[78:81]
	v_mfma_f32_16x16x32_bf16 v[74:77], v[166:169], v[216:219], v[74:77]
	v_mfma_f32_16x16x32_bf16 v[118:121], v[170:173], v[188:191], v[118:121]
	v_mfma_f32_16x16x32_bf16 v[114:117], v[178:181], v[188:191], v[114:117]
	v_mfma_f32_16x16x32_bf16 v[102:105], v[170:173], v[196:199], v[102:105]
	v_mfma_f32_16x16x32_bf16 v[98:101], v[178:181], v[196:199], v[98:101]
	v_mfma_f32_16x16x32_bf16 v[86:89], v[170:173], v[204:207], v[86:89]
	v_mfma_f32_16x16x32_bf16 v[82:85], v[178:181], v[204:207], v[82:85]
	v_mfma_f32_16x16x32_bf16 v[70:73], v[170:173], v[212:215], v[70:73]
	v_mfma_f32_16x16x32_bf16 v[66:69], v[178:181], v[212:215], v[66:69]
	v_mfma_f32_16x16x32_bf16 v[118:121], v[174:177], v[192:195], v[118:121]
	v_mfma_f32_16x16x32_bf16 v[114:117], v[182:185], v[192:195], v[114:117]
	v_mfma_f32_16x16x32_bf16 v[102:105], v[174:177], v[200:203], v[102:105]
	v_mfma_f32_16x16x32_bf16 v[98:101], v[182:185], v[200:203], v[98:101]
	v_mfma_f32_16x16x32_bf16 v[86:89], v[174:177], v[208:211], v[86:89]
	v_mfma_f32_16x16x32_bf16 v[82:85], v[182:185], v[208:211], v[82:85]
	v_mfma_f32_16x16x32_bf16 v[70:73], v[174:177], v[216:219], v[70:73]
	v_mfma_f32_16x16x32_bf16 v[66:69], v[182:185], v[216:219], v[66:69]
	s_setprio 0
	s_barrier
; #define PG8_STAGE(bufoff, gbase, voff) do { _Pragma("unroll") for (int _i = 0; _i < 2; ++_i) \
;         __builtin_amdgcn_global_load_lds((const unsigned*)((const char*)(gbase) + (voff)[_i]), (PG8_LAS unsigned*)(lds + (bufoff) + ldsw + _i * 8192), 16, 0, 0); } while (0)
; #define PG8_LDA(dst, b, h) do { _Pragma("unroll") for (int m = 0; m < 4; ++m) _Pragma("unroll") for (int k = 0; k < 2; ++k) dst[m][k] = *(const PG8_LAS bf16x8*)(lds + PG8_SA(b, h) + aoff + m * 2048 + k * 1024); } while (0)
; #define PG8_MMA(ai, bj, At, Bt) do { __builtin_amdgcn_s_setprio(1); _Pragma("unroll") for (int m = 0; m < 4; ++m) _Pragma("unroll") for (int n = 0; n < 2; ++n) _Pragma("unroll") for (int k = 0; k < 2; ++k) \
;         acc[ai][bj][m][n] = __builtin_amdgcn_mfma_f32_16x16x32_bf16(Bt[n][k], At[m][k], acc[ai][bj][m][n], 0, 0, 0); __builtin_amdgcn_s_setprio(0); } while (0)
; #define PG8_WAIT_V(n) asm volatile("s_waitcnt vmcnt(" #n ")" ::: "memory")
; #define PG8_WAIT_L(n) asm volatile("s_waitcnt lgkmcnt(" #n ")" ::: "memory")
; #define PG8_BAR __builtin_amdgcn_s_barrier()
; #define PG8_SCHED __builtin_amdgcn_sched_barrier(0)
; template <class Epi, class Sched, bool ALIGN_EPI = false, bool SP2 = false>
; __device__ __forceinline__ void gemm_phase(PG8_LAS unsigned char* lds, const Gemm g, const Sched& S, const Epi& E) {
;     ...
;         for (int t = 0; t < nt; t += 2) {
;             const bool last = (t == nt - 2);
;     ...
;             PG8_LDA(At, 1, 1); PG8_STAGE(PG8_SB(1, 0), b3, voffB); PG8_STAGE(PG8_SB(1, 1), b3 + hstep, voffB); PG8_STAGE(PG8_SA(1, 0), a3, voffA);
;             PG8_WAIT_V(8); PG8_WAIT_L(0); PG8_BAR; PG8_MMA(1, 0, At, B0); PG8_MMA(1, 1, At, B1); PG8_BAR; PG8_SCHED;
;     ...
;         if constexpr (ALIGN_EPI) { if (wr == 0) PG8_BAR; }
	s_add_i32 s34, s54, s3
	v_lshl_add_u64 v[146:147], v[146:147], 0, s[8:9]
	s_mov_b32 m0, s34
	ds_read_b128 v[188:191], v153 offset:49152
	ds_read_b128 v[192:195], v153 offset:50176
	ds_read_b128 v[196:199], v153 offset:51200
	ds_read_b128 v[200:203], v153 offset:52224
	ds_read_b128 v[204:207], v153 offset:53248
	ds_read_b128 v[208:211], v153 offset:54272
	ds_read_b128 v[212:215], v153 offset:55296
	ds_read_b128 v[216:219], v153 offset:56320
	global_load_lds_dwordx4 v[146:147], off
	s_add_i32 m0, s34, 0x2000
	s_add_u32 s30, s30, 0x80080
	v_lshl_add_u64 v[146:147], v[220:221], 0, s[8:9]
	s_addc_u32 s31, s31, 0
	s_add_i32 s34, s55, s3
	global_load_lds_dwordx4 v[146:147], off
	v_lshl_add_u64 v[146:147], s[30:31], 0, v[134:135]
	s_mov_b32 m0, s34
	s_nop 0
	global_load_lds_dwordx4 v[146:147], off
	v_lshl_add_u64 v[146:147], s[30:31], 0, v[130:131]
	s_add_i32 m0, s34, 0x2000
	s_nop 0
	global_load_lds_dwordx4 v[146:147], off
	v_lshl_add_u64 v[146:147], v[222:223], 0, s[8:9]
	s_mov_b32 m0, s41
	s_nop 0
	v_lshl_add_u64 v[146:147], v[224:225], 0, s[8:9]
	s_mov_b32 m0, s42
	s_nop 0
	s_waitcnt vmcnt(6)
	s_waitcnt lgkmcnt(0)
	s_setprio 1
	s_barrier
	v_mfma_f32_16x16x32_bf16 v[62:65], v[154:157], v[188:191], v[62:65]
	v_mfma_f32_16x16x32_bf16 v[58:61], v[162:165], v[188:191], v[58:61]
	v_mfma_f32_16x16x32_bf16 v[46:49], v[154:157], v[196:199], v[46:49]
	v_mfma_f32_16x16x32_bf16 v[42:45], v[162:165], v[196:199], v[42:45]
	v_mfma_f32_16x16x32_bf16 v[30:33], v[154:157], v[204:207], v[30:33]
	v_mfma_f32_16x16x32_bf16 v[26:29], v[162:165], v[204:207], v[26:29]
	v_mfma_f32_16x16x32_bf16 v[14:17], v[154:157], v[212:215], v[14:17]
	v_mfma_f32_16x16x32_bf16 v[10:13], v[162:165], v[212:215], v[10:13]
	v_mfma_f32_16x16x32_bf16 v[62:65], v[158:161], v[192:195], v[62:65]
	v_mfma_f32_16x16x32_bf16 v[58:61], v[166:169], v[192:195], v[58:61]
	v_mfma_f32_16x16x32_bf16 v[46:49], v[158:161], v[200:203], v[46:49]
	v_mfma_f32_16x16x32_bf16 v[42:45], v[166:169], v[200:203], v[42:45]
	v_mfma_f32_16x16x32_bf16 v[30:33], v[158:161], v[208:211], v[30:33]
	v_mfma_f32_16x16x32_bf16 v[26:29], v[166:169], v[208:211], v[26:29]
	v_mfma_f32_16x16x32_bf16 v[14:17], v[158:161], v[216:219], v[14:17]
	v_mfma_f32_16x16x32_bf16 v[10:13], v[166:169], v[216:219], v[10:13]
	v_mfma_f32_16x16x32_bf16 v[54:57], v[170:173], v[188:191], v[54:57]
	v_mfma_f32_16x16x32_bf16 v[50:53], v[178:181], v[188:191], v[50:53]
	v_mfma_f32_16x16x32_bf16 v[38:41], v[170:173], v[196:199], v[38:41]
	v_mfma_f32_16x16x32_bf16 v[34:37], v[178:181], v[196:199], v[34:37]
	v_mfma_f32_16x16x32_bf16 v[22:25], v[170:173], v[204:207], v[22:25]
	v_mfma_f32_16x16x32_bf16 v[18:21], v[178:181], v[204:207], v[18:21]
	v_mfma_f32_16x16x32_bf16 v[6:9], v[170:173], v[212:215], v[6:9]
	v_mfma_f32_16x16x32_bf16 v[2:5], v[178:181], v[212:215], v[2:5]
	v_mfma_f32_16x16x32_bf16 v[54:57], v[174:177], v[192:195], v[54:57]
	v_mfma_f32_16x16x32_bf16 v[50:53], v[182:185], v[192:195], v[50:53]
	v_mfma_f32_16x16x32_bf16 v[38:41], v[174:177], v[200:203], v[38:41]
	v_mfma_f32_16x16x32_bf16 v[34:37], v[182:185], v[200:203], v[34:37]
	v_mfma_f32_16x16x32_bf16 v[22:25], v[174:177], v[208:211], v[22:25]
	v_mfma_f32_16x16x32_bf16 v[18:21], v[182:185], v[208:211], v[18:21]
	v_mfma_f32_16x16x32_bf16 v[6:9], v[174:177], v[216:219], v[6:9]
	v_mfma_f32_16x16x32_bf16 v[2:5], v[182:185], v[216:219], v[2:5]
	s_setprio 0
	s_barrier
	s_add_i32 s53, s53, 2
	s_add_u32 s28, s28, 0x100
	s_addc_u32 s29, s29, 0
	s_add_u32 s51, s51, 0x100
	s_addc_u32 s52, s52, 0
	s_cmp_gt_u32 s53, 29
	s_cbranch_scc0 .LBB0_1098
	s_and_b64 vcc, exec, s[16:17]
	s_cbranch_vccz .LBB0_1101
	s_barrier

; #define PG8_STAGE(bufoff, gbase, voff) do { _Pragma("unroll") for (int _i = 0; _i < 2; ++_i) \
;         __builtin_amdgcn_global_load_lds((const unsigned*)((const char*)(gbase) + (voff)[_i]), (PG8_LAS unsigned*)(lds + (bufoff) + ldsw + _i * 8192), 16, 0, 0); } while (0)
; #define PG8_LDA(dst, b, h) do { _Pragma("unroll") for (int m = 0; m < 4; ++m) _Pragma("unroll") for (int k = 0; k < 2; ++k) dst[m][k] = *(const PG8_LAS bf16x8*)(lds + PG8_SA(b, h) + aoff + m * 2048 + k * 1024); } while (0)
; #define PG8_LDB(dst, b, h) do { _Pragma("unroll") for (int n = 0; n < 2; ++n) _Pragma("unroll") for (int k = 0; k < 2; ++k) dst[n][k] = *(const PG8_LAS bf16x8*)(lds + PG8_SB(b, h) + boff + n * 2048 + k * 1024); } while (0)
; #define PG8_MMA(ai, bj, At, Bt) do { __builtin_amdgcn_s_setprio(1); _Pragma("unroll") for (int m = 0; m < 4; ++m) _Pragma("unroll") for (int n = 0; n < 2; ++n) _Pragma("unroll") for (int k = 0; k < 2; ++k) \
;         acc[ai][bj][m][n] = __builtin_amdgcn_mfma_f32_16x16x32_bf16(Bt[n][k], At[m][k], acc[ai][bj][m][n], 0, 0, 0); __builtin_amdgcn_s_setprio(0); } while (0)
; #define PG8_WAIT_V(n) asm volatile("s_waitcnt vmcnt(" #n ")" ::: "memory")
; #define PG8_WAIT_L(n) asm volatile("s_waitcnt lgkmcnt(" #n ")" ::: "memory")
; #define PG8_BAR __builtin_amdgcn_s_barrier()
; #define PG8_SCHED __builtin_amdgcn_sched_barrier(0)
; template <class Epi, class Sched, bool ALIGN_EPI = false, bool SP2 = false>
; __device__ __forceinline__ void gemm_phase(PG8_LAS unsigned char* lds, const Gemm g, const Sched& S, const Epi& E) {
;     ...
;             PG8_LDB(B0, 0, 0); PG8_LDB(B1, 0, 1); PG8_SCHED; PG8_LDA(At, 0, 0); PG8_STAGE(PG8_SA(1, 1), a1 + hstep, voffA);
;             PG8_WAIT_V(8); PG8_WAIT_L(0); PG8_BAR; PG8_MMA(0, 0, At, B0); PG8_MMA(0, 1, At, B1); PG8_BAR; PG8_SCHED;
;             PG8_LDA(At, 0, 1); PG8_STAGE(PG8_SB(0, 0), b2, voffB); PG8_STAGE(PG8_SB(0, 1), b2 + hstep, voffB); PG8_STAGE(PG8_SA(0, 0), a2, voffA);
;             PG8_WAIT_V(8); PG8_WAIT_L(0); PG8_BAR; PG8_MMA(1, 0, At, B0); PG8_MMA(1, 1, At, B1); PG8_BAR; PG8_SCHED;
.LBB0_1195:
	ds_read_b128 v[130:133], v165
	ds_read_b128 v[134:137], v165 offset:1024
	ds_read_b128 v[138:141], v165 offset:2048
	ds_read_b128 v[142:145], v165 offset:3072
	ds_read_b128 v[158:161], v166
	ds_read_b128 v[168:171], v166 offset:1024
	ds_read_b128 v[172:175], v166 offset:2048
	ds_read_b128 v[176:179], v166 offset:3072
	s_add_u32 s24, s22, 0xffea0080
	s_addc_u32 s25, s23, -1
	s_cmpk_eq_i32 s49, 0x54
	s_cselect_b32 s27, s5, s25
	s_cselect_b32 s26, s4, s24
	s_cselect_b32 s25, s21, s48
	s_cselect_b32 s24, s20, s47
	v_lshl_add_u64 v[184:185], s[22:23], 0, v[150:151]
	s_add_i32 m0, s29, 0xc000
	ds_read_b128 v[180:183], v167
	ds_read_b128 v[188:191], v167 offset:1024
	ds_read_b128 v[192:195], v167 offset:2048
	ds_read_b128 v[196:199], v167 offset:3072
	ds_read_b128 v[200:203], v167 offset:4096
	ds_read_b128 v[204:207], v167 offset:5120
	ds_read_b128 v[208:211], v167 offset:6144
	ds_read_b128 v[212:215], v167 offset:7168
	s_add_u32 s98, s22, 0xffea0000
	s_addc_u32 s99, s23, -1
	s_mov_b32 m0, s37
	s_nop 0
	global_load_lds_dwordx4 v150, s[98:99]
	s_mov_b32 m0, s38
	s_nop 0
	global_load_lds_dwordx4 v152, s[98:99]
	s_add_i32 m0, s29, 0xc000
	s_nop 0
	global_load_lds_dwordx4 v[184:185], off
	v_lshl_add_u64 v[184:185], s[22:23], 0, v[152:153]
	s_add_i32 m0, s29, 0xe000
	s_nop 0
	global_load_lds_dwordx4 v[184:185], off
	s_waitcnt vmcnt(8)
	s_waitcnt lgkmcnt(0)
	s_setprio 1
	s_barrier
	v_mfma_f32_16x16x32_bf16 v[126:129], v[130:133], v[180:183], v[126:129]
	v_mfma_f32_16x16x32_bf16 v[122:125], v[138:141], v[180:183], v[122:125]
	v_mfma_f32_16x16x32_bf16 v[118:121], v[130:133], v[192:195], v[118:121]
	v_mfma_f32_16x16x32_bf16 v[114:117], v[138:141], v[192:195], v[114:117]
	v_mfma_f32_16x16x32_bf16 v[94:97], v[130:133], v[200:203], v[94:97]
	v_mfma_f32_16x16x32_bf16 v[90:93], v[138:141], v[200:203], v[90:93]
	v_mfma_f32_16x16x32_bf16 v[86:89], v[130:133], v[208:211], v[86:89]
	v_mfma_f32_16x16x32_bf16 v[82:85], v[138:141], v[208:211], v[82:85]
	v_mfma_f32_16x16x32_bf16 v[126:129], v[134:137], v[188:191], v[126:129]
	v_mfma_f32_16x16x32_bf16 v[122:125], v[142:145], v[188:191], v[122:125]
	v_mfma_f32_16x16x32_bf16 v[118:121], v[134:137], v[196:199], v[118:121]
	v_mfma_f32_16x16x32_bf16 v[114:117], v[142:145], v[196:199], v[114:117]
	v_mfma_f32_16x16x32_bf16 v[94:97], v[134:137], v[204:207], v[94:97]
	v_mfma_f32_16x16x32_bf16 v[90:93], v[142:145], v[204:207], v[90:93]
	v_mfma_f32_16x16x32_bf16 v[86:89], v[134:137], v[212:215], v[86:89]
	v_mfma_f32_16x16x32_bf16 v[82:85], v[142:145], v[212:215], v[82:85]
	v_mfma_f32_16x16x32_bf16 v[110:113], v[158:161], v[180:183], v[110:113]
	v_mfma_f32_16x16x32_bf16 v[106:109], v[172:175], v[180:183], v[106:109]
	v_mfma_f32_16x16x32_bf16 v[102:105], v[158:161], v[192:195], v[102:105]
	v_mfma_f32_16x16x32_bf16 v[98:101], v[172:175], v[192:195], v[98:101]
	v_mfma_f32_16x16x32_bf16 v[78:81], v[158:161], v[200:203], v[78:81]
	v_mfma_f32_16x16x32_bf16 v[74:77], v[172:175], v[200:203], v[74:77]
	v_mfma_f32_16x16x32_bf16 v[70:73], v[158:161], v[208:211], v[70:73]
	v_mfma_f32_16x16x32_bf16 v[66:69], v[172:175], v[208:211], v[66:69]
	v_mfma_f32_16x16x32_bf16 v[110:113], v[168:171], v[188:191], v[110:113]
	v_mfma_f32_16x16x32_bf16 v[106:109], v[176:179], v[188:191], v[106:109]
	v_mfma_f32_16x16x32_bf16 v[102:105], v[168:171], v[196:199], v[102:105]
	v_mfma_f32_16x16x32_bf16 v[98:101], v[176:179], v[196:199], v[98:101]
	v_mfma_f32_16x16x32_bf16 v[78:81], v[168:171], v[204:207], v[78:81]
	v_mfma_f32_16x16x32_bf16 v[74:77], v[176:179], v[204:207], v[74:77]
	v_mfma_f32_16x16x32_bf16 v[70:73], v[168:171], v[212:215], v[70:73]
	v_mfma_f32_16x16x32_bf16 v[66:69], v[176:179], v[212:215], v[66:69]
	s_setprio 0
	s_barrier
	s_add_i32 s50, s41, s28
	v_lshl_add_u64 v[184:185], s[24:25], 0, v[146:147]
	s_mov_b32 m0, s50
	ds_read_b128 v[180:183], v167 offset:16384
	ds_read_b128 v[188:191], v167 offset:17408
	ds_read_b128 v[192:195], v167 offset:18432
	ds_read_b128 v[196:199], v167 offset:19456
	ds_read_b128 v[200:203], v167 offset:20480
	ds_read_b128 v[204:207], v167 offset:21504
	ds_read_b128 v[208:211], v167 offset:22528
	ds_read_b128 v[212:215], v167 offset:23552
	global_load_lds_dwordx4 v[184:185], off
	s_add_i32 m0, s50, 0x2000
	s_add_u32 s50, s24, 0x160000
	v_lshl_add_u64 v[216:217], s[24:25], 0, v[148:149]
	s_addc_u32 s51, s25, 0
	s_add_i32 s52, s42, s28
	global_load_lds_dwordx4 v[216:217], off
	v_lshl_add_u64 v[218:219], s[50:51], 0, v[146:147]
	s_mov_b32 m0, s52
	v_lshl_add_u64 v[220:221], s[26:27], 0, v[148:149]
	global_load_lds_dwordx4 v[218:219], off
	v_lshl_add_u64 v[218:219], s[50:51], 0, v[148:149]
	s_add_i32 m0, s52, 0x2000
	s_nop 0
	global_load_lds_dwordx4 v[218:219], off
	v_lshl_add_u64 v[218:219], s[26:27], 0, v[146:147]
	s_mov_b32 m0, s29
	s_nop 0
	s_mov_b32 m0, s30
	s_nop 0
	s_waitcnt vmcnt(6)
	s_waitcnt lgkmcnt(0)
	s_setprio 1
	s_barrier
; #define PG8_STAGE(bufoff, gbase, voff) do { _Pragma("unroll") for (int _i = 0; _i < 2; ++_i) \
;         __builtin_amdgcn_global_load_lds((const unsigned*)((const char*)(gbase) + (voff)[_i]), (PG8_LAS unsigned*)(lds + (bufoff) + ldsw + _i * 8192), 16, 0, 0); } while (0)
; #define PG8_LDA(dst, b, h) do { _Pragma("unroll") for (int m = 0; m < 4; ++m) _Pragma("unroll") for (int k = 0; k < 2; ++k) dst[m][k] = *(const PG8_LAS bf16x8*)(lds + PG8_SA(b, h) + aoff + m * 2048 + k * 1024); } while (0)
; #define PG8_LDB(dst, b, h) do { _Pragma("unroll") for (int n = 0; n < 2; ++n) _Pragma("unroll") for (int k = 0; k < 2; ++k) dst[n][k] = *(const PG8_LAS bf16x8*)(lds + PG8_SB(b, h) + boff + n * 2048 + k * 1024); } while (0)
; #define PG8_MMA(ai, bj, At, Bt) do { __builtin_amdgcn_s_setprio(1); _Pragma("unroll") for (int m = 0; m < 4; ++m) _Pragma("unroll") for (int n = 0; n < 2; ++n) _Pragma("unroll") for (int k = 0; k < 2; ++k) \
;         acc[ai][bj][m][n] = __builtin_amdgcn_mfma_f32_16x16x32_bf16(Bt[n][k], At[m][k], acc[ai][bj][m][n], 0, 0, 0); __builtin_amdgcn_s_setprio(0); } while (0)
; #define PG8_WAIT_V(n) asm volatile("s_waitcnt vmcnt(" #n ")" ::: "memory")
; #define PG8_WAIT_L(n) asm volatile("s_waitcnt lgkmcnt(" #n ")" ::: "memory")
; #define PG8_BAR __builtin_amdgcn_s_barrier()
; #define PG8_SCHED __builtin_amdgcn_sched_barrier(0)
; template <class Epi, class Sched, bool ALIGN_EPI = false, bool SP2 = false>
; __device__ __forceinline__ void gemm_phase(PG8_LAS unsigned char* lds, const Gemm g, const Sched& S, const Epi& E) {
;     ...
;             PG8_WAIT_V(8); PG8_WAIT_L(0); PG8_BAR; PG8_MMA(1, 0, At, B0); PG8_MMA(1, 1, At, B1); PG8_BAR; PG8_SCHED;
;             PG8_LDB(B0, 1, 0); PG8_LDB(B1, 1, 1); PG8_SCHED; PG8_LDA(At, 1, 0); PG8_STAGE(PG8_SA(0, 1), a2 + hstep, voffA);
;             PG8_WAIT_V(8); PG8_WAIT_L(0); PG8_BAR; PG8_MMA(0, 0, At, B0); PG8_MMA(0, 1, At, B1); PG8_BAR; PG8_SCHED;
	v_mfma_f32_16x16x32_bf16 v[62:65], v[130:133], v[180:183], v[62:65]
	v_mfma_f32_16x16x32_bf16 v[58:61], v[138:141], v[180:183], v[58:61]
	v_mfma_f32_16x16x32_bf16 v[54:57], v[130:133], v[192:195], v[54:57]
	v_mfma_f32_16x16x32_bf16 v[50:53], v[138:141], v[192:195], v[50:53]
	v_mfma_f32_16x16x32_bf16 v[30:33], v[130:133], v[200:203], v[30:33]
	v_mfma_f32_16x16x32_bf16 v[26:29], v[138:141], v[200:203], v[26:29]
	v_mfma_f32_16x16x32_bf16 v[22:25], v[130:133], v[208:211], v[22:25]
	v_mfma_f32_16x16x32_bf16 v[18:21], v[138:141], v[208:211], v[18:21]
	v_mfma_f32_16x16x32_bf16 v[62:65], v[134:137], v[188:191], v[62:65]
	v_mfma_f32_16x16x32_bf16 v[58:61], v[142:145], v[188:191], v[58:61]
	v_mfma_f32_16x16x32_bf16 v[54:57], v[134:137], v[196:199], v[54:57]
	v_mfma_f32_16x16x32_bf16 v[50:53], v[142:145], v[196:199], v[50:53]
	v_mfma_f32_16x16x32_bf16 v[30:33], v[134:137], v[204:207], v[30:33]
	v_mfma_f32_16x16x32_bf16 v[26:29], v[142:145], v[204:207], v[26:29]
	v_mfma_f32_16x16x32_bf16 v[22:25], v[134:137], v[212:215], v[22:25]
	v_mfma_f32_16x16x32_bf16 v[18:21], v[142:145], v[212:215], v[18:21]
	v_mfma_f32_16x16x32_bf16 v[46:49], v[158:161], v[180:183], v[46:49]
	v_mfma_f32_16x16x32_bf16 v[42:45], v[172:175], v[180:183], v[42:45]
	v_mfma_f32_16x16x32_bf16 v[38:41], v[158:161], v[192:195], v[38:41]
	v_mfma_f32_16x16x32_bf16 v[34:37], v[172:175], v[192:195], v[34:37]
	v_mfma_f32_16x16x32_bf16 v[14:17], v[158:161], v[200:203], v[14:17]
	v_mfma_f32_16x16x32_bf16 v[10:13], v[172:175], v[200:203], v[10:13]
	v_mfma_f32_16x16x32_bf16 v[6:9], v[158:161], v[208:211], v[6:9]
	v_mfma_f32_16x16x32_bf16 v[2:5], v[172:175], v[208:211], v[2:5]
	v_mfma_f32_16x16x32_bf16 v[46:49], v[168:171], v[188:191], v[46:49]
	v_mfma_f32_16x16x32_bf16 v[42:45], v[176:179], v[188:191], v[42:45]
	v_mfma_f32_16x16x32_bf16 v[38:41], v[168:171], v[196:199], v[38:41]
	v_mfma_f32_16x16x32_bf16 v[34:37], v[176:179], v[196:199], v[34:37]
	v_mfma_f32_16x16x32_bf16 v[14:17], v[168:171], v[204:207], v[14:17]
	v_mfma_f32_16x16x32_bf16 v[10:13], v[176:179], v[204:207], v[10:13]
	v_mfma_f32_16x16x32_bf16 v[6:9], v[168:171], v[212:215], v[6:9]
	v_mfma_f32_16x16x32_bf16 v[2:5], v[176:179], v[212:215], v[2:5]
	s_setprio 0
	s_barrier
	s_add_i32 s50, 0, 0x18000
	s_add_i32 s51, 0, 0x1c000
	v_add_u32_e32 v142, s50, v163
	v_add_u32_e32 v176, s51, v163
	ds_read_b128 v[130:133], v142
	ds_read_b128 v[134:137], v142 offset:1024
	ds_read_b128 v[138:141], v142 offset:2048
	ds_read_b128 v[142:145], v142 offset:3072
	ds_read_b128 v[158:161], v176
	ds_read_b128 v[168:171], v176 offset:1024
	ds_read_b128 v[172:175], v176 offset:2048
	ds_read_b128 v[176:179], v176 offset:3072
	s_add_u32 s26, s26, 0x160000
	s_addc_u32 s27, s27, 0
	s_mov_b32 m0, s31
	v_lshl_add_u64 v[222:223], s[26:27], 0, v[146:147]
	ds_read_b128 v[180:183], v167 offset:32768
	ds_read_b128 v[188:191], v167 offset:33792
	ds_read_b128 v[192:195], v167 offset:34816
	ds_read_b128 v[196:199], v167 offset:35840
	ds_read_b128 v[200:203], v167 offset:36864
	ds_read_b128 v[204:207], v167 offset:37888
	ds_read_b128 v[208:211], v167 offset:38912
	ds_read_b128 v[212:215], v167 offset:39936
	s_add_u32 s98, s26, 0xffea0000
	s_addc_u32 s99, s27, -1
	s_mov_b32 m0, s29
	s_nop 0
	global_load_lds_dwordx4 v146, s[98:99]
	s_mov_b32 m0, s30
	s_nop 0
	global_load_lds_dwordx4 v148, s[98:99]
	s_mov_b32 m0, s31
	s_nop 0
	global_load_lds_dwordx4 v[222:223], off
	v_lshl_add_u64 v[222:223], s[26:27], 0, v[148:149]
	s_mov_b32 m0, s33
	s_nop 0
	global_load_lds_dwordx4 v[222:223], off
	s_waitcnt vmcnt(8)
	s_waitcnt lgkmcnt(0)
	s_setprio 1
	s_barrier
	v_mfma_f32_16x16x32_bf16 v[126:129], v[130:133], v[180:183], v[126:129]
	v_mfma_f32_16x16x32_bf16 v[122:125], v[138:141], v[180:183], v[122:125]
	v_mfma_f32_16x16x32_bf16 v[118:121], v[130:133], v[192:195], v[118:121]
	v_mfma_f32_16x16x32_bf16 v[114:117], v[138:141], v[192:195], v[114:117]
	v_mfma_f32_16x16x32_bf16 v[94:97], v[130:133], v[200:203], v[94:97]
	v_mfma_f32_16x16x32_bf16 v[90:93], v[138:141], v[200:203], v[90:93]
	v_mfma_f32_16x16x32_bf16 v[86:89], v[130:133], v[208:211], v[86:89]
	v_mfma_f32_16x16x32_bf16 v[82:85], v[138:141], v[208:211], v[82:85]
	v_mfma_f32_16x16x32_bf16 v[126:129], v[134:137], v[188:191], v[126:129]
	v_mfma_f32_16x16x32_bf16 v[122:125], v[142:145], v[188:191], v[122:125]
	v_mfma_f32_16x16x32_bf16 v[118:121], v[134:137], v[196:199], v[118:121]
	v_mfma_f32_16x16x32_bf16 v[114:117], v[142:145], v[196:199], v[114:117]
	v_mfma_f32_16x16x32_bf16 v[94:97], v[134:137], v[204:207], v[94:97]
	v_mfma_f32_16x16x32_bf16 v[90:93], v[142:145], v[204:207], v[90:93]
	v_mfma_f32_16x16x32_bf16 v[86:89], v[134:137], v[212:215], v[86:89]
	v_mfma_f32_16x16x32_bf16 v[82:85], v[142:145], v[212:215], v[82:85]
	v_mfma_f32_16x16x32_bf16 v[110:113], v[158:161], v[180:183], v[110:113]
	v_mfma_f32_16x16x32_bf16 v[106:109], v[172:175], v[180:183], v[106:109]
	v_mfma_f32_16x16x32_bf16 v[102:105], v[158:161], v[192:195], v[102:105]
	v_mfma_f32_16x16x32_bf16 v[98:101], v[172:175], v[192:195], v[98:101]
	v_mfma_f32_16x16x32_bf16 v[78:81], v[158:161], v[200:203], v[78:81]
	v_mfma_f32_16x16x32_bf16 v[74:77], v[172:175], v[200:203], v[74:77]
	v_mfma_f32_16x16x32_bf16 v[70:73], v[158:161], v[208:211], v[70:73]
	v_mfma_f32_16x16x32_bf16 v[66:69], v[172:175], v[208:211], v[66:69]
	v_mfma_f32_16x16x32_bf16 v[110:113], v[168:171], v[188:191], v[110:113]
	v_mfma_f32_16x16x32_bf16 v[106:109], v[176:179], v[188:191], v[106:109]
	v_mfma_f32_16x16x32_bf16 v[102:105], v[168:171], v[196:199], v[102:105]
	v_mfma_f32_16x16x32_bf16 v[98:101], v[176:179], v[196:199], v[98:101]
	v_mfma_f32_16x16x32_bf16 v[78:81], v[168:171], v[204:207], v[78:81]
	v_mfma_f32_16x16x32_bf16 v[74:77], v[176:179], v[204:207], v[74:77]
	v_mfma_f32_16x16x32_bf16 v[70:73], v[168:171], v[212:215], v[70:73]
	v_mfma_f32_16x16x32_bf16 v[66:69], v[176:179], v[212:215], v[66:69]
	s_setprio 0
	s_barrier
; #define PG8_STAGE(bufoff, gbase, voff) do { _Pragma("unroll") for (int _i = 0; _i < 2; ++_i) \
;         __builtin_amdgcn_global_load_lds((const unsigned*)((const char*)(gbase) + (voff)[_i]), (PG8_LAS unsigned*)(lds + (bufoff) + ldsw + _i * 8192), 16, 0, 0); } while (0)
; #define PG8_LDA(dst, b, h) do { _Pragma("unroll") for (int m = 0; m < 4; ++m) _Pragma("unroll") for (int k = 0; k < 2; ++k) dst[m][k] = *(const PG8_LAS bf16x8*)(lds + PG8_SA(b, h) + aoff + m * 2048 + k * 1024); } while (0)
; #define PG8_MMA(ai, bj, At, Bt) do { __builtin_amdgcn_s_setprio(1); _Pragma("unroll") for (int m = 0; m < 4; ++m) _Pragma("unroll") for (int n = 0; n < 2; ++n) _Pragma("unroll") for (int k = 0; k < 2; ++k) \
;         acc[ai][bj][m][n] = __builtin_amdgcn_mfma_f32_16x16x32_bf16(Bt[n][k], At[m][k], acc[ai][bj][m][n], 0, 0, 0); __builtin_amdgcn_s_setprio(0); } while (0)
; #define PG8_WAIT_V(n) asm volatile("s_waitcnt vmcnt(" #n ")" ::: "memory")
; #define PG8_WAIT_L(n) asm volatile("s_waitcnt lgkmcnt(" #n ")" ::: "memory")
; #define PG8_BAR __builtin_amdgcn_s_barrier()
; #define PG8_SCHED __builtin_amdgcn_sched_barrier(0)
; template <class Epi, class Sched, bool ALIGN_EPI = false, bool SP2 = false>
; __device__ __forceinline__ void gemm_phase(PG8_LAS unsigned char* lds, const Gemm g, const Sched& S, const Epi& E) {
;     ...
;         for (int t = 0; t < nt; t += 2) {
;             const bool last = (t == nt - 2);
;     ...
;             PG8_LDA(At, 1, 1); PG8_STAGE(PG8_SB(1, 0), b3, voffB); PG8_STAGE(PG8_SB(1, 1), b3 + hstep, voffB); PG8_STAGE(PG8_SA(1, 0), a3, voffA);
;             PG8_WAIT_V(8); PG8_WAIT_L(0); PG8_BAR; PG8_MMA(1, 0, At, B0); PG8_MMA(1, 1, At, B1); PG8_BAR; PG8_SCHED;
;     ...
;         if constexpr (ALIGN_EPI) { if (wr == 0) PG8_BAR; }
	s_add_i32 s26, s50, s28
	v_lshl_add_u64 v[184:185], v[184:185], 0, s[16:17]
	s_mov_b32 m0, s26
	ds_read_b128 v[180:183], v167 offset:49152
	ds_read_b128 v[188:191], v167 offset:50176
	ds_read_b128 v[192:195], v167 offset:51200
	ds_read_b128 v[196:199], v167 offset:52224
	ds_read_b128 v[200:203], v167 offset:53248
	ds_read_b128 v[204:207], v167 offset:54272
	ds_read_b128 v[208:211], v167 offset:55296
	ds_read_b128 v[212:215], v167 offset:56320
	global_load_lds_dwordx4 v[184:185], off
	s_add_i32 m0, s26, 0x2000
	s_add_u32 s24, s24, 0x160080
	v_lshl_add_u64 v[184:185], v[216:217], 0, s[16:17]
	s_addc_u32 s25, s25, 0
	s_add_i32 s26, s51, s28
	global_load_lds_dwordx4 v[184:185], off
	v_lshl_add_u64 v[184:185], s[24:25], 0, v[146:147]
	s_mov_b32 m0, s26
	s_nop 0
	global_load_lds_dwordx4 v[184:185], off
	v_lshl_add_u64 v[184:185], s[24:25], 0, v[148:149]
	s_add_i32 m0, s26, 0x2000
	s_nop 0
	global_load_lds_dwordx4 v[184:185], off
	v_lshl_add_u64 v[184:185], v[218:219], 0, s[16:17]
	s_mov_b32 m0, s37
	s_nop 0
	v_lshl_add_u64 v[184:185], v[220:221], 0, s[16:17]
	s_mov_b32 m0, s38
	s_nop 0
	s_waitcnt vmcnt(6)
	s_waitcnt lgkmcnt(0)
	s_setprio 1
	s_barrier
	v_mfma_f32_16x16x32_bf16 v[62:65], v[130:133], v[180:183], v[62:65]
	v_mfma_f32_16x16x32_bf16 v[58:61], v[138:141], v[180:183], v[58:61]
	v_mfma_f32_16x16x32_bf16 v[54:57], v[130:133], v[192:195], v[54:57]
	v_mfma_f32_16x16x32_bf16 v[50:53], v[138:141], v[192:195], v[50:53]
	v_mfma_f32_16x16x32_bf16 v[30:33], v[130:133], v[200:203], v[30:33]
	v_mfma_f32_16x16x32_bf16 v[26:29], v[138:141], v[200:203], v[26:29]
	v_mfma_f32_16x16x32_bf16 v[22:25], v[130:133], v[208:211], v[22:25]
	v_mfma_f32_16x16x32_bf16 v[18:21], v[138:141], v[208:211], v[18:21]
	v_mfma_f32_16x16x32_bf16 v[62:65], v[134:137], v[188:191], v[62:65]
	v_mfma_f32_16x16x32_bf16 v[58:61], v[142:145], v[188:191], v[58:61]
	v_mfma_f32_16x16x32_bf16 v[54:57], v[134:137], v[196:199], v[54:57]
	v_mfma_f32_16x16x32_bf16 v[50:53], v[142:145], v[196:199], v[50:53]
	v_mfma_f32_16x16x32_bf16 v[30:33], v[134:137], v[204:207], v[30:33]
	v_mfma_f32_16x16x32_bf16 v[26:29], v[142:145], v[204:207], v[26:29]
	v_mfma_f32_16x16x32_bf16 v[22:25], v[134:137], v[212:215], v[22:25]
	v_mfma_f32_16x16x32_bf16 v[18:21], v[142:145], v[212:215], v[18:21]
	v_mfma_f32_16x16x32_bf16 v[46:49], v[158:161], v[180:183], v[46:49]
	v_mfma_f32_16x16x32_bf16 v[42:45], v[172:175], v[180:183], v[42:45]
	v_mfma_f32_16x16x32_bf16 v[38:41], v[158:161], v[192:195], v[38:41]
	v_mfma_f32_16x16x32_bf16 v[34:37], v[172:175], v[192:195], v[34:37]
	v_mfma_f32_16x16x32_bf16 v[14:17], v[158:161], v[200:203], v[14:17]
	v_mfma_f32_16x16x32_bf16 v[10:13], v[172:175], v[200:203], v[10:13]
	v_mfma_f32_16x16x32_bf16 v[6:9], v[158:161], v[208:211], v[6:9]
	v_mfma_f32_16x16x32_bf16 v[2:5], v[172:175], v[208:211], v[2:5]
	v_mfma_f32_16x16x32_bf16 v[46:49], v[168:171], v[188:191], v[46:49]
	v_mfma_f32_16x16x32_bf16 v[42:45], v[176:179], v[188:191], v[42:45]
	v_mfma_f32_16x16x32_bf16 v[38:41], v[168:171], v[196:199], v[38:41]
	v_mfma_f32_16x16x32_bf16 v[34:37], v[176:179], v[196:199], v[34:37]
	v_mfma_f32_16x16x32_bf16 v[14:17], v[168:171], v[204:207], v[14:17]
	v_mfma_f32_16x16x32_bf16 v[10:13], v[176:179], v[204:207], v[10:13]
	v_mfma_f32_16x16x32_bf16 v[6:9], v[168:171], v[212:215], v[6:9]
	v_mfma_f32_16x16x32_bf16 v[2:5], v[176:179], v[212:215], v[2:5]
	s_setprio 0
	s_barrier
	s_add_i32 s49, s49, 2
	s_add_u32 s22, s22, 0x100
	s_addc_u32 s23, s23, 0
	s_add_u32 s47, s47, 0x100
	s_addc_u32 s48, s48, 0
	s_cmpk_gt_u32 s49, 0x55
	s_cbranch_scc0 .LBB0_1195
	s_and_b64 vcc, exec, s[18:19]
	s_cbranch_vccz .LBB0_1198
	s_barrier
